# GEMM K loops: MFMA half trimmed -- mid-block s_setprio flip pairs and the already-satisfied lgkmcnt wait after the barrier removed
# speedup vs baseline: 1.0050x; 1.0050x over previous
; #define G_STAGE_A(bufoff, p0, p1, koff) do { \
;         __builtin_amdgcn_global_load_lds((const unsigned*)(gbase + (size_t)(unsigned)((p0) + (koff) + voffA[0])), (LAS unsigned*)(lds + (bufoff) + ldsw), 16, 0, 0); \
;         __builtin_amdgcn_global_load_lds((const unsigned*)(gbase + (size_t)(unsigned)((p1) + (koff) + voffA[1])), (LAS unsigned*)(lds + (bufoff) + ldsw + 8192), 16, 0, 0); } while (0)
; #define G_STAGE_B(bufoff, p, koff) do { \
;         __builtin_amdgcn_global_load_lds((const unsigned*)(gbase + (size_t)(unsigned)((p) + (koff) + voffB[0])), (LAS unsigned*)(lds + (bufoff) + ldsw), 16, 0, 0); \
;         __builtin_amdgcn_global_load_lds((const unsigned*)(gbase + (size_t)(unsigned)((p) + (koff) + voffB[1])), (LAS unsigned*)(lds + (bufoff) + ldsw + 8192), 16, 0, 0); } while (0)
; #define G_LDA(dst, b, h) do { _Pragma("unroll") for (int m = 0; m < 4; ++m) _Pragma("unroll") for (int k = 0; k < 2; ++k) dst[m][k] = *(const LAS bf16x8*)(lds + G_SA(b, h) + aoff + m * 2048 + k * 1024); } while (0)
; #define G_LDB(dst, b, h) do { _Pragma("unroll") for (int n = 0; n < 2; ++n) _Pragma("unroll") for (int k = 0; k < 2; ++k) dst[n][k] = *(const LAS bf16x8*)(lds + G_SB(b, h) + boff + n * 2048 + k * 1024); } while (0)
; #define G_WAIT_V(n) asm volatile("s_waitcnt vmcnt(" #n ")" ::: "memory")
; template <class Epi>
; DI void gemm_phase(LAS unsigned char* lds, const Sched& S, const Epi& E, const int K) {
;     ...
;             const bool last = (t == nt - 2);
;             const unsigned k1 = (unsigned)(t + 1) * kstepA;
;             const unsigned k2 = last ? 0u : (unsigned)(t + 2) * kstepA, k3 = k2 + kstepA;
;             const unsigned kb2 = last ? 0u : (unsigned)(t + 2) * kstepB, kb3 = kb2 + kstepB;
;             const unsigned x0 = last ? n0 : cur.a0, x1 = last ? n1 : cur.a1, x2 = last ? n2 : cur.a2, x3 = last ? n3 : cur.a3;
;             const unsigned xb = last ? nB : cur.b;
;     ...
;             G_LDB(B0, 0, 0); G_LDB(B1, 0, 1); G_SCHED; G_LDA(At, 0, 0); G_STAGE_A(G_SA(1, 1), cur.a2, cur.a3, k1);
;             G_WAIT_V(8); G_WAIT_L(0); G_BAR; G_MMA(0, 0, At, B0); G_MMA(0, 1, At, B1); G_BAR; G_SCHED;
;             G_LDA(At, 0, 1); G_STAGE_B(G_SB(0, 0), xb, kb2); G_STAGE_B(G_SB(0, 1), xb + hstepB, kb2); G_STAGE_A(G_SA(0, 0), x0, x1, k2);
;             G_WAIT_V(8); G_WAIT_L(0); G_BAR; G_MMA(1, 0, At, B0); G_MMA(1, 1, At, B1); G_BAR; G_SCHED;
.LBB0_110:
	s_add_i32 s91, s90, 0x100
	s_cmp_eq_u32 s44, 28
	s_cselect_b32 s40, 0, s91
	s_cselect_b32 s46, s54, s41
	s_cselect_b32 s47, s56, s61
	s_cselect_b32 s88, s55, s27
	s_cselect_b32 s62, s45, s58
	s_cselect_b32 vcc_hi, s57, s60
	s_add_i32 s63, 0, 0x10000
	s_add_i32 s0, 0, 0x14000
	v_add_u32_e32 v142, s63, v207
	v_add_u32_e32 v158, s0, v207
	ds_read_b128 v[130:133], v142
	ds_read_b128 v[134:137], v142 offset:1024
	ds_read_b128 v[138:141], v142 offset:2048
	ds_read_b128 v[142:145], v142 offset:3072
	ds_read_b128 v[146:149], v158
	ds_read_b128 v[150:153], v158 offset:1024
	ds_read_b128 v[154:157], v158 offset:2048
	ds_read_b128 v[162:165], v158 offset:3072
	s_or_b32 vcc_lo, s40, 0x80
	v_add_u32_e32 v158, s90, v129
	s_add_i32 m0, s78, 0xc000
	ds_read_b128 v[166:169], v214
	ds_read_b128 v[170:173], v214 offset:1024
	ds_read_b128 v[174:177], v214 offset:2048
	ds_read_b128 v[178:181], v214 offset:3072
	ds_read_b128 v[194:197], v214 offset:4096
	ds_read_b128 v[198:201], v214 offset:5120
	ds_read_b128 v[216:219], v214 offset:6144
	ds_read_b128 v[220:223], v214 offset:7168
	global_load_lds_dwordx4 v158, s[82:83]
	v_add_u32_e32 v158, s90, v128
	s_add_i32 m0, s78, 0xe000
	s_nop 0
	global_load_lds_dwordx4 v158, s[82:83]
	s_waitcnt vmcnt(8)
	s_waitcnt lgkmcnt(0)
	s_barrier
	s_setprio 1
	v_mfma_f32_16x16x32_bf16 v[124:127], v[130:133], v[166:169], v[124:127]
	v_mfma_f32_16x16x32_bf16 v[120:123], v[138:141], v[166:169], v[120:123]
	v_mfma_f32_16x16x32_bf16 v[116:119], v[130:133], v[174:177], v[116:119]
	v_mfma_f32_16x16x32_bf16 v[112:115], v[138:141], v[174:177], v[112:115]
	v_mfma_f32_16x16x32_bf16 v[108:111], v[130:133], v[194:197], v[108:111]
	v_mfma_f32_16x16x32_bf16 v[104:107], v[138:141], v[194:197], v[104:107]
	v_mfma_f32_16x16x32_bf16 v[100:103], v[130:133], v[216:219], v[100:103]
	v_mfma_f32_16x16x32_bf16 v[96:99], v[138:141], v[216:219], v[96:99]
	v_mfma_f32_16x16x32_bf16 v[124:127], v[134:137], v[170:173], v[124:127]
	v_mfma_f32_16x16x32_bf16 v[120:123], v[142:145], v[170:173], v[120:123]
	v_mfma_f32_16x16x32_bf16 v[116:119], v[134:137], v[178:181], v[116:119]
	v_mfma_f32_16x16x32_bf16 v[112:115], v[142:145], v[178:181], v[112:115]
	v_mfma_f32_16x16x32_bf16 v[108:111], v[134:137], v[198:201], v[108:111]
	v_mfma_f32_16x16x32_bf16 v[104:107], v[142:145], v[198:201], v[104:107]
	v_mfma_f32_16x16x32_bf16 v[100:103], v[134:137], v[220:223], v[100:103]
	v_mfma_f32_16x16x32_bf16 v[96:99], v[142:145], v[220:223], v[96:99]
	v_mfma_f32_16x16x32_bf16 v[92:95], v[146:149], v[166:169], v[92:95]
	v_mfma_f32_16x16x32_bf16 v[88:91], v[154:157], v[166:169], v[88:91]
	v_mfma_f32_16x16x32_bf16 v[84:87], v[146:149], v[174:177], v[84:87]
	v_mfma_f32_16x16x32_bf16 v[80:83], v[154:157], v[174:177], v[80:83]
	v_mfma_f32_16x16x32_bf16 v[76:79], v[146:149], v[194:197], v[76:79]
	v_mfma_f32_16x16x32_bf16 v[72:75], v[154:157], v[194:197], v[72:75]
	v_mfma_f32_16x16x32_bf16 v[68:71], v[146:149], v[216:219], v[68:71]
	v_mfma_f32_16x16x32_bf16 v[64:67], v[154:157], v[216:219], v[64:67]
	v_mfma_f32_16x16x32_bf16 v[92:95], v[150:153], v[170:173], v[92:95]
	v_mfma_f32_16x16x32_bf16 v[88:91], v[162:165], v[170:173], v[88:91]
	v_mfma_f32_16x16x32_bf16 v[84:87], v[150:153], v[178:181], v[84:87]
	v_mfma_f32_16x16x32_bf16 v[80:83], v[162:165], v[178:181], v[80:83]
	v_mfma_f32_16x16x32_bf16 v[76:79], v[150:153], v[198:201], v[76:79]
	v_mfma_f32_16x16x32_bf16 v[72:75], v[162:165], v[198:201], v[72:75]
	v_mfma_f32_16x16x32_bf16 v[68:71], v[150:153], v[220:223], v[68:71]
	v_mfma_f32_16x16x32_bf16 v[64:67], v[162:165], v[220:223], v[64:67]
	s_setprio 0
	s_barrier
	s_add_i32 s90, s40, vcc_hi
	s_add_i32 s63, s63, s50
	v_add_u32_e32 v158, s90, v204
	s_mov_b32 m0, s63
	ds_read_b128 v[166:169], v214 offset:16384
	ds_read_b128 v[170:173], v214 offset:17408
	ds_read_b128 v[174:177], v214 offset:18432
	ds_read_b128 v[178:181], v214 offset:19456
	ds_read_b128 v[194:197], v214 offset:20480
	ds_read_b128 v[198:201], v214 offset:21504
	ds_read_b128 v[216:219], v214 offset:22528
	ds_read_b128 v[220:223], v214 offset:23552
	global_load_lds_dwordx4 v158, s[82:83]
	s_add_i32 m0, s63, 0x2000
	s_add_i32 s63, vcc_hi, 0x80000
	v_add_u32_e32 v158, s90, v206
	s_add_i32 s90, s63, s40
	s_add_i32 s0, s0, s50
	global_load_lds_dwordx4 v158, s[82:83]
	v_add_u32_e32 v158, s90, v204
	s_mov_b32 m0, s0
	s_nop 0
	global_load_lds_dwordx4 v158, s[82:83]
	v_add_u32_e32 v158, s90, v206
	s_add_i32 m0, s0, 0x2000
	s_nop 0
	global_load_lds_dwordx4 v158, s[82:83]
	v_add_u32_e32 v158, s62, v161
	v_add_u32_e32 v159, s40, v158
	s_mov_b32 m0, s78
	s_nop 0
	global_load_lds_dwordx4 v159, s[82:83]
	v_add_u32_e32 v159, s46, v205
	v_add_u32_e32 v182, s40, v159
	s_mov_b32 m0, s79
	s_nop 0
	global_load_lds_dwordx4 v182, s[82:83]
	s_waitcnt vmcnt(8)
	s_waitcnt lgkmcnt(0)
	s_barrier
; #define G_STAGE_A(bufoff, p0, p1, koff) do { \
;         __builtin_amdgcn_global_load_lds((const unsigned*)(gbase + (size_t)(unsigned)((p0) + (koff) + voffA[0])), (LAS unsigned*)(lds + (bufoff) + ldsw), 16, 0, 0); \
;         __builtin_amdgcn_global_load_lds((const unsigned*)(gbase + (size_t)(unsigned)((p1) + (koff) + voffA[1])), (LAS unsigned*)(lds + (bufoff) + ldsw + 8192), 16, 0, 0); } while (0)
; #define G_LDA(dst, b, h) do { _Pragma("unroll") for (int m = 0; m < 4; ++m) _Pragma("unroll") for (int k = 0; k < 2; ++k) dst[m][k] = *(const LAS bf16x8*)(lds + G_SA(b, h) + aoff + m * 2048 + k * 1024); } while (0)
; #define G_LDB(dst, b, h) do { _Pragma("unroll") for (int n = 0; n < 2; ++n) _Pragma("unroll") for (int k = 0; k < 2; ++k) dst[n][k] = *(const LAS bf16x8*)(lds + G_SB(b, h) + boff + n * 2048 + k * 1024); } while (0)
; #define G_MMA(ai, bj, At, Bt) do { __builtin_amdgcn_s_setprio(1); _Pragma("unroll") for (int m = 0; m < 4; ++m) _Pragma("unroll") for (int n = 0; n < 2; ++n) _Pragma("unroll") for (int k = 0; k < 2; ++k) \
;         acc[ai][bj][m][n] = __builtin_amdgcn_mfma_f32_16x16x32_bf16(Bt[n][k], At[m][k], acc[ai][bj][m][n], 0, 0, 0); __builtin_amdgcn_s_setprio(0); } while (0)
; #define G_WAIT_V(n) asm volatile("s_waitcnt vmcnt(" #n ")" ::: "memory")
; #define G_WAIT_L(n) asm volatile("s_waitcnt lgkmcnt(" #n ")" ::: "memory")
; #define G_BAR __builtin_amdgcn_s_barrier()
; #define G_SCHED __builtin_amdgcn_sched_barrier(0)
; template <class Epi>
; DI void gemm_phase(LAS unsigned char* lds, const Sched& S, const Epi& E, const int K) {
;     ...
;             G_WAIT_V(8); G_WAIT_L(0); G_BAR; G_MMA(1, 0, At, B0); G_MMA(1, 1, At, B1); G_BAR; G_SCHED;
;             G_LDB(B0, 1, 0); G_LDB(B1, 1, 1); G_SCHED; G_LDA(At, 1, 0); G_STAGE_A(G_SA(0, 1), x2, x3, k2);
;             G_WAIT_V(8); G_WAIT_L(0); G_BAR; G_MMA(0, 0, At, B0); G_MMA(0, 1, At, B1); G_BAR; G_SCHED;
	s_setprio 1
	v_mfma_f32_16x16x32_bf16 v[60:63], v[130:133], v[166:169], v[60:63]
	v_mfma_f32_16x16x32_bf16 v[56:59], v[138:141], v[166:169], v[56:59]
	v_mfma_f32_16x16x32_bf16 v[52:55], v[130:133], v[174:177], v[52:55]
	v_mfma_f32_16x16x32_bf16 v[48:51], v[138:141], v[174:177], v[48:51]
	v_mfma_f32_16x16x32_bf16 v[44:47], v[130:133], v[194:197], v[44:47]
	v_mfma_f32_16x16x32_bf16 v[40:43], v[138:141], v[194:197], v[40:43]
	v_mfma_f32_16x16x32_bf16 v[36:39], v[130:133], v[216:219], v[36:39]
	v_mfma_f32_16x16x32_bf16 v[32:35], v[138:141], v[216:219], v[32:35]
	v_mfma_f32_16x16x32_bf16 v[60:63], v[134:137], v[170:173], v[60:63]
	v_mfma_f32_16x16x32_bf16 v[56:59], v[142:145], v[170:173], v[56:59]
	v_mfma_f32_16x16x32_bf16 v[52:55], v[134:137], v[178:181], v[52:55]
	v_mfma_f32_16x16x32_bf16 v[48:51], v[142:145], v[178:181], v[48:51]
	v_mfma_f32_16x16x32_bf16 v[44:47], v[134:137], v[198:201], v[44:47]
	v_mfma_f32_16x16x32_bf16 v[40:43], v[142:145], v[198:201], v[40:43]
	v_mfma_f32_16x16x32_bf16 v[36:39], v[134:137], v[220:223], v[36:39]
	v_mfma_f32_16x16x32_bf16 v[32:35], v[142:145], v[220:223], v[32:35]
	v_mfma_f32_16x16x32_bf16 v[28:31], v[146:149], v[166:169], v[28:31]
	v_mfma_f32_16x16x32_bf16 v[24:27], v[154:157], v[166:169], v[24:27]
	v_mfma_f32_16x16x32_bf16 v[20:23], v[146:149], v[174:177], v[20:23]
	v_mfma_f32_16x16x32_bf16 v[16:19], v[154:157], v[174:177], v[16:19]
	v_mfma_f32_16x16x32_bf16 v[12:15], v[146:149], v[194:197], v[12:15]
	v_mfma_f32_16x16x32_bf16 v[8:11], v[154:157], v[194:197], v[8:11]
	v_mfma_f32_16x16x32_bf16 v[4:7], v[146:149], v[216:219], v[4:7]
	v_mfma_f32_16x16x32_bf16 v[0:3], v[154:157], v[216:219], v[0:3]
	v_mfma_f32_16x16x32_bf16 v[28:31], v[150:153], v[170:173], v[28:31]
	v_mfma_f32_16x16x32_bf16 v[24:27], v[162:165], v[170:173], v[24:27]
	v_mfma_f32_16x16x32_bf16 v[20:23], v[150:153], v[178:181], v[20:23]
	v_mfma_f32_16x16x32_bf16 v[16:19], v[162:165], v[178:181], v[16:19]
	v_mfma_f32_16x16x32_bf16 v[12:15], v[150:153], v[198:201], v[12:15]
	v_mfma_f32_16x16x32_bf16 v[8:11], v[162:165], v[198:201], v[8:11]
	v_mfma_f32_16x16x32_bf16 v[4:7], v[150:153], v[220:223], v[4:7]
	v_mfma_f32_16x16x32_bf16 v[0:3], v[162:165], v[220:223], v[0:3]
	s_setprio 0
	s_barrier
	s_add_i32 s0, 0, 0x18000
	s_add_i32 s46, 0, 0x1c000
	v_add_u32_e32 v142, s0, v207
	v_add_u32_e32 v162, s46, v207
	ds_read_b128 v[130:133], v142
	ds_read_b128 v[134:137], v142 offset:1024
	ds_read_b128 v[138:141], v142 offset:2048
	ds_read_b128 v[142:145], v142 offset:3072
	ds_read_b128 v[146:149], v162
	ds_read_b128 v[150:153], v162 offset:1024
	ds_read_b128 v[154:157], v162 offset:2048
	ds_read_b128 v[162:165], v162 offset:3072
	s_add_i32 s88, s88, s40
	s_mov_b32 m0, s92
	v_add_u32_e32 v182, s88, v161
	s_add_i32 s47, s47, s40
	ds_read_b128 v[166:169], v214 offset:32768
	ds_read_b128 v[170:173], v214 offset:33792
	ds_read_b128 v[174:177], v214 offset:34816
	ds_read_b128 v[178:181], v214 offset:35840
	ds_read_b128 v[194:197], v214 offset:36864
	ds_read_b128 v[198:201], v214 offset:37888
	ds_read_b128 v[216:219], v214 offset:38912
	ds_read_b128 v[220:223], v214 offset:39936
	global_load_lds_dwordx4 v182, s[82:83]
	v_add_u32_e32 v182, s47, v205
	s_mov_b32 m0, s93
	s_nop 0
	global_load_lds_dwordx4 v182, s[82:83]
	s_waitcnt vmcnt(8)
	s_waitcnt lgkmcnt(0)
	s_barrier
	s_setprio 1
	v_mfma_f32_16x16x32_bf16 v[124:127], v[130:133], v[166:169], v[124:127]
	v_mfma_f32_16x16x32_bf16 v[120:123], v[138:141], v[166:169], v[120:123]
	v_mfma_f32_16x16x32_bf16 v[116:119], v[130:133], v[174:177], v[116:119]
	v_mfma_f32_16x16x32_bf16 v[112:115], v[138:141], v[174:177], v[112:115]
	v_mfma_f32_16x16x32_bf16 v[108:111], v[130:133], v[194:197], v[108:111]
	v_mfma_f32_16x16x32_bf16 v[104:107], v[138:141], v[194:197], v[104:107]
	v_mfma_f32_16x16x32_bf16 v[100:103], v[130:133], v[216:219], v[100:103]
	v_mfma_f32_16x16x32_bf16 v[96:99], v[138:141], v[216:219], v[96:99]
	v_mfma_f32_16x16x32_bf16 v[124:127], v[134:137], v[170:173], v[124:127]
	v_mfma_f32_16x16x32_bf16 v[120:123], v[142:145], v[170:173], v[120:123]
	v_mfma_f32_16x16x32_bf16 v[116:119], v[134:137], v[178:181], v[116:119]
	v_mfma_f32_16x16x32_bf16 v[112:115], v[142:145], v[178:181], v[112:115]
	v_mfma_f32_16x16x32_bf16 v[108:111], v[134:137], v[198:201], v[108:111]
	v_mfma_f32_16x16x32_bf16 v[104:107], v[142:145], v[198:201], v[104:107]
	v_mfma_f32_16x16x32_bf16 v[100:103], v[134:137], v[220:223], v[100:103]
	v_mfma_f32_16x16x32_bf16 v[96:99], v[142:145], v[220:223], v[96:99]
	v_mfma_f32_16x16x32_bf16 v[92:95], v[146:149], v[166:169], v[92:95]
	v_mfma_f32_16x16x32_bf16 v[88:91], v[154:157], v[166:169], v[88:91]
	v_mfma_f32_16x16x32_bf16 v[84:87], v[146:149], v[174:177], v[84:87]
	v_mfma_f32_16x16x32_bf16 v[80:83], v[154:157], v[174:177], v[80:83]
	v_mfma_f32_16x16x32_bf16 v[76:79], v[146:149], v[194:197], v[76:79]
	v_mfma_f32_16x16x32_bf16 v[72:75], v[154:157], v[194:197], v[72:75]
	v_mfma_f32_16x16x32_bf16 v[68:71], v[146:149], v[216:219], v[68:71]
	v_mfma_f32_16x16x32_bf16 v[64:67], v[154:157], v[216:219], v[64:67]
	v_mfma_f32_16x16x32_bf16 v[92:95], v[150:153], v[170:173], v[92:95]
	v_mfma_f32_16x16x32_bf16 v[88:91], v[162:165], v[170:173], v[88:91]
	v_mfma_f32_16x16x32_bf16 v[84:87], v[150:153], v[178:181], v[84:87]
	v_mfma_f32_16x16x32_bf16 v[80:83], v[162:165], v[178:181], v[80:83]
	v_mfma_f32_16x16x32_bf16 v[76:79], v[150:153], v[198:201], v[76:79]
	v_mfma_f32_16x16x32_bf16 v[72:75], v[162:165], v[198:201], v[72:75]
	v_mfma_f32_16x16x32_bf16 v[68:71], v[150:153], v[220:223], v[68:71]
	v_mfma_f32_16x16x32_bf16 v[64:67], v[162:165], v[220:223], v[64:67]
	s_setprio 0
	s_barrier
; #define G_STAGE_A(bufoff, p0, p1, koff) do { \
;         __builtin_amdgcn_global_load_lds((const unsigned*)(gbase + (size_t)(unsigned)((p0) + (koff) + voffA[0])), (LAS unsigned*)(lds + (bufoff) + ldsw), 16, 0, 0); \
;         __builtin_amdgcn_global_load_lds((const unsigned*)(gbase + (size_t)(unsigned)((p1) + (koff) + voffA[1])), (LAS unsigned*)(lds + (bufoff) + ldsw + 8192), 16, 0, 0); } while (0)
; #define G_STAGE_B(bufoff, p, koff) do { \
;         __builtin_amdgcn_global_load_lds((const unsigned*)(gbase + (size_t)(unsigned)((p) + (koff) + voffB[0])), (LAS unsigned*)(lds + (bufoff) + ldsw), 16, 0, 0); \
;         __builtin_amdgcn_global_load_lds((const unsigned*)(gbase + (size_t)(unsigned)((p) + (koff) + voffB[1])), (LAS unsigned*)(lds + (bufoff) + ldsw + 8192), 16, 0, 0); } while (0)
; #define G_LDA(dst, b, h) do { _Pragma("unroll") for (int m = 0; m < 4; ++m) _Pragma("unroll") for (int k = 0; k < 2; ++k) dst[m][k] = *(const LAS bf16x8*)(lds + G_SA(b, h) + aoff + m * 2048 + k * 1024); } while (0)
; #define G_MMA(ai, bj, At, Bt) do { __builtin_amdgcn_s_setprio(1); _Pragma("unroll") for (int m = 0; m < 4; ++m) _Pragma("unroll") for (int n = 0; n < 2; ++n) _Pragma("unroll") for (int k = 0; k < 2; ++k) \
;         acc[ai][bj][m][n] = __builtin_amdgcn_mfma_f32_16x16x32_bf16(Bt[n][k], At[m][k], acc[ai][bj][m][n], 0, 0, 0); __builtin_amdgcn_s_setprio(0); } while (0)
; #define G_WAIT_V(n) asm volatile("s_waitcnt vmcnt(" #n ")" ::: "memory")
; #define G_WAIT_L(n) asm volatile("s_waitcnt lgkmcnt(" #n ")" ::: "memory")
; #define G_BAR __builtin_amdgcn_s_barrier()
; #define G_SCHED __builtin_amdgcn_sched_barrier(0)
; template <class Epi>
; DI void gemm_phase(LAS unsigned char* lds, const Sched& S, const Epi& E, const int K) {
;     ...
;             G_WAIT_V(8); G_WAIT_L(0); G_BAR; G_MMA(0, 0, At, B0); G_MMA(0, 1, At, B1); G_BAR; G_SCHED;
;             G_LDA(At, 1, 1); G_STAGE_B(G_SB(1, 0), xb, kb3); G_STAGE_B(G_SB(1, 1), xb + hstepB, kb3); G_STAGE_A(G_SA(1, 0), x0, x1, k3);
;             G_WAIT_V(8); G_WAIT_L(0); G_BAR; G_MMA(1, 0, At, B0); G_MMA(1, 1, At, B1); G_BAR; G_SCHED;
;     ...
;         }
;     ...
;         if (wr == 0) G_BAR;
	s_add_i32 s40, vcc_lo, vcc_hi
	s_add_i32 s0, s0, s50
	v_add_u32_e32 v182, s40, v204
	s_mov_b32 m0, s0
	ds_read_b128 v[166:169], v214 offset:49152
	ds_read_b128 v[170:173], v214 offset:50176
	ds_read_b128 v[174:177], v214 offset:51200
	ds_read_b128 v[178:181], v214 offset:52224
	ds_read_b128 v[194:197], v214 offset:53248
	ds_read_b128 v[198:201], v214 offset:54272
	ds_read_b128 v[216:219], v214 offset:55296
	ds_read_b128 v[220:223], v214 offset:56320
	global_load_lds_dwordx4 v182, s[82:83]
	v_add_u32_e32 v182, s40, v206
	s_add_i32 m0, s0, 0x2000
	s_add_i32 s0, vcc_lo, s63
	s_add_i32 s40, s46, s50
	global_load_lds_dwordx4 v182, s[82:83]
	v_add_u32_e32 v182, s0, v204
	s_mov_b32 m0, s40
	v_add_u32_e32 v158, vcc_lo, v158
	global_load_lds_dwordx4 v182, s[82:83]
	v_add_u32_e32 v182, s0, v206
	s_add_i32 m0, s40, 0x2000
	s_nop 0
	global_load_lds_dwordx4 v182, s[82:83]
	s_mov_b32 m0, s39
	s_nop 0
	global_load_lds_dwordx4 v158, s[82:83]
	v_add_u32_e32 v158, vcc_lo, v159
	s_mov_b32 m0, s38
	s_nop 0
	global_load_lds_dwordx4 v158, s[82:83]
	s_waitcnt vmcnt(8)
	s_waitcnt lgkmcnt(0)
	s_barrier
	s_setprio 1
	v_mfma_f32_16x16x32_bf16 v[60:63], v[130:133], v[166:169], v[60:63]
	v_mfma_f32_16x16x32_bf16 v[56:59], v[138:141], v[166:169], v[56:59]
	v_mfma_f32_16x16x32_bf16 v[52:55], v[130:133], v[174:177], v[52:55]
	v_mfma_f32_16x16x32_bf16 v[48:51], v[138:141], v[174:177], v[48:51]
	v_mfma_f32_16x16x32_bf16 v[44:47], v[130:133], v[194:197], v[44:47]
	v_mfma_f32_16x16x32_bf16 v[40:43], v[138:141], v[194:197], v[40:43]
	v_mfma_f32_16x16x32_bf16 v[36:39], v[130:133], v[216:219], v[36:39]
	v_mfma_f32_16x16x32_bf16 v[32:35], v[138:141], v[216:219], v[32:35]
	v_mfma_f32_16x16x32_bf16 v[60:63], v[134:137], v[170:173], v[60:63]
	v_mfma_f32_16x16x32_bf16 v[56:59], v[142:145], v[170:173], v[56:59]
	v_mfma_f32_16x16x32_bf16 v[52:55], v[134:137], v[178:181], v[52:55]
	v_mfma_f32_16x16x32_bf16 v[48:51], v[142:145], v[178:181], v[48:51]
	v_mfma_f32_16x16x32_bf16 v[44:47], v[134:137], v[198:201], v[44:47]
	v_mfma_f32_16x16x32_bf16 v[40:43], v[142:145], v[198:201], v[40:43]
	v_mfma_f32_16x16x32_bf16 v[36:39], v[134:137], v[220:223], v[36:39]
	v_mfma_f32_16x16x32_bf16 v[32:35], v[142:145], v[220:223], v[32:35]
	v_mfma_f32_16x16x32_bf16 v[28:31], v[146:149], v[166:169], v[28:31]
	v_mfma_f32_16x16x32_bf16 v[24:27], v[154:157], v[166:169], v[24:27]
	v_mfma_f32_16x16x32_bf16 v[20:23], v[146:149], v[174:177], v[20:23]
	v_mfma_f32_16x16x32_bf16 v[16:19], v[154:157], v[174:177], v[16:19]
	v_mfma_f32_16x16x32_bf16 v[12:15], v[146:149], v[194:197], v[12:15]
	v_mfma_f32_16x16x32_bf16 v[8:11], v[154:157], v[194:197], v[8:11]
	v_mfma_f32_16x16x32_bf16 v[4:7], v[146:149], v[216:219], v[4:7]
	v_mfma_f32_16x16x32_bf16 v[0:3], v[154:157], v[216:219], v[0:3]
	v_mfma_f32_16x16x32_bf16 v[28:31], v[150:153], v[170:173], v[28:31]
	v_mfma_f32_16x16x32_bf16 v[24:27], v[162:165], v[170:173], v[24:27]
	v_mfma_f32_16x16x32_bf16 v[20:23], v[150:153], v[178:181], v[20:23]
	v_mfma_f32_16x16x32_bf16 v[16:19], v[162:165], v[178:181], v[16:19]
	v_mfma_f32_16x16x32_bf16 v[12:15], v[150:153], v[198:201], v[12:15]
	v_mfma_f32_16x16x32_bf16 v[8:11], v[162:165], v[198:201], v[8:11]
	v_mfma_f32_16x16x32_bf16 v[4:7], v[150:153], v[220:223], v[4:7]
	v_mfma_f32_16x16x32_bf16 v[0:3], v[162:165], v[220:223], v[0:3]
	s_setprio 0
	s_barrier
	s_add_i32 s44, s44, 2
	s_cmp_gt_u32 s44, 29
	s_mov_b32 s90, s91
	s_cbranch_scc0 .LBB0_110
	v_readlane_b32 s44, v254, 63
	v_readlane_b32 s45, v255, 0
	s_and_b64 vcc, exec, s[44:45]
	s_cbranch_vccz .LBB0_113
	s_barrier

; #define G_STAGE_A(bufoff, p0, p1, koff) do { \
;         __builtin_amdgcn_global_load_lds((const unsigned*)(gbase + (size_t)(unsigned)((p0) + (koff) + voffA[0])), (LAS unsigned*)(lds + (bufoff) + ldsw), 16, 0, 0); \
;         __builtin_amdgcn_global_load_lds((const unsigned*)(gbase + (size_t)(unsigned)((p1) + (koff) + voffA[1])), (LAS unsigned*)(lds + (bufoff) + ldsw + 8192), 16, 0, 0); } while (0)
; #define G_STAGE_B(bufoff, p, koff) do { \
;         __builtin_amdgcn_global_load_lds((const unsigned*)(gbase + (size_t)(unsigned)((p) + (koff) + voffB[0])), (LAS unsigned*)(lds + (bufoff) + ldsw), 16, 0, 0); \
;         __builtin_amdgcn_global_load_lds((const unsigned*)(gbase + (size_t)(unsigned)((p) + (koff) + voffB[1])), (LAS unsigned*)(lds + (bufoff) + ldsw + 8192), 16, 0, 0); } while (0)
; #define G_LDA(dst, b, h) do { _Pragma("unroll") for (int m = 0; m < 4; ++m) _Pragma("unroll") for (int k = 0; k < 2; ++k) dst[m][k] = *(const LAS bf16x8*)(lds + G_SA(b, h) + aoff + m * 2048 + k * 1024); } while (0)
; #define G_LDB(dst, b, h) do { _Pragma("unroll") for (int n = 0; n < 2; ++n) _Pragma("unroll") for (int k = 0; k < 2; ++k) dst[n][k] = *(const LAS bf16x8*)(lds + G_SB(b, h) + boff + n * 2048 + k * 1024); } while (0)
; #define G_BAR __builtin_amdgcn_s_barrier()
; template <class Epi>
; DI void gemm_phase(LAS unsigned char* lds, const Sched& S, const Epi& E, const int K) {
;     ...
;         for (int t = 0; t < nt; t += 2) {
;             const bool last = (t == nt - 2);
;             const unsigned k1 = (unsigned)(t + 1) * kstepA;
;             const unsigned k2 = last ? 0u : (unsigned)(t + 2) * kstepA, k3 = k2 + kstepA;
;             const unsigned kb2 = last ? 0u : (unsigned)(t + 2) * kstepB, kb3 = kb2 + kstepB;
;             const unsigned x0 = last ? n0 : cur.a0, x1 = last ? n1 : cur.a1, x2 = last ? n2 : cur.a2, x3 = last ? n3 : cur.a3;
;             const unsigned xb = last ? nB : cur.b;
;     ...
;             G_LDB(B0, 0, 0); G_LDB(B1, 0, 1); G_SCHED; G_LDA(At, 0, 0); G_STAGE_A(G_SA(1, 1), cur.a2, cur.a3, k1);
;             G_WAIT_V(8); G_WAIT_L(0); G_BAR; G_MMA(0, 0, At, B0); G_MMA(0, 1, At, B1); G_BAR; G_SCHED;
;             G_LDA(At, 0, 1); G_STAGE_B(G_SB(0, 0), xb, kb2); G_STAGE_B(G_SB(0, 1), xb + hstepB, kb2); G_STAGE_A(G_SA(0, 0), x0, x1, k2);
;             G_WAIT_V(8); G_WAIT_L(0); G_BAR; G_MMA(1, 0, At, B0); G_MMA(1, 1, At, B1); G_BAR; G_SCHED;
.LBB0_196:
	s_add_i32 s72, s71, 2
	s_add_i32 s73, s14, 0x100
	s_cmp_eq_u32 s47, s71
	s_cselect_b32 s40, 0, s73
	s_cselect_b32 s78, s67, s37
	s_cselect_b32 s79, s69, s35
	s_cselect_b32 s80, s68, s36
	s_cselect_b32 s81, s15, s27
	s_cselect_b32 s75, s70, s26
	s_add_i32 s86, 0, 0x10000
	s_add_i32 s87, 0, 0x14000
	v_add_u32_e32 v152, s86, v133
	v_add_u32_e32 v168, s87, v133
	ds_read_b128 v[140:143], v152
	ds_read_b128 v[144:147], v152 offset:1024
	ds_read_b128 v[148:151], v152 offset:2048
	ds_read_b128 v[152:155], v152 offset:3072
	ds_read_b128 v[156:159], v168
	ds_read_b128 v[160:163], v168 offset:1024
	ds_read_b128 v[164:167], v168 offset:2048
	ds_read_b128 v[168:171], v168 offset:3072
	s_or_b32 s71, s40, 0x80
	v_add_u32_e32 v184, s14, v139
	s_add_i32 m0, s25, 0xc000
	ds_read_b128 v[172:175], v137
	ds_read_b128 v[176:179], v137 offset:1024
	ds_read_b128 v[180:183], v137 offset:2048
	ds_read_b128 v[194:197], v137 offset:3072
	ds_read_b128 v[198:201], v137 offset:4096
	ds_read_b128 v[202:205], v137 offset:5120
	ds_read_b128 v[206:209], v137 offset:6144
	ds_read_b128 v[210:213], v137 offset:7168
	global_load_lds_dwordx4 v184, s[82:83]
	v_add_u32_e32 v184, s14, v138
	s_add_i32 m0, s25, 0xe000
	s_nop 0
	global_load_lds_dwordx4 v184, s[82:83]
	s_waitcnt vmcnt(8)
	s_waitcnt lgkmcnt(0)
	s_barrier
	s_setprio 1
	v_mfma_f32_16x16x32_bf16 v[124:127], v[140:143], v[172:175], v[124:127]
	v_mfma_f32_16x16x32_bf16 v[120:123], v[148:151], v[172:175], v[120:123]
	v_mfma_f32_16x16x32_bf16 v[116:119], v[140:143], v[180:183], v[116:119]
	v_mfma_f32_16x16x32_bf16 v[112:115], v[148:151], v[180:183], v[112:115]
	v_mfma_f32_16x16x32_bf16 v[108:111], v[140:143], v[198:201], v[108:111]
	v_mfma_f32_16x16x32_bf16 v[104:107], v[148:151], v[198:201], v[104:107]
	v_mfma_f32_16x16x32_bf16 v[100:103], v[140:143], v[206:209], v[100:103]
	v_mfma_f32_16x16x32_bf16 v[96:99], v[148:151], v[206:209], v[96:99]
	v_mfma_f32_16x16x32_bf16 v[124:127], v[144:147], v[176:179], v[124:127]
	v_mfma_f32_16x16x32_bf16 v[120:123], v[152:155], v[176:179], v[120:123]
	v_mfma_f32_16x16x32_bf16 v[116:119], v[144:147], v[194:197], v[116:119]
	v_mfma_f32_16x16x32_bf16 v[112:115], v[152:155], v[194:197], v[112:115]
	v_mfma_f32_16x16x32_bf16 v[108:111], v[144:147], v[202:205], v[108:111]
	v_mfma_f32_16x16x32_bf16 v[104:107], v[152:155], v[202:205], v[104:107]
	v_mfma_f32_16x16x32_bf16 v[100:103], v[144:147], v[210:213], v[100:103]
	v_mfma_f32_16x16x32_bf16 v[96:99], v[152:155], v[210:213], v[96:99]
	v_mfma_f32_16x16x32_bf16 v[92:95], v[156:159], v[172:175], v[92:95]
	v_mfma_f32_16x16x32_bf16 v[88:91], v[164:167], v[172:175], v[88:91]
	v_mfma_f32_16x16x32_bf16 v[84:87], v[156:159], v[180:183], v[84:87]
	v_mfma_f32_16x16x32_bf16 v[80:83], v[164:167], v[180:183], v[80:83]
	v_mfma_f32_16x16x32_bf16 v[76:79], v[156:159], v[198:201], v[76:79]
	v_mfma_f32_16x16x32_bf16 v[72:75], v[164:167], v[198:201], v[72:75]
	v_mfma_f32_16x16x32_bf16 v[68:71], v[156:159], v[206:209], v[68:71]
	v_mfma_f32_16x16x32_bf16 v[64:67], v[164:167], v[206:209], v[64:67]
	v_mfma_f32_16x16x32_bf16 v[92:95], v[160:163], v[176:179], v[92:95]
	v_mfma_f32_16x16x32_bf16 v[88:91], v[168:171], v[176:179], v[88:91]
	v_mfma_f32_16x16x32_bf16 v[84:87], v[160:163], v[194:197], v[84:87]
	v_mfma_f32_16x16x32_bf16 v[80:83], v[168:171], v[194:197], v[80:83]
	v_mfma_f32_16x16x32_bf16 v[76:79], v[160:163], v[202:205], v[76:79]
	v_mfma_f32_16x16x32_bf16 v[72:75], v[168:171], v[202:205], v[72:75]
	v_mfma_f32_16x16x32_bf16 v[68:71], v[160:163], v[210:213], v[68:71]
	v_mfma_f32_16x16x32_bf16 v[64:67], v[168:171], v[210:213], v[64:67]
	s_setprio 0
	s_barrier
	s_add_i32 s14, s40, s75
	s_add_i32 s86, s86, s20
	v_add_u32_e32 v184, s14, v128
	s_mov_b32 m0, s86
	ds_read_b128 v[172:175], v137 offset:16384
	ds_read_b128 v[176:179], v137 offset:17408
	ds_read_b128 v[180:183], v137 offset:18432
	ds_read_b128 v[194:197], v137 offset:19456
	ds_read_b128 v[198:201], v137 offset:20480
	ds_read_b128 v[202:205], v137 offset:21504
	ds_read_b128 v[206:209], v137 offset:22528
	ds_read_b128 v[210:213], v137 offset:23552
	global_load_lds_dwordx4 v184, s[82:83]
	v_add_u32_e32 v184, s14, v130
	s_add_i32 s14, s75, s16
	s_add_i32 m0, s86, 0x2000
	s_add_i32 s86, s14, s40
	s_add_i32 s87, s87, s20
	global_load_lds_dwordx4 v184, s[82:83]
	v_add_u32_e32 v184, s86, v128
	s_mov_b32 m0, s87
	s_nop 0
	global_load_lds_dwordx4 v184, s[82:83]
	v_add_u32_e32 v184, s86, v130
	s_add_i32 m0, s87, 0x2000
	s_nop 0
	global_load_lds_dwordx4 v184, s[82:83]
	v_add_u32_e32 v184, s81, v132
	v_add_u32_e32 v214, s40, v184
	s_mov_b32 m0, s25
	s_nop 0
	global_load_lds_dwordx4 v214, s[82:83]
	v_add_u32_e32 v214, s78, v129
	v_add_u32_e32 v215, s40, v214
	s_mov_b32 m0, s38
	s_nop 0
	global_load_lds_dwordx4 v215, s[82:83]
	s_waitcnt vmcnt(8)
	s_waitcnt lgkmcnt(0)
	s_barrier
; #define G_STAGE_A(bufoff, p0, p1, koff) do { \
;         __builtin_amdgcn_global_load_lds((const unsigned*)(gbase + (size_t)(unsigned)((p0) + (koff) + voffA[0])), (LAS unsigned*)(lds + (bufoff) + ldsw), 16, 0, 0); \
;         __builtin_amdgcn_global_load_lds((const unsigned*)(gbase + (size_t)(unsigned)((p1) + (koff) + voffA[1])), (LAS unsigned*)(lds + (bufoff) + ldsw + 8192), 16, 0, 0); } while (0)
; #define G_LDA(dst, b, h) do { _Pragma("unroll") for (int m = 0; m < 4; ++m) _Pragma("unroll") for (int k = 0; k < 2; ++k) dst[m][k] = *(const LAS bf16x8*)(lds + G_SA(b, h) + aoff + m * 2048 + k * 1024); } while (0)
; #define G_LDB(dst, b, h) do { _Pragma("unroll") for (int n = 0; n < 2; ++n) _Pragma("unroll") for (int k = 0; k < 2; ++k) dst[n][k] = *(const LAS bf16x8*)(lds + G_SB(b, h) + boff + n * 2048 + k * 1024); } while (0)
; #define G_MMA(ai, bj, At, Bt) do { __builtin_amdgcn_s_setprio(1); _Pragma("unroll") for (int m = 0; m < 4; ++m) _Pragma("unroll") for (int n = 0; n < 2; ++n) _Pragma("unroll") for (int k = 0; k < 2; ++k) \
;         acc[ai][bj][m][n] = __builtin_amdgcn_mfma_f32_16x16x32_bf16(Bt[n][k], At[m][k], acc[ai][bj][m][n], 0, 0, 0); __builtin_amdgcn_s_setprio(0); } while (0)
; #define G_WAIT_V(n) asm volatile("s_waitcnt vmcnt(" #n ")" ::: "memory")
; #define G_WAIT_L(n) asm volatile("s_waitcnt lgkmcnt(" #n ")" ::: "memory")
; #define G_BAR __builtin_amdgcn_s_barrier()
; #define G_SCHED __builtin_amdgcn_sched_barrier(0)
; template <class Epi>
; DI void gemm_phase(LAS unsigned char* lds, const Sched& S, const Epi& E, const int K) {
;     ...
;             G_WAIT_V(8); G_WAIT_L(0); G_BAR; G_MMA(1, 0, At, B0); G_MMA(1, 1, At, B1); G_BAR; G_SCHED;
;             G_LDB(B0, 1, 0); G_LDB(B1, 1, 1); G_SCHED; G_LDA(At, 1, 0); G_STAGE_A(G_SA(0, 1), x2, x3, k2);
;             G_WAIT_V(8); G_WAIT_L(0); G_BAR; G_MMA(0, 0, At, B0); G_MMA(0, 1, At, B1); G_BAR; G_SCHED;
	s_setprio 1
	v_mfma_f32_16x16x32_bf16 v[60:63], v[140:143], v[172:175], v[60:63]
	v_mfma_f32_16x16x32_bf16 v[56:59], v[148:151], v[172:175], v[56:59]
	v_mfma_f32_16x16x32_bf16 v[52:55], v[140:143], v[180:183], v[52:55]
	v_mfma_f32_16x16x32_bf16 v[48:51], v[148:151], v[180:183], v[48:51]
	v_mfma_f32_16x16x32_bf16 v[44:47], v[140:143], v[198:201], v[44:47]
	v_mfma_f32_16x16x32_bf16 v[40:43], v[148:151], v[198:201], v[40:43]
	v_mfma_f32_16x16x32_bf16 v[36:39], v[140:143], v[206:209], v[36:39]
	v_mfma_f32_16x16x32_bf16 v[32:35], v[148:151], v[206:209], v[32:35]
	v_mfma_f32_16x16x32_bf16 v[60:63], v[144:147], v[176:179], v[60:63]
	v_mfma_f32_16x16x32_bf16 v[56:59], v[152:155], v[176:179], v[56:59]
	v_mfma_f32_16x16x32_bf16 v[52:55], v[144:147], v[194:197], v[52:55]
	v_mfma_f32_16x16x32_bf16 v[48:51], v[152:155], v[194:197], v[48:51]
	v_mfma_f32_16x16x32_bf16 v[44:47], v[144:147], v[202:205], v[44:47]
	v_mfma_f32_16x16x32_bf16 v[40:43], v[152:155], v[202:205], v[40:43]
	v_mfma_f32_16x16x32_bf16 v[36:39], v[144:147], v[210:213], v[36:39]
	v_mfma_f32_16x16x32_bf16 v[32:35], v[152:155], v[210:213], v[32:35]
	v_mfma_f32_16x16x32_bf16 v[28:31], v[156:159], v[172:175], v[28:31]
	v_mfma_f32_16x16x32_bf16 v[24:27], v[164:167], v[172:175], v[24:27]
	v_mfma_f32_16x16x32_bf16 v[20:23], v[156:159], v[180:183], v[20:23]
	v_mfma_f32_16x16x32_bf16 v[16:19], v[164:167], v[180:183], v[16:19]
	v_mfma_f32_16x16x32_bf16 v[12:15], v[156:159], v[198:201], v[12:15]
	v_mfma_f32_16x16x32_bf16 v[8:11], v[164:167], v[198:201], v[8:11]
	v_mfma_f32_16x16x32_bf16 v[4:7], v[156:159], v[206:209], v[4:7]
	v_mfma_f32_16x16x32_bf16 v[0:3], v[164:167], v[206:209], v[0:3]
	v_mfma_f32_16x16x32_bf16 v[28:31], v[160:163], v[176:179], v[28:31]
	v_mfma_f32_16x16x32_bf16 v[24:27], v[168:171], v[176:179], v[24:27]
	v_mfma_f32_16x16x32_bf16 v[20:23], v[160:163], v[194:197], v[20:23]
	v_mfma_f32_16x16x32_bf16 v[16:19], v[168:171], v[194:197], v[16:19]
	v_mfma_f32_16x16x32_bf16 v[12:15], v[160:163], v[202:205], v[12:15]
	v_mfma_f32_16x16x32_bf16 v[8:11], v[168:171], v[202:205], v[8:11]
	v_mfma_f32_16x16x32_bf16 v[4:7], v[160:163], v[210:213], v[4:7]
	v_mfma_f32_16x16x32_bf16 v[0:3], v[168:171], v[210:213], v[0:3]
	s_setprio 0
	s_barrier
	s_add_i32 s78, 0, 0x18000
	s_add_i32 s81, 0, 0x1c000
	v_add_u32_e32 v152, s78, v133
	v_add_u32_e32 v168, s81, v133
	ds_read_b128 v[140:143], v152
	ds_read_b128 v[144:147], v152 offset:1024
	ds_read_b128 v[148:151], v152 offset:2048
	ds_read_b128 v[152:155], v152 offset:3072
	ds_read_b128 v[156:159], v168
	ds_read_b128 v[160:163], v168 offset:1024
	ds_read_b128 v[164:167], v168 offset:2048
	ds_read_b128 v[168:171], v168 offset:3072
	s_add_i32 s80, s80, s40
	s_mov_b32 m0, s39
	v_add_u32_e32 v215, s80, v132
	s_add_i32 s79, s79, s40
	ds_read_b128 v[172:175], v137 offset:32768
	ds_read_b128 v[176:179], v137 offset:33792
	ds_read_b128 v[180:183], v137 offset:34816
	ds_read_b128 v[194:197], v137 offset:35840
	ds_read_b128 v[198:201], v137 offset:36864
	ds_read_b128 v[202:205], v137 offset:37888
	ds_read_b128 v[206:209], v137 offset:38912
	ds_read_b128 v[210:213], v137 offset:39936
	global_load_lds_dwordx4 v215, s[82:83]
	v_add_u32_e32 v215, s79, v129
	s_mov_b32 m0, s41
	s_nop 0
	global_load_lds_dwordx4 v215, s[82:83]
	s_waitcnt vmcnt(8)
	s_waitcnt lgkmcnt(0)
	s_barrier
	s_setprio 1
	v_mfma_f32_16x16x32_bf16 v[124:127], v[140:143], v[172:175], v[124:127]
	v_mfma_f32_16x16x32_bf16 v[120:123], v[148:151], v[172:175], v[120:123]
	v_mfma_f32_16x16x32_bf16 v[116:119], v[140:143], v[180:183], v[116:119]
	v_mfma_f32_16x16x32_bf16 v[112:115], v[148:151], v[180:183], v[112:115]
	v_mfma_f32_16x16x32_bf16 v[108:111], v[140:143], v[198:201], v[108:111]
	v_mfma_f32_16x16x32_bf16 v[104:107], v[148:151], v[198:201], v[104:107]
	v_mfma_f32_16x16x32_bf16 v[100:103], v[140:143], v[206:209], v[100:103]
	v_mfma_f32_16x16x32_bf16 v[96:99], v[148:151], v[206:209], v[96:99]
	v_mfma_f32_16x16x32_bf16 v[124:127], v[144:147], v[176:179], v[124:127]
	v_mfma_f32_16x16x32_bf16 v[120:123], v[152:155], v[176:179], v[120:123]
	v_mfma_f32_16x16x32_bf16 v[116:119], v[144:147], v[194:197], v[116:119]
	v_mfma_f32_16x16x32_bf16 v[112:115], v[152:155], v[194:197], v[112:115]
	v_mfma_f32_16x16x32_bf16 v[108:111], v[144:147], v[202:205], v[108:111]
	v_mfma_f32_16x16x32_bf16 v[104:107], v[152:155], v[202:205], v[104:107]
	v_mfma_f32_16x16x32_bf16 v[100:103], v[144:147], v[210:213], v[100:103]
	v_mfma_f32_16x16x32_bf16 v[96:99], v[152:155], v[210:213], v[96:99]
	v_mfma_f32_16x16x32_bf16 v[92:95], v[156:159], v[172:175], v[92:95]
	v_mfma_f32_16x16x32_bf16 v[88:91], v[164:167], v[172:175], v[88:91]
	v_mfma_f32_16x16x32_bf16 v[84:87], v[156:159], v[180:183], v[84:87]
	v_mfma_f32_16x16x32_bf16 v[80:83], v[164:167], v[180:183], v[80:83]
	v_mfma_f32_16x16x32_bf16 v[76:79], v[156:159], v[198:201], v[76:79]
	v_mfma_f32_16x16x32_bf16 v[72:75], v[164:167], v[198:201], v[72:75]
	v_mfma_f32_16x16x32_bf16 v[68:71], v[156:159], v[206:209], v[68:71]
	v_mfma_f32_16x16x32_bf16 v[64:67], v[164:167], v[206:209], v[64:67]
	v_mfma_f32_16x16x32_bf16 v[92:95], v[160:163], v[176:179], v[92:95]
	v_mfma_f32_16x16x32_bf16 v[88:91], v[168:171], v[176:179], v[88:91]
	v_mfma_f32_16x16x32_bf16 v[84:87], v[160:163], v[194:197], v[84:87]
	v_mfma_f32_16x16x32_bf16 v[80:83], v[168:171], v[194:197], v[80:83]
	v_mfma_f32_16x16x32_bf16 v[76:79], v[160:163], v[202:205], v[76:79]
	v_mfma_f32_16x16x32_bf16 v[72:75], v[168:171], v[202:205], v[72:75]
	v_mfma_f32_16x16x32_bf16 v[68:71], v[160:163], v[210:213], v[68:71]
	v_mfma_f32_16x16x32_bf16 v[64:67], v[168:171], v[210:213], v[64:67]
	s_setprio 0
	s_barrier
; #define G_STAGE_A(bufoff, p0, p1, koff) do { \
;         __builtin_amdgcn_global_load_lds((const unsigned*)(gbase + (size_t)(unsigned)((p0) + (koff) + voffA[0])), (LAS unsigned*)(lds + (bufoff) + ldsw), 16, 0, 0); \
;         __builtin_amdgcn_global_load_lds((const unsigned*)(gbase + (size_t)(unsigned)((p1) + (koff) + voffA[1])), (LAS unsigned*)(lds + (bufoff) + ldsw + 8192), 16, 0, 0); } while (0)
; #define G_STAGE_B(bufoff, p, koff) do { \
;         __builtin_amdgcn_global_load_lds((const unsigned*)(gbase + (size_t)(unsigned)((p) + (koff) + voffB[0])), (LAS unsigned*)(lds + (bufoff) + ldsw), 16, 0, 0); \
;         __builtin_amdgcn_global_load_lds((const unsigned*)(gbase + (size_t)(unsigned)((p) + (koff) + voffB[1])), (LAS unsigned*)(lds + (bufoff) + ldsw + 8192), 16, 0, 0); } while (0)
; #define G_LDA(dst, b, h) do { _Pragma("unroll") for (int m = 0; m < 4; ++m) _Pragma("unroll") for (int k = 0; k < 2; ++k) dst[m][k] = *(const LAS bf16x8*)(lds + G_SA(b, h) + aoff + m * 2048 + k * 1024); } while (0)
; #define G_MMA(ai, bj, At, Bt) do { __builtin_amdgcn_s_setprio(1); _Pragma("unroll") for (int m = 0; m < 4; ++m) _Pragma("unroll") for (int n = 0; n < 2; ++n) _Pragma("unroll") for (int k = 0; k < 2; ++k) \
;         acc[ai][bj][m][n] = __builtin_amdgcn_mfma_f32_16x16x32_bf16(Bt[n][k], At[m][k], acc[ai][bj][m][n], 0, 0, 0); __builtin_amdgcn_s_setprio(0); } while (0)
; #define G_WAIT_V(n) asm volatile("s_waitcnt vmcnt(" #n ")" ::: "memory")
; #define G_WAIT_L(n) asm volatile("s_waitcnt lgkmcnt(" #n ")" ::: "memory")
; #define G_BAR __builtin_amdgcn_s_barrier()
; #define G_SCHED __builtin_amdgcn_sched_barrier(0)
; template <class Epi>
; DI void gemm_phase(LAS unsigned char* lds, const Sched& S, const Epi& E, const int K) {
;     ...
;             G_WAIT_V(8); G_WAIT_L(0); G_BAR; G_MMA(0, 0, At, B0); G_MMA(0, 1, At, B1); G_BAR; G_SCHED;
;             G_LDA(At, 1, 1); G_STAGE_B(G_SB(1, 0), xb, kb3); G_STAGE_B(G_SB(1, 1), xb + hstepB, kb3); G_STAGE_A(G_SA(1, 0), x0, x1, k3);
;             G_WAIT_V(8); G_WAIT_L(0); G_BAR; G_MMA(1, 0, At, B0); G_MMA(1, 1, At, B1); G_BAR; G_SCHED;
;     ...
;         }
;     ...
;         if (wr == 0) G_BAR;
	s_add_i32 s40, s71, s75
	s_add_i32 s75, s78, s20
	v_add_u32_e32 v215, s40, v128
	s_mov_b32 m0, s75
	ds_read_b128 v[172:175], v137 offset:49152
	ds_read_b128 v[176:179], v137 offset:50176
	ds_read_b128 v[180:183], v137 offset:51200
	ds_read_b128 v[194:197], v137 offset:52224
	ds_read_b128 v[198:201], v137 offset:53248
	ds_read_b128 v[202:205], v137 offset:54272
	ds_read_b128 v[206:209], v137 offset:55296
	ds_read_b128 v[210:213], v137 offset:56320
	global_load_lds_dwordx4 v215, s[82:83]
	v_add_u32_e32 v215, s40, v130
	s_add_i32 m0, s75, 0x2000
	s_add_i32 s14, s71, s14
	s_add_i32 s40, s81, s20
	global_load_lds_dwordx4 v215, s[82:83]
	v_add_u32_e32 v215, s14, v128
	s_mov_b32 m0, s40
	v_add_u32_e32 v184, s71, v184
	global_load_lds_dwordx4 v215, s[82:83]
	v_add_u32_e32 v215, s14, v130
	s_add_i32 m0, s40, 0x2000
	s_nop 0
	global_load_lds_dwordx4 v215, s[82:83]
	s_mov_b32 m0, s45
	s_nop 0
	global_load_lds_dwordx4 v184, s[82:83]
	v_add_u32_e32 v184, s71, v214
	s_mov_b32 m0, s46
	s_nop 0
	global_load_lds_dwordx4 v184, s[82:83]
	s_waitcnt vmcnt(8)
	s_waitcnt lgkmcnt(0)
	s_barrier
	s_setprio 1
	v_mfma_f32_16x16x32_bf16 v[60:63], v[140:143], v[172:175], v[60:63]
	v_mfma_f32_16x16x32_bf16 v[56:59], v[148:151], v[172:175], v[56:59]
	v_mfma_f32_16x16x32_bf16 v[52:55], v[140:143], v[180:183], v[52:55]
	v_mfma_f32_16x16x32_bf16 v[48:51], v[148:151], v[180:183], v[48:51]
	v_mfma_f32_16x16x32_bf16 v[44:47], v[140:143], v[198:201], v[44:47]
	v_mfma_f32_16x16x32_bf16 v[40:43], v[148:151], v[198:201], v[40:43]
	v_mfma_f32_16x16x32_bf16 v[36:39], v[140:143], v[206:209], v[36:39]
	v_mfma_f32_16x16x32_bf16 v[32:35], v[148:151], v[206:209], v[32:35]
	v_mfma_f32_16x16x32_bf16 v[60:63], v[144:147], v[176:179], v[60:63]
	v_mfma_f32_16x16x32_bf16 v[56:59], v[152:155], v[176:179], v[56:59]
	v_mfma_f32_16x16x32_bf16 v[52:55], v[144:147], v[194:197], v[52:55]
	v_mfma_f32_16x16x32_bf16 v[48:51], v[152:155], v[194:197], v[48:51]
	v_mfma_f32_16x16x32_bf16 v[44:47], v[144:147], v[202:205], v[44:47]
	v_mfma_f32_16x16x32_bf16 v[40:43], v[152:155], v[202:205], v[40:43]
	v_mfma_f32_16x16x32_bf16 v[36:39], v[144:147], v[210:213], v[36:39]
	v_mfma_f32_16x16x32_bf16 v[32:35], v[152:155], v[210:213], v[32:35]
	v_mfma_f32_16x16x32_bf16 v[28:31], v[156:159], v[172:175], v[28:31]
	v_mfma_f32_16x16x32_bf16 v[24:27], v[164:167], v[172:175], v[24:27]
	v_mfma_f32_16x16x32_bf16 v[20:23], v[156:159], v[180:183], v[20:23]
	v_mfma_f32_16x16x32_bf16 v[16:19], v[164:167], v[180:183], v[16:19]
	v_mfma_f32_16x16x32_bf16 v[12:15], v[156:159], v[198:201], v[12:15]
	v_mfma_f32_16x16x32_bf16 v[8:11], v[164:167], v[198:201], v[8:11]
	v_mfma_f32_16x16x32_bf16 v[4:7], v[156:159], v[206:209], v[4:7]
	v_mfma_f32_16x16x32_bf16 v[0:3], v[164:167], v[206:209], v[0:3]
	v_mfma_f32_16x16x32_bf16 v[28:31], v[160:163], v[176:179], v[28:31]
	v_mfma_f32_16x16x32_bf16 v[24:27], v[168:171], v[176:179], v[24:27]
	v_mfma_f32_16x16x32_bf16 v[20:23], v[160:163], v[194:197], v[20:23]
	v_mfma_f32_16x16x32_bf16 v[16:19], v[168:171], v[194:197], v[16:19]
	v_mfma_f32_16x16x32_bf16 v[12:15], v[160:163], v[202:205], v[12:15]
	v_mfma_f32_16x16x32_bf16 v[8:11], v[168:171], v[202:205], v[8:11]
	v_mfma_f32_16x16x32_bf16 v[4:7], v[160:163], v[210:213], v[4:7]
	v_mfma_f32_16x16x32_bf16 v[0:3], v[168:171], v[210:213], v[0:3]
	s_setprio 0
	s_barrier
	s_cmp_ge_u32 s72, s44
	s_mov_b32 s14, s73
	s_mov_b32 s71, s72
	s_cbranch_scc0 .LBB0_196
	s_and_b64 vcc, exec, s[12:13]
	s_mov_b32 s71, 0xf800000
	s_cbranch_vccz .LBB0_199
	s_barrier

; #define G_STAGE_A(bufoff, p0, p1, koff) do { \
;         __builtin_amdgcn_global_load_lds((const unsigned*)(gbase + (size_t)(unsigned)((p0) + (koff) + voffA[0])), (LAS unsigned*)(lds + (bufoff) + ldsw), 16, 0, 0); \
;         __builtin_amdgcn_global_load_lds((const unsigned*)(gbase + (size_t)(unsigned)((p1) + (koff) + voffA[1])), (LAS unsigned*)(lds + (bufoff) + ldsw + 8192), 16, 0, 0); } while (0)
; #define G_STAGE_B(bufoff, p, koff) do { \
;         __builtin_amdgcn_global_load_lds((const unsigned*)(gbase + (size_t)(unsigned)((p) + (koff) + voffB[0])), (LAS unsigned*)(lds + (bufoff) + ldsw), 16, 0, 0); \
;         __builtin_amdgcn_global_load_lds((const unsigned*)(gbase + (size_t)(unsigned)((p) + (koff) + voffB[1])), (LAS unsigned*)(lds + (bufoff) + ldsw + 8192), 16, 0, 0); } while (0)
; #define G_LDA(dst, b, h) do { _Pragma("unroll") for (int m = 0; m < 4; ++m) _Pragma("unroll") for (int k = 0; k < 2; ++k) dst[m][k] = *(const LAS bf16x8*)(lds + G_SA(b, h) + aoff + m * 2048 + k * 1024); } while (0)
; #define G_LDB(dst, b, h) do { _Pragma("unroll") for (int n = 0; n < 2; ++n) _Pragma("unroll") for (int k = 0; k < 2; ++k) dst[n][k] = *(const LAS bf16x8*)(lds + G_SB(b, h) + boff + n * 2048 + k * 1024); } while (0)
; #define G_BAR __builtin_amdgcn_s_barrier()
; template <class Epi>
; DI void gemm_phase(LAS unsigned char* lds, const Sched& S, const Epi& E, const int K) {
;     ...
;         for (int t = 0; t < nt; t += 2) {
;             const bool last = (t == nt - 2);
;             const unsigned k1 = (unsigned)(t + 1) * kstepA;
;             const unsigned k2 = last ? 0u : (unsigned)(t + 2) * kstepA, k3 = k2 + kstepA;
;             const unsigned kb2 = last ? 0u : (unsigned)(t + 2) * kstepB, kb3 = kb2 + kstepB;
;             const unsigned x0 = last ? n0 : cur.a0, x1 = last ? n1 : cur.a1, x2 = last ? n2 : cur.a2, x3 = last ? n3 : cur.a3;
;             const unsigned xb = last ? nB : cur.b;
;     ...
;             G_LDB(B0, 0, 0); G_LDB(B1, 0, 1); G_SCHED; G_LDA(At, 0, 0); G_STAGE_A(G_SA(1, 1), cur.a2, cur.a3, k1);
;             G_WAIT_V(8); G_WAIT_L(0); G_BAR; G_MMA(0, 0, At, B0); G_MMA(0, 1, At, B1); G_BAR; G_SCHED;
;             G_LDA(At, 0, 1); G_STAGE_B(G_SB(0, 0), xb, kb2); G_STAGE_B(G_SB(0, 1), xb + hstepB, kb2); G_STAGE_A(G_SA(0, 0), x0, x1, k2);
;             G_WAIT_V(8); G_WAIT_L(0); G_BAR; G_MMA(1, 0, At, B0); G_MMA(1, 1, At, B1); G_BAR; G_SCHED;
.LBB0_217:
	s_add_i32 s71, s70, 2
	s_add_i32 s72, s14, 0x100
	s_cmp_eq_u32 s46, s70
	s_cselect_b32 s40, 0, s72
	s_cselect_b32 s75, s15, s38
	s_cselect_b32 s78, s68, s36
	s_cselect_b32 s79, s67, s37
	s_cselect_b32 s80, s13, s35
	s_cselect_b32 s73, s69, s27
	s_add_i32 s81, 0, 0x10000
	s_add_i32 s86, 0, 0x14000
	v_add_u32_e32 v152, s81, v133
	v_add_u32_e32 v168, s86, v133
	ds_read_b128 v[140:143], v152
	ds_read_b128 v[144:147], v152 offset:1024
	ds_read_b128 v[148:151], v152 offset:2048
	ds_read_b128 v[152:155], v152 offset:3072
	ds_read_b128 v[156:159], v168
	ds_read_b128 v[160:163], v168 offset:1024
	ds_read_b128 v[164:167], v168 offset:2048
	ds_read_b128 v[168:171], v168 offset:3072
	s_or_b32 s70, s40, 0x80
	v_add_u32_e32 v184, s14, v139
	s_add_i32 m0, s26, 0xc000
	ds_read_b128 v[172:175], v137
	ds_read_b128 v[176:179], v137 offset:1024
	ds_read_b128 v[180:183], v137 offset:2048
	ds_read_b128 v[194:197], v137 offset:3072
	ds_read_b128 v[198:201], v137 offset:4096
	ds_read_b128 v[202:205], v137 offset:5120
	ds_read_b128 v[206:209], v137 offset:6144
	ds_read_b128 v[210:213], v137 offset:7168
	global_load_lds_dwordx4 v184, s[82:83]
	v_add_u32_e32 v184, s14, v138
	s_add_i32 m0, s26, 0xe000
	s_nop 0
	global_load_lds_dwordx4 v184, s[82:83]
	s_waitcnt vmcnt(8)
	s_waitcnt lgkmcnt(0)
	s_barrier
	s_setprio 1
	v_mfma_f32_16x16x32_bf16 v[124:127], v[140:143], v[172:175], v[124:127]
	v_mfma_f32_16x16x32_bf16 v[120:123], v[148:151], v[172:175], v[120:123]
	v_mfma_f32_16x16x32_bf16 v[116:119], v[140:143], v[180:183], v[116:119]
	v_mfma_f32_16x16x32_bf16 v[112:115], v[148:151], v[180:183], v[112:115]
	v_mfma_f32_16x16x32_bf16 v[108:111], v[140:143], v[198:201], v[108:111]
	v_mfma_f32_16x16x32_bf16 v[104:107], v[148:151], v[198:201], v[104:107]
	v_mfma_f32_16x16x32_bf16 v[100:103], v[140:143], v[206:209], v[100:103]
	v_mfma_f32_16x16x32_bf16 v[96:99], v[148:151], v[206:209], v[96:99]
	v_mfma_f32_16x16x32_bf16 v[124:127], v[144:147], v[176:179], v[124:127]
	v_mfma_f32_16x16x32_bf16 v[120:123], v[152:155], v[176:179], v[120:123]
	v_mfma_f32_16x16x32_bf16 v[116:119], v[144:147], v[194:197], v[116:119]
	v_mfma_f32_16x16x32_bf16 v[112:115], v[152:155], v[194:197], v[112:115]
	v_mfma_f32_16x16x32_bf16 v[108:111], v[144:147], v[202:205], v[108:111]
	v_mfma_f32_16x16x32_bf16 v[104:107], v[152:155], v[202:205], v[104:107]
	v_mfma_f32_16x16x32_bf16 v[100:103], v[144:147], v[210:213], v[100:103]
	v_mfma_f32_16x16x32_bf16 v[96:99], v[152:155], v[210:213], v[96:99]
	v_mfma_f32_16x16x32_bf16 v[92:95], v[156:159], v[172:175], v[92:95]
	v_mfma_f32_16x16x32_bf16 v[88:91], v[164:167], v[172:175], v[88:91]
	v_mfma_f32_16x16x32_bf16 v[84:87], v[156:159], v[180:183], v[84:87]
	v_mfma_f32_16x16x32_bf16 v[80:83], v[164:167], v[180:183], v[80:83]
	v_mfma_f32_16x16x32_bf16 v[76:79], v[156:159], v[198:201], v[76:79]
	v_mfma_f32_16x16x32_bf16 v[72:75], v[164:167], v[198:201], v[72:75]
	v_mfma_f32_16x16x32_bf16 v[68:71], v[156:159], v[206:209], v[68:71]
	v_mfma_f32_16x16x32_bf16 v[64:67], v[164:167], v[206:209], v[64:67]
	v_mfma_f32_16x16x32_bf16 v[92:95], v[160:163], v[176:179], v[92:95]
	v_mfma_f32_16x16x32_bf16 v[88:91], v[168:171], v[176:179], v[88:91]
	v_mfma_f32_16x16x32_bf16 v[84:87], v[160:163], v[194:197], v[84:87]
	v_mfma_f32_16x16x32_bf16 v[80:83], v[168:171], v[194:197], v[80:83]
	v_mfma_f32_16x16x32_bf16 v[76:79], v[160:163], v[202:205], v[76:79]
	v_mfma_f32_16x16x32_bf16 v[72:75], v[168:171], v[202:205], v[72:75]
	v_mfma_f32_16x16x32_bf16 v[68:71], v[160:163], v[210:213], v[68:71]
	v_mfma_f32_16x16x32_bf16 v[64:67], v[168:171], v[210:213], v[64:67]
	s_setprio 0
	s_barrier
	s_add_i32 s14, s40, s73
	s_add_i32 s81, s81, s21
	v_add_u32_e32 v184, s14, v128
	s_mov_b32 m0, s81
	ds_read_b128 v[172:175], v137 offset:16384
	ds_read_b128 v[176:179], v137 offset:17408
	ds_read_b128 v[180:183], v137 offset:18432
	ds_read_b128 v[194:197], v137 offset:19456
	ds_read_b128 v[198:201], v137 offset:20480
	ds_read_b128 v[202:205], v137 offset:21504
	ds_read_b128 v[206:209], v137 offset:22528
	ds_read_b128 v[210:213], v137 offset:23552
	global_load_lds_dwordx4 v184, s[82:83]
	v_add_u32_e32 v184, s14, v130
	s_add_i32 s14, s73, s16
	s_add_i32 m0, s81, 0x2000
	s_add_i32 s81, s14, s40
	s_add_i32 s86, s86, s21
	global_load_lds_dwordx4 v184, s[82:83]
	v_add_u32_e32 v184, s81, v128
	s_mov_b32 m0, s86
	s_nop 0
	global_load_lds_dwordx4 v184, s[82:83]
	v_add_u32_e32 v184, s81, v130
	s_add_i32 m0, s86, 0x2000
	s_nop 0
	global_load_lds_dwordx4 v184, s[82:83]
	v_add_u32_e32 v184, s80, v132
	v_add_u32_e32 v214, s40, v184
	s_mov_b32 m0, s26
	s_nop 0
	global_load_lds_dwordx4 v214, s[82:83]
	v_add_u32_e32 v214, s75, v129
	v_add_u32_e32 v215, s40, v214
	s_mov_b32 m0, s39
	s_nop 0
	global_load_lds_dwordx4 v215, s[82:83]
	s_waitcnt vmcnt(8)
	s_waitcnt lgkmcnt(0)
	s_barrier
; #define G_STAGE_A(bufoff, p0, p1, koff) do { \
;         __builtin_amdgcn_global_load_lds((const unsigned*)(gbase + (size_t)(unsigned)((p0) + (koff) + voffA[0])), (LAS unsigned*)(lds + (bufoff) + ldsw), 16, 0, 0); \
;         __builtin_amdgcn_global_load_lds((const unsigned*)(gbase + (size_t)(unsigned)((p1) + (koff) + voffA[1])), (LAS unsigned*)(lds + (bufoff) + ldsw + 8192), 16, 0, 0); } while (0)
; #define G_LDA(dst, b, h) do { _Pragma("unroll") for (int m = 0; m < 4; ++m) _Pragma("unroll") for (int k = 0; k < 2; ++k) dst[m][k] = *(const LAS bf16x8*)(lds + G_SA(b, h) + aoff + m * 2048 + k * 1024); } while (0)
; #define G_LDB(dst, b, h) do { _Pragma("unroll") for (int n = 0; n < 2; ++n) _Pragma("unroll") for (int k = 0; k < 2; ++k) dst[n][k] = *(const LAS bf16x8*)(lds + G_SB(b, h) + boff + n * 2048 + k * 1024); } while (0)
; #define G_MMA(ai, bj, At, Bt) do { __builtin_amdgcn_s_setprio(1); _Pragma("unroll") for (int m = 0; m < 4; ++m) _Pragma("unroll") for (int n = 0; n < 2; ++n) _Pragma("unroll") for (int k = 0; k < 2; ++k) \
;         acc[ai][bj][m][n] = __builtin_amdgcn_mfma_f32_16x16x32_bf16(Bt[n][k], At[m][k], acc[ai][bj][m][n], 0, 0, 0); __builtin_amdgcn_s_setprio(0); } while (0)
; #define G_WAIT_V(n) asm volatile("s_waitcnt vmcnt(" #n ")" ::: "memory")
; #define G_WAIT_L(n) asm volatile("s_waitcnt lgkmcnt(" #n ")" ::: "memory")
; #define G_BAR __builtin_amdgcn_s_barrier()
; #define G_SCHED __builtin_amdgcn_sched_barrier(0)
; template <class Epi>
; DI void gemm_phase(LAS unsigned char* lds, const Sched& S, const Epi& E, const int K) {
;     ...
;             G_WAIT_V(8); G_WAIT_L(0); G_BAR; G_MMA(1, 0, At, B0); G_MMA(1, 1, At, B1); G_BAR; G_SCHED;
;             G_LDB(B0, 1, 0); G_LDB(B1, 1, 1); G_SCHED; G_LDA(At, 1, 0); G_STAGE_A(G_SA(0, 1), x2, x3, k2);
;             G_WAIT_V(8); G_WAIT_L(0); G_BAR; G_MMA(0, 0, At, B0); G_MMA(0, 1, At, B1); G_BAR; G_SCHED;
	s_setprio 1
	v_mfma_f32_16x16x32_bf16 v[60:63], v[140:143], v[172:175], v[60:63]
	v_mfma_f32_16x16x32_bf16 v[56:59], v[148:151], v[172:175], v[56:59]
	v_mfma_f32_16x16x32_bf16 v[52:55], v[140:143], v[180:183], v[52:55]
	v_mfma_f32_16x16x32_bf16 v[48:51], v[148:151], v[180:183], v[48:51]
	v_mfma_f32_16x16x32_bf16 v[44:47], v[140:143], v[198:201], v[44:47]
	v_mfma_f32_16x16x32_bf16 v[40:43], v[148:151], v[198:201], v[40:43]
	v_mfma_f32_16x16x32_bf16 v[36:39], v[140:143], v[206:209], v[36:39]
	v_mfma_f32_16x16x32_bf16 v[32:35], v[148:151], v[206:209], v[32:35]
	v_mfma_f32_16x16x32_bf16 v[60:63], v[144:147], v[176:179], v[60:63]
	v_mfma_f32_16x16x32_bf16 v[56:59], v[152:155], v[176:179], v[56:59]
	v_mfma_f32_16x16x32_bf16 v[52:55], v[144:147], v[194:197], v[52:55]
	v_mfma_f32_16x16x32_bf16 v[48:51], v[152:155], v[194:197], v[48:51]
	v_mfma_f32_16x16x32_bf16 v[44:47], v[144:147], v[202:205], v[44:47]
	v_mfma_f32_16x16x32_bf16 v[40:43], v[152:155], v[202:205], v[40:43]
	v_mfma_f32_16x16x32_bf16 v[36:39], v[144:147], v[210:213], v[36:39]
	v_mfma_f32_16x16x32_bf16 v[32:35], v[152:155], v[210:213], v[32:35]
	v_mfma_f32_16x16x32_bf16 v[28:31], v[156:159], v[172:175], v[28:31]
	v_mfma_f32_16x16x32_bf16 v[24:27], v[164:167], v[172:175], v[24:27]
	v_mfma_f32_16x16x32_bf16 v[20:23], v[156:159], v[180:183], v[20:23]
	v_mfma_f32_16x16x32_bf16 v[16:19], v[164:167], v[180:183], v[16:19]
	v_mfma_f32_16x16x32_bf16 v[12:15], v[156:159], v[198:201], v[12:15]
	v_mfma_f32_16x16x32_bf16 v[8:11], v[164:167], v[198:201], v[8:11]
	v_mfma_f32_16x16x32_bf16 v[4:7], v[156:159], v[206:209], v[4:7]
	v_mfma_f32_16x16x32_bf16 v[0:3], v[164:167], v[206:209], v[0:3]
	v_mfma_f32_16x16x32_bf16 v[28:31], v[160:163], v[176:179], v[28:31]
	v_mfma_f32_16x16x32_bf16 v[24:27], v[168:171], v[176:179], v[24:27]
	v_mfma_f32_16x16x32_bf16 v[20:23], v[160:163], v[194:197], v[20:23]
	v_mfma_f32_16x16x32_bf16 v[16:19], v[168:171], v[194:197], v[16:19]
	v_mfma_f32_16x16x32_bf16 v[12:15], v[160:163], v[202:205], v[12:15]
	v_mfma_f32_16x16x32_bf16 v[8:11], v[168:171], v[202:205], v[8:11]
	v_mfma_f32_16x16x32_bf16 v[4:7], v[160:163], v[210:213], v[4:7]
	v_mfma_f32_16x16x32_bf16 v[0:3], v[168:171], v[210:213], v[0:3]
	s_setprio 0
	s_barrier
	s_add_i32 s75, 0, 0x18000
	s_add_i32 s80, 0, 0x1c000
	v_add_u32_e32 v152, s75, v133
	v_add_u32_e32 v168, s80, v133
	ds_read_b128 v[140:143], v152
	ds_read_b128 v[144:147], v152 offset:1024
	ds_read_b128 v[148:151], v152 offset:2048
	ds_read_b128 v[152:155], v152 offset:3072
	ds_read_b128 v[156:159], v168
	ds_read_b128 v[160:163], v168 offset:1024
	ds_read_b128 v[164:167], v168 offset:2048
	ds_read_b128 v[168:171], v168 offset:3072
	s_add_i32 s79, s79, s40
	s_mov_b32 m0, s41
	v_add_u32_e32 v215, s79, v132
	s_add_i32 s78, s78, s40
	ds_read_b128 v[172:175], v137 offset:32768
	ds_read_b128 v[176:179], v137 offset:33792
	ds_read_b128 v[180:183], v137 offset:34816
	ds_read_b128 v[194:197], v137 offset:35840
	ds_read_b128 v[198:201], v137 offset:36864
	ds_read_b128 v[202:205], v137 offset:37888
	ds_read_b128 v[206:209], v137 offset:38912
	ds_read_b128 v[210:213], v137 offset:39936
	global_load_lds_dwordx4 v215, s[82:83]
	v_add_u32_e32 v215, s78, v129
	s_mov_b32 m0, s44
	s_nop 0
	global_load_lds_dwordx4 v215, s[82:83]
	s_waitcnt vmcnt(8)
	s_waitcnt lgkmcnt(0)
	s_barrier
	s_setprio 1
	v_mfma_f32_16x16x32_bf16 v[124:127], v[140:143], v[172:175], v[124:127]
	v_mfma_f32_16x16x32_bf16 v[120:123], v[148:151], v[172:175], v[120:123]
	v_mfma_f32_16x16x32_bf16 v[116:119], v[140:143], v[180:183], v[116:119]
	v_mfma_f32_16x16x32_bf16 v[112:115], v[148:151], v[180:183], v[112:115]
	v_mfma_f32_16x16x32_bf16 v[108:111], v[140:143], v[198:201], v[108:111]
	v_mfma_f32_16x16x32_bf16 v[104:107], v[148:151], v[198:201], v[104:107]
	v_mfma_f32_16x16x32_bf16 v[100:103], v[140:143], v[206:209], v[100:103]
	v_mfma_f32_16x16x32_bf16 v[96:99], v[148:151], v[206:209], v[96:99]
	v_mfma_f32_16x16x32_bf16 v[124:127], v[144:147], v[176:179], v[124:127]
	v_mfma_f32_16x16x32_bf16 v[120:123], v[152:155], v[176:179], v[120:123]
	v_mfma_f32_16x16x32_bf16 v[116:119], v[144:147], v[194:197], v[116:119]
	v_mfma_f32_16x16x32_bf16 v[112:115], v[152:155], v[194:197], v[112:115]
	v_mfma_f32_16x16x32_bf16 v[108:111], v[144:147], v[202:205], v[108:111]
	v_mfma_f32_16x16x32_bf16 v[104:107], v[152:155], v[202:205], v[104:107]
	v_mfma_f32_16x16x32_bf16 v[100:103], v[144:147], v[210:213], v[100:103]
	v_mfma_f32_16x16x32_bf16 v[96:99], v[152:155], v[210:213], v[96:99]
	v_mfma_f32_16x16x32_bf16 v[92:95], v[156:159], v[172:175], v[92:95]
	v_mfma_f32_16x16x32_bf16 v[88:91], v[164:167], v[172:175], v[88:91]
	v_mfma_f32_16x16x32_bf16 v[84:87], v[156:159], v[180:183], v[84:87]
	v_mfma_f32_16x16x32_bf16 v[80:83], v[164:167], v[180:183], v[80:83]
	v_mfma_f32_16x16x32_bf16 v[76:79], v[156:159], v[198:201], v[76:79]
	v_mfma_f32_16x16x32_bf16 v[72:75], v[164:167], v[198:201], v[72:75]
	v_mfma_f32_16x16x32_bf16 v[68:71], v[156:159], v[206:209], v[68:71]
	v_mfma_f32_16x16x32_bf16 v[64:67], v[164:167], v[206:209], v[64:67]
	v_mfma_f32_16x16x32_bf16 v[92:95], v[160:163], v[176:179], v[92:95]
	v_mfma_f32_16x16x32_bf16 v[88:91], v[168:171], v[176:179], v[88:91]
	v_mfma_f32_16x16x32_bf16 v[84:87], v[160:163], v[194:197], v[84:87]
	v_mfma_f32_16x16x32_bf16 v[80:83], v[168:171], v[194:197], v[80:83]
	v_mfma_f32_16x16x32_bf16 v[76:79], v[160:163], v[202:205], v[76:79]
	v_mfma_f32_16x16x32_bf16 v[72:75], v[168:171], v[202:205], v[72:75]
	v_mfma_f32_16x16x32_bf16 v[68:71], v[160:163], v[210:213], v[68:71]
	v_mfma_f32_16x16x32_bf16 v[64:67], v[168:171], v[210:213], v[64:67]
	s_setprio 0
	s_barrier
; #define G_STAGE_A(bufoff, p0, p1, koff) do { \
;         __builtin_amdgcn_global_load_lds((const unsigned*)(gbase + (size_t)(unsigned)((p0) + (koff) + voffA[0])), (LAS unsigned*)(lds + (bufoff) + ldsw), 16, 0, 0); \
;         __builtin_amdgcn_global_load_lds((const unsigned*)(gbase + (size_t)(unsigned)((p1) + (koff) + voffA[1])), (LAS unsigned*)(lds + (bufoff) + ldsw + 8192), 16, 0, 0); } while (0)
; #define G_STAGE_B(bufoff, p, koff) do { \
;         __builtin_amdgcn_global_load_lds((const unsigned*)(gbase + (size_t)(unsigned)((p) + (koff) + voffB[0])), (LAS unsigned*)(lds + (bufoff) + ldsw), 16, 0, 0); \
;         __builtin_amdgcn_global_load_lds((const unsigned*)(gbase + (size_t)(unsigned)((p) + (koff) + voffB[1])), (LAS unsigned*)(lds + (bufoff) + ldsw + 8192), 16, 0, 0); } while (0)
; #define G_LDA(dst, b, h) do { _Pragma("unroll") for (int m = 0; m < 4; ++m) _Pragma("unroll") for (int k = 0; k < 2; ++k) dst[m][k] = *(const LAS bf16x8*)(lds + G_SA(b, h) + aoff + m * 2048 + k * 1024); } while (0)
; #define G_MMA(ai, bj, At, Bt) do { __builtin_amdgcn_s_setprio(1); _Pragma("unroll") for (int m = 0; m < 4; ++m) _Pragma("unroll") for (int n = 0; n < 2; ++n) _Pragma("unroll") for (int k = 0; k < 2; ++k) \
;         acc[ai][bj][m][n] = __builtin_amdgcn_mfma_f32_16x16x32_bf16(Bt[n][k], At[m][k], acc[ai][bj][m][n], 0, 0, 0); __builtin_amdgcn_s_setprio(0); } while (0)
; #define G_WAIT_V(n) asm volatile("s_waitcnt vmcnt(" #n ")" ::: "memory")
; #define G_WAIT_L(n) asm volatile("s_waitcnt lgkmcnt(" #n ")" ::: "memory")
; #define G_BAR __builtin_amdgcn_s_barrier()
; #define G_SCHED __builtin_amdgcn_sched_barrier(0)
; template <class Epi>
; DI void gemm_phase(LAS unsigned char* lds, const Sched& S, const Epi& E, const int K) {
;     ...
;             G_WAIT_V(8); G_WAIT_L(0); G_BAR; G_MMA(0, 0, At, B0); G_MMA(0, 1, At, B1); G_BAR; G_SCHED;
;             G_LDA(At, 1, 1); G_STAGE_B(G_SB(1, 0), xb, kb3); G_STAGE_B(G_SB(1, 1), xb + hstepB, kb3); G_STAGE_A(G_SA(1, 0), x0, x1, k3);
;             G_WAIT_V(8); G_WAIT_L(0); G_BAR; G_MMA(1, 0, At, B0); G_MMA(1, 1, At, B1); G_BAR; G_SCHED;
;     ...
;         }
;     ...
;         if (wr == 0) G_BAR;
	s_add_i32 s40, s70, s73
	s_add_i32 s73, s75, s21
	v_add_u32_e32 v215, s40, v128
	s_mov_b32 m0, s73
	ds_read_b128 v[172:175], v137 offset:49152
	ds_read_b128 v[176:179], v137 offset:50176
	ds_read_b128 v[180:183], v137 offset:51200
	ds_read_b128 v[194:197], v137 offset:52224
	ds_read_b128 v[198:201], v137 offset:53248
	ds_read_b128 v[202:205], v137 offset:54272
	ds_read_b128 v[206:209], v137 offset:55296
	ds_read_b128 v[210:213], v137 offset:56320
	global_load_lds_dwordx4 v215, s[82:83]
	v_add_u32_e32 v215, s40, v130
	s_add_i32 m0, s73, 0x2000
	s_add_i32 s14, s70, s14
	s_add_i32 s40, s80, s21
	global_load_lds_dwordx4 v215, s[82:83]
	v_add_u32_e32 v215, s14, v128
	s_mov_b32 m0, s40
	v_add_u32_e32 v184, s70, v184
	global_load_lds_dwordx4 v215, s[82:83]
	v_add_u32_e32 v215, s14, v130
	s_add_i32 m0, s40, 0x2000
	s_nop 0
	global_load_lds_dwordx4 v215, s[82:83]
	s_mov_b32 m0, s18
	s_nop 0
	global_load_lds_dwordx4 v184, s[82:83]
	v_add_u32_e32 v184, s70, v214
	s_mov_b32 m0, s45
	s_nop 0
	global_load_lds_dwordx4 v184, s[82:83]
	s_waitcnt vmcnt(8)
	s_waitcnt lgkmcnt(0)
	s_barrier
	s_setprio 1
	v_mfma_f32_16x16x32_bf16 v[60:63], v[140:143], v[172:175], v[60:63]
	v_mfma_f32_16x16x32_bf16 v[56:59], v[148:151], v[172:175], v[56:59]
	v_mfma_f32_16x16x32_bf16 v[52:55], v[140:143], v[180:183], v[52:55]
	v_mfma_f32_16x16x32_bf16 v[48:51], v[148:151], v[180:183], v[48:51]
	v_mfma_f32_16x16x32_bf16 v[44:47], v[140:143], v[198:201], v[44:47]
	v_mfma_f32_16x16x32_bf16 v[40:43], v[148:151], v[198:201], v[40:43]
	v_mfma_f32_16x16x32_bf16 v[36:39], v[140:143], v[206:209], v[36:39]
	v_mfma_f32_16x16x32_bf16 v[32:35], v[148:151], v[206:209], v[32:35]
	v_mfma_f32_16x16x32_bf16 v[60:63], v[144:147], v[176:179], v[60:63]
	v_mfma_f32_16x16x32_bf16 v[56:59], v[152:155], v[176:179], v[56:59]
	v_mfma_f32_16x16x32_bf16 v[52:55], v[144:147], v[194:197], v[52:55]
	v_mfma_f32_16x16x32_bf16 v[48:51], v[152:155], v[194:197], v[48:51]
	v_mfma_f32_16x16x32_bf16 v[44:47], v[144:147], v[202:205], v[44:47]
	v_mfma_f32_16x16x32_bf16 v[40:43], v[152:155], v[202:205], v[40:43]
	v_mfma_f32_16x16x32_bf16 v[36:39], v[144:147], v[210:213], v[36:39]
	v_mfma_f32_16x16x32_bf16 v[32:35], v[152:155], v[210:213], v[32:35]
	v_mfma_f32_16x16x32_bf16 v[28:31], v[156:159], v[172:175], v[28:31]
	v_mfma_f32_16x16x32_bf16 v[24:27], v[164:167], v[172:175], v[24:27]
	v_mfma_f32_16x16x32_bf16 v[20:23], v[156:159], v[180:183], v[20:23]
	v_mfma_f32_16x16x32_bf16 v[16:19], v[164:167], v[180:183], v[16:19]
	v_mfma_f32_16x16x32_bf16 v[12:15], v[156:159], v[198:201], v[12:15]
	v_mfma_f32_16x16x32_bf16 v[8:11], v[164:167], v[198:201], v[8:11]
	v_mfma_f32_16x16x32_bf16 v[4:7], v[156:159], v[206:209], v[4:7]
	v_mfma_f32_16x16x32_bf16 v[0:3], v[164:167], v[206:209], v[0:3]
	v_mfma_f32_16x16x32_bf16 v[28:31], v[160:163], v[176:179], v[28:31]
	v_mfma_f32_16x16x32_bf16 v[24:27], v[168:171], v[176:179], v[24:27]
	v_mfma_f32_16x16x32_bf16 v[20:23], v[160:163], v[194:197], v[20:23]
	v_mfma_f32_16x16x32_bf16 v[16:19], v[168:171], v[194:197], v[16:19]
	v_mfma_f32_16x16x32_bf16 v[12:15], v[160:163], v[202:205], v[12:15]
	v_mfma_f32_16x16x32_bf16 v[8:11], v[168:171], v[202:205], v[8:11]
	v_mfma_f32_16x16x32_bf16 v[4:7], v[160:163], v[210:213], v[4:7]
	v_mfma_f32_16x16x32_bf16 v[0:3], v[168:171], v[210:213], v[0:3]
	s_setprio 0
	s_barrier
	s_cmp_ge_u32 s71, s17
	s_mov_b32 s14, s72
	s_mov_b32 s70, s71
	s_cbranch_scc0 .LBB0_217
	s_and_b64 vcc, exec, s[10:11]
	s_movk_i32 s70, 0x1000
	s_cbranch_vccz .LBB0_220
	s_barrier

; #define G_STAGE_A(bufoff, p0, p1, koff) do { \
;         __builtin_amdgcn_global_load_lds((const unsigned*)(gbase + (size_t)(unsigned)((p0) + (koff) + voffA[0])), (LAS unsigned*)(lds + (bufoff) + ldsw), 16, 0, 0); \
;         __builtin_amdgcn_global_load_lds((const unsigned*)(gbase + (size_t)(unsigned)((p1) + (koff) + voffA[1])), (LAS unsigned*)(lds + (bufoff) + ldsw + 8192), 16, 0, 0); } while (0)
; #define G_STAGE_B(bufoff, p, koff) do { \
;         __builtin_amdgcn_global_load_lds((const unsigned*)(gbase + (size_t)(unsigned)((p) + (koff) + voffB[0])), (LAS unsigned*)(lds + (bufoff) + ldsw), 16, 0, 0); \
;         __builtin_amdgcn_global_load_lds((const unsigned*)(gbase + (size_t)(unsigned)((p) + (koff) + voffB[1])), (LAS unsigned*)(lds + (bufoff) + ldsw + 8192), 16, 0, 0); } while (0)
; #define G_LDA(dst, b, h) do { _Pragma("unroll") for (int m = 0; m < 4; ++m) _Pragma("unroll") for (int k = 0; k < 2; ++k) dst[m][k] = *(const LAS bf16x8*)(lds + G_SA(b, h) + aoff + m * 2048 + k * 1024); } while (0)
; #define G_LDB(dst, b, h) do { _Pragma("unroll") for (int n = 0; n < 2; ++n) _Pragma("unroll") for (int k = 0; k < 2; ++k) dst[n][k] = *(const LAS bf16x8*)(lds + G_SB(b, h) + boff + n * 2048 + k * 1024); } while (0)
; #define G_WAIT_V(n) asm volatile("s_waitcnt vmcnt(" #n ")" ::: "memory")
; #define G_BAR __builtin_amdgcn_s_barrier()
; template <class Epi>
; DI void gemm_phase(LAS unsigned char* lds, const Sched& S, const Epi& E, const int K) {
;     ...
;             G_LDB(B0, 0, 0); G_LDB(B1, 0, 1); G_SCHED; G_LDA(At, 0, 0); G_STAGE_A(G_SA(1, 1), cur.a2, cur.a3, k1);
;             G_WAIT_V(8); G_WAIT_L(0); G_BAR; G_MMA(0, 0, At, B0); G_MMA(0, 1, At, B1); G_BAR; G_SCHED;
;             G_LDA(At, 0, 1); G_STAGE_B(G_SB(0, 0), xb, kb2); G_STAGE_B(G_SB(0, 1), xb + hstepB, kb2); G_STAGE_A(G_SA(0, 0), x0, x1, k2);
;             G_WAIT_V(8); G_WAIT_L(0); G_BAR; G_MMA(1, 0, At, B0); G_MMA(1, 1, At, B1); G_BAR; G_SCHED;
;             G_LDB(B0, 1, 0); G_LDB(B1, 1, 1); G_SCHED; G_LDA(At, 1, 0); G_STAGE_A(G_SA(0, 1), x2, x3, k2);
;             G_WAIT_V(8); G_WAIT_L(0); G_BAR; G_MMA(0, 0, At, B0); G_MMA(0, 1, At, B1); G_BAR; G_SCHED;
;             G_LDA(At, 1, 1); G_STAGE_B(G_SB(1, 0), xb, kb3); G_STAGE_B(G_SB(1, 1), xb + hstepB, kb3); G_STAGE_A(G_SA(1, 0), x0, x1, k3);
;             G_WAIT_V(8); G_WAIT_L(0); G_BAR; G_MMA(1, 0, At, B0); G_MMA(1, 1, At, B1); G_BAR; G_SCHED;
.LBB0_240:
	s_add_i32 s14, s15, 0x8000
	v_add_u32_e32 v151, s14, v80
	v_add_u32_e32 v152, s14, v81
	s_add_i32 s14, s15, 0x80
	v_add_u32_e32 v153, s14, v80
	v_add_u32_e32 v154, s14, v81
	s_add_i32 s14, s15, 0x8080
	v_add_u32_e32 v85, s15, v80
	v_add_u32_e32 v150, s15, v81
	v_add_u32_e32 v155, s14, v80
	v_add_u32_e32 v156, s14, v81
	s_add_i32 s14, 0, 0x10000
	s_add_i32 s15, 0, 0x14000
	v_add_u32_e32 v98, s14, v83
	v_add_u32_e32 v114, s15, v83
	ds_read_b128 v[86:89], v98
	ds_read_b128 v[90:93], v98 offset:1024
	ds_read_b128 v[94:97], v98 offset:2048
	ds_read_b128 v[98:101], v98 offset:3072
	ds_read_b128 v[102:105], v114
	ds_read_b128 v[106:109], v114 offset:1024
	ds_read_b128 v[110:113], v114 offset:2048
	ds_read_b128 v[114:117], v114 offset:3072
	s_add_i32 m0, s17, 0xc000
	s_waitcnt vmcnt(0)
	ds_read_b128 v[118:121], v84
	ds_read_b128 v[122:125], v84 offset:1024
	ds_read_b128 v[126:129], v84 offset:2048
	ds_read_b128 v[130:133], v84 offset:3072
	ds_read_b128 v[134:137], v84 offset:4096
	ds_read_b128 v[138:141], v84 offset:5120
	ds_read_b128 v[142:145], v84 offset:6144
	ds_read_b128 v[146:149], v84 offset:7168
	global_load_lds_dwordx4 v[76:77], off
	s_add_i32 m0, s17, 0xe000
	s_nop 0
	global_load_lds_dwordx4 v[78:79], off
	s_waitcnt vmcnt(8)
	s_waitcnt lgkmcnt(0)
	s_barrier
	s_setprio 1
	v_mfma_f32_16x16x32_bf16 v[60:63], v[86:89], v[118:121], v[60:63]
	v_mfma_f32_16x16x32_bf16 v[56:59], v[94:97], v[118:121], v[56:59]
	v_mfma_f32_16x16x32_bf16 v[52:55], v[86:89], v[126:129], v[52:55]
	v_mfma_f32_16x16x32_bf16 v[48:51], v[94:97], v[126:129], v[48:51]
	v_mfma_f32_16x16x32_bf16 v[44:47], v[86:89], v[134:137], v[44:47]
	v_mfma_f32_16x16x32_bf16 v[40:43], v[94:97], v[134:137], v[40:43]
	v_mfma_f32_16x16x32_bf16 v[36:39], v[86:89], v[142:145], v[36:39]
	v_mfma_f32_16x16x32_bf16 v[32:35], v[94:97], v[142:145], v[32:35]
	v_mfma_f32_16x16x32_bf16 v[60:63], v[90:93], v[122:125], v[60:63]
	v_mfma_f32_16x16x32_bf16 v[56:59], v[98:101], v[122:125], v[56:59]
	v_mfma_f32_16x16x32_bf16 v[52:55], v[90:93], v[130:133], v[52:55]
	v_mfma_f32_16x16x32_bf16 v[48:51], v[98:101], v[130:133], v[48:51]
	v_mfma_f32_16x16x32_bf16 v[44:47], v[90:93], v[138:141], v[44:47]
	v_mfma_f32_16x16x32_bf16 v[40:43], v[98:101], v[138:141], v[40:43]
	v_mfma_f32_16x16x32_bf16 v[36:39], v[90:93], v[146:149], v[36:39]
	v_mfma_f32_16x16x32_bf16 v[32:35], v[98:101], v[146:149], v[32:35]
	v_mfma_f32_16x16x32_bf16 v[28:31], v[102:105], v[118:121], v[28:31]
	v_mfma_f32_16x16x32_bf16 v[24:27], v[110:113], v[118:121], v[24:27]
	v_mfma_f32_16x16x32_bf16 v[20:23], v[102:105], v[126:129], v[20:23]
	v_mfma_f32_16x16x32_bf16 v[16:19], v[110:113], v[126:129], v[16:19]
	v_mfma_f32_16x16x32_bf16 v[12:15], v[102:105], v[134:137], v[12:15]
	v_mfma_f32_16x16x32_bf16 v[8:11], v[110:113], v[134:137], v[8:11]
	v_mfma_f32_16x16x32_bf16 v[4:7], v[102:105], v[142:145], v[4:7]
	v_mfma_f32_16x16x32_bf16 v[0:3], v[110:113], v[142:145], v[0:3]
	v_mfma_f32_16x16x32_bf16 v[28:31], v[106:109], v[122:125], v[28:31]
	v_mfma_f32_16x16x32_bf16 v[24:27], v[114:117], v[122:125], v[24:27]
	v_mfma_f32_16x16x32_bf16 v[20:23], v[106:109], v[130:133], v[20:23]
	v_mfma_f32_16x16x32_bf16 v[16:19], v[114:117], v[130:133], v[16:19]
	v_mfma_f32_16x16x32_bf16 v[12:15], v[106:109], v[138:141], v[12:15]
	v_mfma_f32_16x16x32_bf16 v[8:11], v[114:117], v[138:141], v[8:11]
	v_mfma_f32_16x16x32_bf16 v[4:7], v[106:109], v[146:149], v[4:7]
	v_mfma_f32_16x16x32_bf16 v[0:3], v[114:117], v[146:149], v[0:3]
	s_setprio 0
	s_barrier
	s_add_i32 s14, s14, s16
	s_mov_b32 m0, s14
	s_nop 0
	global_load_lds_dwordx4 v85, s[82:83]
	s_add_i32 m0, s14, 0x2000
	s_add_i32 s14, s15, s16
	global_load_lds_dwordx4 v150, s[82:83]
	s_mov_b32 m0, s14
	s_nop 0
	global_load_lds_dwordx4 v151, s[82:83]
	s_add_i32 m0, s14, 0x2000
	s_nop 0
	global_load_lds_dwordx4 v152, s[82:83]
	s_mov_b32 m0, s17
	s_nop 0
	global_load_lds_dwordx4 v[64:65], off
	s_mov_b32 m0, s18
	s_nop 0
	global_load_lds_dwordx4 v[66:67], off
	s_waitcnt vmcnt(8)
	s_waitcnt lgkmcnt(0)
	s_barrier
	s_setprio 1
	s_setprio 0
	s_setprio 1
	s_setprio 0
	s_barrier
	s_add_i32 s14, 0, 0x18000
	v_add_u32_e32 v85, s14, v83
	s_add_i32 s15, 0, 0x1c000
	ds_read_b128 v[86:89], v85
	ds_read_b128 v[90:93], v85 offset:1024
	ds_read_b128 v[94:97], v85 offset:2048
	ds_read_b128 v[98:101], v85 offset:3072
	v_add_u32_e32 v85, s15, v83
	ds_read_b128 v[102:105], v85
	ds_read_b128 v[106:109], v85 offset:1024
	ds_read_b128 v[110:113], v85 offset:2048
	ds_read_b128 v[114:117], v85 offset:3072
	s_mov_b32 m0, s19
	ds_read_b128 v[118:121], v84 offset:32768
	ds_read_b128 v[122:125], v84 offset:33792
	ds_read_b128 v[126:129], v84 offset:34816
	ds_read_b128 v[130:133], v84 offset:35840
	ds_read_b128 v[134:137], v84 offset:36864
	ds_read_b128 v[138:141], v84 offset:37888
	ds_read_b128 v[142:145], v84 offset:38912
	ds_read_b128 v[146:149], v84 offset:39936
	global_load_lds_dwordx4 v[68:69], off
	s_mov_b32 m0, s20
	s_nop 0
	global_load_lds_dwordx4 v[70:71], off
	s_waitcnt vmcnt(8)
	s_waitcnt lgkmcnt(0)
	s_barrier
; #define G_STAGE_A(bufoff, p0, p1, koff) do { \
;         __builtin_amdgcn_global_load_lds((const unsigned*)(gbase + (size_t)(unsigned)((p0) + (koff) + voffA[0])), (LAS unsigned*)(lds + (bufoff) + ldsw), 16, 0, 0); \
;         __builtin_amdgcn_global_load_lds((const unsigned*)(gbase + (size_t)(unsigned)((p1) + (koff) + voffA[1])), (LAS unsigned*)(lds + (bufoff) + ldsw + 8192), 16, 0, 0); } while (0)
; #define G_STAGE_B(bufoff, p, koff) do { \
;         __builtin_amdgcn_global_load_lds((const unsigned*)(gbase + (size_t)(unsigned)((p) + (koff) + voffB[0])), (LAS unsigned*)(lds + (bufoff) + ldsw), 16, 0, 0); \
;         __builtin_amdgcn_global_load_lds((const unsigned*)(gbase + (size_t)(unsigned)((p) + (koff) + voffB[1])), (LAS unsigned*)(lds + (bufoff) + ldsw + 8192), 16, 0, 0); } while (0)
; #define G_LDA(dst, b, h) do { _Pragma("unroll") for (int m = 0; m < 4; ++m) _Pragma("unroll") for (int k = 0; k < 2; ++k) dst[m][k] = *(const LAS bf16x8*)(lds + G_SA(b, h) + aoff + m * 2048 + k * 1024); } while (0)
; #define G_LDB(dst, b, h) do { _Pragma("unroll") for (int n = 0; n < 2; ++n) _Pragma("unroll") for (int k = 0; k < 2; ++k) dst[n][k] = *(const LAS bf16x8*)(lds + G_SB(b, h) + boff + n * 2048 + k * 1024); } while (0)
; #define G_WAIT_V(n) asm volatile("s_waitcnt vmcnt(" #n ")" ::: "memory")
; template <class Epi>
; DI void gemm_phase(LAS unsigned char* lds, const Sched& S, const Epi& E, const int K) {
;     ...
;             G_LDB(B0, 1, 0); G_LDB(B1, 1, 1); G_SCHED; G_LDA(At, 1, 0); G_STAGE_A(G_SA(0, 1), x2, x3, k2);
;             G_WAIT_V(8); G_WAIT_L(0); G_BAR; G_MMA(0, 0, At, B0); G_MMA(0, 1, At, B1); G_BAR; G_SCHED;
;             G_LDA(At, 1, 1); G_STAGE_B(G_SB(1, 0), xb, kb3); G_STAGE_B(G_SB(1, 1), xb + hstepB, kb3); G_STAGE_A(G_SA(1, 0), x0, x1, k3);
;             G_WAIT_V(8); G_WAIT_L(0); G_BAR; G_MMA(1, 0, At, B0); G_MMA(1, 1, At, B1); G_BAR; G_SCHED;
;     DI void operator()(const f32x4 (&acc)[2][2][4][2], const Unit& u, int wr, int wc, int fr, int fq) const {
;     ...
;         const int b = u.z >> 6, k1 = u.z & 63;
; #pragma unroll
;         for (int m = 0; m < 4; ++m) { const int k2 = 16 * m + fr; bf16_t* rowp = MIXCAT + (size_t)(b * 4096 + k1 + 64 * k2) * DM + 1024 + u.pn * 256 + wc * 32 + 8 * fq;
; #pragma unroll
;             for (int bj = 0; bj < 2; ++bj) *(u32x4*)(rowp + bj * 128) = pack8(acc[0][bj][m][0] * 0.015625f, acc[0][bj][m][1] * 0.015625f); }
	s_setprio 1
	v_mfma_f32_16x16x32_bf16 v[60:63], v[86:89], v[118:121], v[60:63]
	v_mfma_f32_16x16x32_bf16 v[56:59], v[94:97], v[118:121], v[56:59]
	v_mfma_f32_16x16x32_bf16 v[52:55], v[86:89], v[126:129], v[52:55]
	v_mfma_f32_16x16x32_bf16 v[48:51], v[94:97], v[126:129], v[48:51]
	v_mfma_f32_16x16x32_bf16 v[44:47], v[86:89], v[134:137], v[44:47]
	v_mfma_f32_16x16x32_bf16 v[40:43], v[94:97], v[134:137], v[40:43]
	v_mfma_f32_16x16x32_bf16 v[36:39], v[86:89], v[142:145], v[36:39]
	v_mfma_f32_16x16x32_bf16 v[32:35], v[94:97], v[142:145], v[32:35]
	v_mfma_f32_16x16x32_bf16 v[60:63], v[90:93], v[122:125], v[60:63]
	v_mfma_f32_16x16x32_bf16 v[56:59], v[98:101], v[122:125], v[56:59]
	v_mfma_f32_16x16x32_bf16 v[52:55], v[90:93], v[130:133], v[52:55]
	v_mfma_f32_16x16x32_bf16 v[48:51], v[98:101], v[130:133], v[48:51]
	v_mfma_f32_16x16x32_bf16 v[44:47], v[90:93], v[138:141], v[44:47]
	v_mfma_f32_16x16x32_bf16 v[40:43], v[98:101], v[138:141], v[40:43]
	v_mfma_f32_16x16x32_bf16 v[36:39], v[90:93], v[146:149], v[36:39]
	v_mfma_f32_16x16x32_bf16 v[32:35], v[98:101], v[146:149], v[32:35]
	v_mfma_f32_16x16x32_bf16 v[28:31], v[102:105], v[118:121], v[28:31]
	v_mfma_f32_16x16x32_bf16 v[24:27], v[110:113], v[118:121], v[24:27]
	v_mfma_f32_16x16x32_bf16 v[20:23], v[102:105], v[126:129], v[20:23]
	v_mfma_f32_16x16x32_bf16 v[16:19], v[110:113], v[126:129], v[16:19]
	v_mfma_f32_16x16x32_bf16 v[12:15], v[102:105], v[134:137], v[12:15]
	v_mfma_f32_16x16x32_bf16 v[8:11], v[110:113], v[134:137], v[8:11]
	v_mfma_f32_16x16x32_bf16 v[4:7], v[102:105], v[142:145], v[4:7]
	v_mfma_f32_16x16x32_bf16 v[0:3], v[110:113], v[142:145], v[0:3]
	v_mfma_f32_16x16x32_bf16 v[28:31], v[106:109], v[122:125], v[28:31]
	v_mfma_f32_16x16x32_bf16 v[24:27], v[114:117], v[122:125], v[24:27]
	v_mfma_f32_16x16x32_bf16 v[20:23], v[106:109], v[130:133], v[20:23]
	v_mfma_f32_16x16x32_bf16 v[16:19], v[114:117], v[130:133], v[16:19]
	v_mfma_f32_16x16x32_bf16 v[12:15], v[106:109], v[138:141], v[12:15]
	v_mfma_f32_16x16x32_bf16 v[8:11], v[114:117], v[138:141], v[8:11]
	v_mfma_f32_16x16x32_bf16 v[4:7], v[106:109], v[146:149], v[4:7]
	v_mfma_f32_16x16x32_bf16 v[0:3], v[114:117], v[146:149], v[0:3]
	s_setprio 0
	s_barrier
	s_add_i32 s14, s14, s16
	s_mov_b32 m0, s14
	s_nop 0
	global_load_lds_dwordx4 v153, s[82:83]
	s_add_i32 m0, s14, 0x2000
	s_add_i32 s14, s15, s16
	global_load_lds_dwordx4 v154, s[82:83]
	s_mov_b32 m0, s14
	s_nop 0
	global_load_lds_dwordx4 v155, s[82:83]
	s_add_i32 m0, s14, 0x2000
	s_nop 0
	global_load_lds_dwordx4 v156, s[82:83]
	s_mov_b32 m0, s21
	s_nop 0
	global_load_lds_dwordx4 v[72:73], off
	s_mov_b32 m0, s24
	s_nop 0
	global_load_lds_dwordx4 v[74:75], off
	s_waitcnt vmcnt(8)
	s_waitcnt lgkmcnt(0)
	s_barrier
	s_setprio 1
	s_setprio 0
	s_setprio 1
	s_setprio 0
	s_barrier
	s_andn2_b64 vcc, exec, s[12:13]
	s_cbranch_vccnz .LBB0_242
	s_lshl_b32 s15, s25, 6
	s_and_b32 s14, s25, 63
	s_and_b32 s15, s15, 0xfffff000
	s_or_b32 s14, s14, s15
	v_or_b32_e32 v90, s14, v82
	s_lshl_b32 s14, s26, 8
	v_ashrrev_i32_e32 v91, 31, v90
	v_readlane_b32 s44, v254, 30
	s_ashr_i32 s15, s14, 31
	v_lshlrev_b64 v[86:87], 12, v[90:91]
	v_readlane_b32 s45, v254, 31
	s_lshl_b64 s[14:15], s[14:15], 1
	s_mov_b32 s40, 0x3c800000
	v_lshl_add_u64 v[86:87], s[44:45], 0, v[86:87]
	v_lshl_add_u64 v[86:87], v[86:87], 0, s[14:15]
	v_lshl_add_u64 v[86:87], v[86:87], 0, s[48:49]
	v_lshl_add_u64 v[92:93], v[86:87], 0, v[184:185]
	v_pk_mul_f32 v[88:89], v[62:63], s[40:41] op_sel_hi:[1,0]
	v_pk_mul_f32 v[86:87], v[60:61], s[40:41] op_sel_hi:[1,0]
	v_pk_mul_f32 v[94:95], v[58:59], s[40:41] op_sel_hi:[1,0]
	v_pk_mul_f32 v[96:97], v[56:57], s[40:41] op_sel_hi:[1,0]
	v_cvt_pk_bf16_f32 v86, v86, v87
	v_cvt_pk_bf16_f32 v87, v88, v89
	v_cvt_pk_bf16_f32 v88, v96, v97
	v_cvt_pk_bf16_f32 v89, v94, v95
	s_barrier
; DI u32x4 pack8(const f32x4& v0, const f32x4& v1) { u32x4 w; w.x = pk2(v0[0], v0[1]); w.y = pk2(v0[2], v0[3]); w.z = pk2(v1[0], v1[1]); w.w = pk2(v1[2], v1[3]); return w; }
;     DI void operator()(const f32x4 (&acc)[2][2][4][2], const Unit& u, int wr, int wc, int fr, int fq) const {
;     ...
;         for (int m = 0; m < 4; ++m) { const int k2 = 16 * m + fr; bf16_t* rowp = MIXCAT + (size_t)(b * 4096 + k1 + 64 * k2) * DM + 1024 + u.pn * 256 + wc * 32 + 8 * fq;
; #pragma unroll
;             for (int bj = 0; bj < 2; ++bj) *(u32x4*)(rowp + bj * 128) = pack8(acc[0][bj][m][0] * 0.015625f, acc[0][bj][m][1] * 0.015625f); }
	global_store_dwordx4 v[92:93], v[86:89], off offset:2048
	v_pk_mul_f32 v[94:95], v[26:27], s[40:41] op_sel_hi:[1,0]
	v_pk_mul_f32 v[96:97], v[24:25], s[40:41] op_sel_hi:[1,0]
	v_pk_mul_f32 v[88:89], v[30:31], s[40:41] op_sel_hi:[1,0]
	v_pk_mul_f32 v[86:87], v[28:29], s[40:41] op_sel_hi:[1,0]
	s_nop 0
	v_cvt_pk_bf16_f32 v86, v86, v87
	v_cvt_pk_bf16_f32 v87, v88, v89
	v_cvt_pk_bf16_f32 v88, v96, v97
	v_cvt_pk_bf16_f32 v89, v94, v95
	global_store_dwordx4 v[92:93], v[86:89], off offset:2304
	v_pk_mul_f32 v[94:95], v[50:51], s[40:41] op_sel_hi:[1,0]
	v_pk_mul_f32 v[96:97], v[48:49], s[40:41] op_sel_hi:[1,0]
	v_or_b32_e32 v86, 0x400, v90
	v_ashrrev_i32_e32 v87, 31, v86
	v_lshlrev_b64 v[86:87], 12, v[86:87]
	v_lshl_add_u64 v[86:87], s[44:45], 0, v[86:87]
	v_lshl_add_u64 v[86:87], v[86:87], 0, s[14:15]
	v_lshl_add_u64 v[86:87], v[86:87], 0, s[48:49]
	v_lshl_add_u64 v[92:93], v[86:87], 0, v[184:185]
	v_pk_mul_f32 v[88:89], v[54:55], s[40:41] op_sel_hi:[1,0]
	v_pk_mul_f32 v[86:87], v[52:53], s[40:41] op_sel_hi:[1,0]
	s_nop 0
	v_cvt_pk_bf16_f32 v86, v86, v87
	v_cvt_pk_bf16_f32 v87, v88, v89
	v_cvt_pk_bf16_f32 v88, v96, v97
	v_cvt_pk_bf16_f32 v89, v94, v95
	global_store_dwordx4 v[92:93], v[86:89], off offset:2048
	v_pk_mul_f32 v[94:95], v[18:19], s[40:41] op_sel_hi:[1,0]
	v_pk_mul_f32 v[96:97], v[16:17], s[40:41] op_sel_hi:[1,0]
	v_pk_mul_f32 v[88:89], v[22:23], s[40:41] op_sel_hi:[1,0]
	v_pk_mul_f32 v[86:87], v[20:21], s[40:41] op_sel_hi:[1,0]
	s_nop 0
	v_cvt_pk_bf16_f32 v86, v86, v87
	v_cvt_pk_bf16_f32 v87, v88, v89
	v_cvt_pk_bf16_f32 v88, v96, v97
	v_cvt_pk_bf16_f32 v89, v94, v95
	global_store_dwordx4 v[92:93], v[86:89], off offset:2304
	v_pk_mul_f32 v[94:95], v[42:43], s[40:41] op_sel_hi:[1,0]
	v_pk_mul_f32 v[96:97], v[40:41], s[40:41] op_sel_hi:[1,0]
	v_or_b32_e32 v86, 0x800, v90
	v_ashrrev_i32_e32 v87, 31, v86
	v_lshlrev_b64 v[86:87], 12, v[86:87]
	v_lshl_add_u64 v[86:87], s[44:45], 0, v[86:87]
	v_lshl_add_u64 v[86:87], v[86:87], 0, s[14:15]
	v_lshl_add_u64 v[86:87], v[86:87], 0, s[48:49]
	v_lshl_add_u64 v[92:93], v[86:87], 0, v[184:185]
	v_pk_mul_f32 v[88:89], v[46:47], s[40:41] op_sel_hi:[1,0]
	v_pk_mul_f32 v[86:87], v[44:45], s[40:41] op_sel_hi:[1,0]
	s_nop 0
	v_cvt_pk_bf16_f32 v86, v86, v87
	v_cvt_pk_bf16_f32 v87, v88, v89
	v_cvt_pk_bf16_f32 v88, v96, v97
	v_cvt_pk_bf16_f32 v89, v94, v95
	global_store_dwordx4 v[92:93], v[86:89], off offset:2048
	v_pk_mul_f32 v[94:95], v[10:11], s[40:41] op_sel_hi:[1,0]
	v_pk_mul_f32 v[96:97], v[8:9], s[40:41] op_sel_hi:[1,0]
	v_pk_mul_f32 v[88:89], v[14:15], s[40:41] op_sel_hi:[1,0]
	v_pk_mul_f32 v[86:87], v[12:13], s[40:41] op_sel_hi:[1,0]
	s_nop 0
	v_cvt_pk_bf16_f32 v86, v86, v87
	v_cvt_pk_bf16_f32 v87, v88, v89
	v_cvt_pk_bf16_f32 v88, v96, v97
	v_cvt_pk_bf16_f32 v89, v94, v95
	global_store_dwordx4 v[92:93], v[86:89], off offset:2304
	v_pk_mul_f32 v[92:93], v[34:35], s[40:41] op_sel_hi:[1,0]
	v_pk_mul_f32 v[94:95], v[32:33], s[40:41] op_sel_hi:[1,0]
	v_or_b32_e32 v86, 0xc00, v90
	v_ashrrev_i32_e32 v87, 31, v86
	v_lshlrev_b64 v[86:87], 12, v[86:87]
	v_lshl_add_u64 v[86:87], s[44:45], 0, v[86:87]
	v_lshl_add_u64 v[86:87], v[86:87], 0, s[14:15]
	v_lshl_add_u64 v[86:87], v[86:87], 0, s[48:49]
	v_lshl_add_u64 v[90:91], v[86:87], 0, v[184:185]
	v_pk_mul_f32 v[88:89], v[38:39], s[40:41] op_sel_hi:[1,0]
	v_pk_mul_f32 v[86:87], v[36:37], s[40:41] op_sel_hi:[1,0]
	s_nop 0
	v_cvt_pk_bf16_f32 v86, v86, v87
	v_cvt_pk_bf16_f32 v87, v88, v89
	v_cvt_pk_bf16_f32 v88, v94, v95
	v_cvt_pk_bf16_f32 v89, v92, v93
	global_store_dwordx4 v[90:91], v[86:89], off offset:2048
	v_pk_mul_f32 v[92:93], v[2:3], s[40:41] op_sel_hi:[1,0]
	v_pk_mul_f32 v[94:95], v[0:1], s[40:41] op_sel_hi:[1,0]
	v_pk_mul_f32 v[88:89], v[6:7], s[40:41] op_sel_hi:[1,0]
	v_pk_mul_f32 v[86:87], v[4:5], s[40:41] op_sel_hi:[1,0]
	s_nop 0
	v_cvt_pk_bf16_f32 v86, v86, v87
	v_cvt_pk_bf16_f32 v87, v88, v89
	v_cvt_pk_bf16_f32 v88, v94, v95
	v_cvt_pk_bf16_f32 v89, v92, v93
	global_store_dwordx4 v[90:91], v[86:89], off offset:2304
	s_andn2_b64 vcc, exec, s[10:11]
	s_cbranch_vccnz .LBB0_233
	s_branch .LBB0_243

; #define G_STAGE_A(bufoff, p0, p1, koff) do { \
;         __builtin_amdgcn_global_load_lds((const unsigned*)(gbase + (size_t)(unsigned)((p0) + (koff) + voffA[0])), (LAS unsigned*)(lds + (bufoff) + ldsw), 16, 0, 0); \
;         __builtin_amdgcn_global_load_lds((const unsigned*)(gbase + (size_t)(unsigned)((p1) + (koff) + voffA[1])), (LAS unsigned*)(lds + (bufoff) + ldsw + 8192), 16, 0, 0); } while (0)
; #define G_STAGE_B(bufoff, p, koff) do { \
;         __builtin_amdgcn_global_load_lds((const unsigned*)(gbase + (size_t)(unsigned)((p) + (koff) + voffB[0])), (LAS unsigned*)(lds + (bufoff) + ldsw), 16, 0, 0); \
;         __builtin_amdgcn_global_load_lds((const unsigned*)(gbase + (size_t)(unsigned)((p) + (koff) + voffB[1])), (LAS unsigned*)(lds + (bufoff) + ldsw + 8192), 16, 0, 0); } while (0)
; #define G_LDA(dst, b, h) do { _Pragma("unroll") for (int m = 0; m < 4; ++m) _Pragma("unroll") for (int k = 0; k < 2; ++k) dst[m][k] = *(const LAS bf16x8*)(lds + G_SA(b, h) + aoff + m * 2048 + k * 1024); } while (0)
; #define G_LDB(dst, b, h) do { _Pragma("unroll") for (int n = 0; n < 2; ++n) _Pragma("unroll") for (int k = 0; k < 2; ++k) dst[n][k] = *(const LAS bf16x8*)(lds + G_SB(b, h) + boff + n * 2048 + k * 1024); } while (0)
; #define G_MMA(ai, bj, At, Bt) do { __builtin_amdgcn_s_setprio(1); _Pragma("unroll") for (int m = 0; m < 4; ++m) _Pragma("unroll") for (int n = 0; n < 2; ++n) _Pragma("unroll") for (int k = 0; k < 2; ++k) \
;         acc[ai][bj][m][n] = __builtin_amdgcn_mfma_f32_16x16x32_bf16(Bt[n][k], At[m][k], acc[ai][bj][m][n], 0, 0, 0); __builtin_amdgcn_s_setprio(0); } while (0)
; template <class Epi>
; DI void gemm_phase(LAS unsigned char* lds, const Sched& S, const Epi& E, const int K) {
;     ...
;             G_LDB(B0, 0, 0); G_LDB(B1, 0, 1); G_SCHED; G_LDA(At, 0, 0); G_STAGE_A(G_SA(1, 1), cur.a2, cur.a3, k1);
;             G_WAIT_V(8); G_WAIT_L(0); G_BAR; G_MMA(0, 0, At, B0); G_MMA(0, 1, At, B1); G_BAR; G_SCHED;
;             G_LDA(At, 0, 1); G_STAGE_B(G_SB(0, 0), xb, kb2); G_STAGE_B(G_SB(0, 1), xb + hstepB, kb2); G_STAGE_A(G_SA(0, 0), x0, x1, k2);
;             G_WAIT_V(8); G_WAIT_L(0); G_BAR; G_MMA(1, 0, At, B0); G_MMA(1, 1, At, B1); G_BAR; G_SCHED;
;             G_LDB(B0, 1, 0); G_LDB(B1, 1, 1); G_SCHED; G_LDA(At, 1, 0); G_STAGE_A(G_SA(0, 1), x2, x3, k2);
;             G_WAIT_V(8); G_WAIT_L(0); G_BAR; G_MMA(0, 0, At, B0); G_MMA(0, 1, At, B1); G_BAR; G_SCHED;
.LBB0_261:
	s_add_i32 s12, s13, 0x8000
	v_add_u32_e32 v182, s12, v170
	v_add_u32_e32 v183, s12, v171
	s_add_i32 s12, s13, 0x2000
	v_add_u32_e32 v226, s12, v170
	v_add_u32_e32 v229, s12, v171
	s_add_i32 s12, s13, 0xa000
	v_add_u32_e32 v168, s13, v170
	v_add_u32_e32 v169, s13, v171
	v_add_u32_e32 v233, s12, v170
	v_add_u32_e32 v250, s12, v171
	s_add_i32 s12, 0, 0x10000
	s_add_i32 s13, 0, 0x14000
	v_add_u32_e32 v164, s12, v173
	v_add_u32_e32 v202, s13, v173
	ds_read_b128 v[152:155], v164
	ds_read_b128 v[156:159], v164 offset:1024
	ds_read_b128 v[160:163], v164 offset:2048
	ds_read_b128 v[164:167], v164 offset:3072
	ds_read_b128 v[178:181], v202
	ds_read_b128 v[194:197], v202 offset:1024
	ds_read_b128 v[198:201], v202 offset:2048
	ds_read_b128 v[202:205], v202 offset:3072
	s_add_i32 m0, s17, 0xc000
	ds_read_b128 v[206:209], v177
	ds_read_b128 v[210:213], v177 offset:1024
	ds_read_b128 v[214:217], v177 offset:2048
	ds_read_b128 v[218:221], v177 offset:3072
	ds_read_b128 v[222:225], v177 offset:4096
	ds_read_b128 v[234:237], v177 offset:5120
	ds_read_b128 v[242:245], v177 offset:6144
	ds_read_b128 v[246:249], v177 offset:7168
	global_load_lds_dwordx4 v[148:149], off
	s_add_i32 m0, s17, 0xe000
	s_nop 0
	global_load_lds_dwordx4 v[150:151], off
	s_waitcnt vmcnt(8)
	s_waitcnt lgkmcnt(0)
	s_barrier
	s_setprio 1
	v_mfma_f32_16x16x32_bf16 v[124:127], v[152:155], v[206:209], v[124:127]
	v_mfma_f32_16x16x32_bf16 v[120:123], v[160:163], v[206:209], v[120:123]
	v_mfma_f32_16x16x32_bf16 v[116:119], v[152:155], v[214:217], v[116:119]
	v_mfma_f32_16x16x32_bf16 v[112:115], v[160:163], v[214:217], v[112:115]
	v_mfma_f32_16x16x32_bf16 v[108:111], v[152:155], v[222:225], v[108:111]
	v_mfma_f32_16x16x32_bf16 v[104:107], v[160:163], v[222:225], v[104:107]
	v_mfma_f32_16x16x32_bf16 v[100:103], v[152:155], v[242:245], v[100:103]
	v_mfma_f32_16x16x32_bf16 v[96:99], v[160:163], v[242:245], v[96:99]
	v_mfma_f32_16x16x32_bf16 v[124:127], v[156:159], v[210:213], v[124:127]
	v_mfma_f32_16x16x32_bf16 v[120:123], v[164:167], v[210:213], v[120:123]
	v_mfma_f32_16x16x32_bf16 v[116:119], v[156:159], v[218:221], v[116:119]
	v_mfma_f32_16x16x32_bf16 v[112:115], v[164:167], v[218:221], v[112:115]
	v_mfma_f32_16x16x32_bf16 v[108:111], v[156:159], v[234:237], v[108:111]
	v_mfma_f32_16x16x32_bf16 v[104:107], v[164:167], v[234:237], v[104:107]
	v_mfma_f32_16x16x32_bf16 v[100:103], v[156:159], v[246:249], v[100:103]
	v_mfma_f32_16x16x32_bf16 v[96:99], v[164:167], v[246:249], v[96:99]
	v_mfma_f32_16x16x32_bf16 v[92:95], v[178:181], v[206:209], v[92:95]
	v_mfma_f32_16x16x32_bf16 v[88:91], v[198:201], v[206:209], v[88:91]
	v_mfma_f32_16x16x32_bf16 v[84:87], v[178:181], v[214:217], v[84:87]
	v_mfma_f32_16x16x32_bf16 v[80:83], v[198:201], v[214:217], v[80:83]
	v_mfma_f32_16x16x32_bf16 v[76:79], v[178:181], v[222:225], v[76:79]
	v_mfma_f32_16x16x32_bf16 v[72:75], v[198:201], v[222:225], v[72:75]
	v_mfma_f32_16x16x32_bf16 v[68:71], v[178:181], v[242:245], v[68:71]
	v_mfma_f32_16x16x32_bf16 v[64:67], v[198:201], v[242:245], v[64:67]
	v_mfma_f32_16x16x32_bf16 v[92:95], v[194:197], v[210:213], v[92:95]
	v_mfma_f32_16x16x32_bf16 v[88:91], v[202:205], v[210:213], v[88:91]
	v_mfma_f32_16x16x32_bf16 v[84:87], v[194:197], v[218:221], v[84:87]
	v_mfma_f32_16x16x32_bf16 v[80:83], v[202:205], v[218:221], v[80:83]
	v_mfma_f32_16x16x32_bf16 v[76:79], v[194:197], v[234:237], v[76:79]
	v_mfma_f32_16x16x32_bf16 v[72:75], v[202:205], v[234:237], v[72:75]
	v_mfma_f32_16x16x32_bf16 v[68:71], v[194:197], v[246:249], v[68:71]
	v_mfma_f32_16x16x32_bf16 v[64:67], v[202:205], v[246:249], v[64:67]
	s_setprio 0
	s_barrier
	s_add_i32 s12, s12, s16
	s_mov_b32 m0, s12
	ds_read_b128 v[206:209], v177 offset:16384
	ds_read_b128 v[210:213], v177 offset:17408
	ds_read_b128 v[214:217], v177 offset:18432
	ds_read_b128 v[218:221], v177 offset:19456
	ds_read_b128 v[222:225], v177 offset:20480
	ds_read_b128 v[234:237], v177 offset:21504
	ds_read_b128 v[242:245], v177 offset:22528
	ds_read_b128 v[246:249], v177 offset:23552
	global_load_lds_dwordx4 v168, s[82:83]
	s_add_i32 m0, s12, 0x2000
	s_add_i32 s12, s13, s16
	global_load_lds_dwordx4 v169, s[82:83]
	s_mov_b32 m0, s12
	s_nop 0
	global_load_lds_dwordx4 v182, s[82:83]
	s_add_i32 m0, s12, 0x2000
	s_nop 0
	global_load_lds_dwordx4 v183, s[82:83]
	s_mov_b32 m0, s17
	s_nop 0
	global_load_lds_dwordx4 v[128:129], off
	s_mov_b32 m0, s18
	s_nop 0
	global_load_lds_dwordx4 v[130:131], off
	s_waitcnt vmcnt(8)
	s_waitcnt lgkmcnt(0)
	s_barrier
	s_setprio 1
	v_mfma_f32_16x16x32_bf16 v[60:63], v[152:155], v[206:209], v[60:63]
	v_mfma_f32_16x16x32_bf16 v[56:59], v[160:163], v[206:209], v[56:59]
	v_mfma_f32_16x16x32_bf16 v[52:55], v[152:155], v[214:217], v[52:55]
	v_mfma_f32_16x16x32_bf16 v[48:51], v[160:163], v[214:217], v[48:51]
	v_mfma_f32_16x16x32_bf16 v[44:47], v[152:155], v[222:225], v[44:47]
	v_mfma_f32_16x16x32_bf16 v[40:43], v[160:163], v[222:225], v[40:43]
	v_mfma_f32_16x16x32_bf16 v[36:39], v[152:155], v[242:245], v[36:39]
	v_mfma_f32_16x16x32_bf16 v[32:35], v[160:163], v[242:245], v[32:35]
	v_mfma_f32_16x16x32_bf16 v[60:63], v[156:159], v[210:213], v[60:63]
	v_mfma_f32_16x16x32_bf16 v[56:59], v[164:167], v[210:213], v[56:59]
	v_mfma_f32_16x16x32_bf16 v[52:55], v[156:159], v[218:221], v[52:55]
	v_mfma_f32_16x16x32_bf16 v[48:51], v[164:167], v[218:221], v[48:51]
	v_mfma_f32_16x16x32_bf16 v[44:47], v[156:159], v[234:237], v[44:47]
	v_mfma_f32_16x16x32_bf16 v[40:43], v[164:167], v[234:237], v[40:43]
	v_mfma_f32_16x16x32_bf16 v[36:39], v[156:159], v[246:249], v[36:39]
	v_mfma_f32_16x16x32_bf16 v[32:35], v[164:167], v[246:249], v[32:35]
	v_mfma_f32_16x16x32_bf16 v[28:31], v[178:181], v[206:209], v[28:31]
	v_mfma_f32_16x16x32_bf16 v[24:27], v[198:201], v[206:209], v[24:27]
	v_mfma_f32_16x16x32_bf16 v[20:23], v[178:181], v[214:217], v[20:23]
	v_mfma_f32_16x16x32_bf16 v[16:19], v[198:201], v[214:217], v[16:19]
	v_mfma_f32_16x16x32_bf16 v[12:15], v[178:181], v[222:225], v[12:15]
	v_mfma_f32_16x16x32_bf16 v[8:11], v[198:201], v[222:225], v[8:11]
	v_mfma_f32_16x16x32_bf16 v[4:7], v[178:181], v[242:245], v[4:7]
	v_mfma_f32_16x16x32_bf16 v[0:3], v[198:201], v[242:245], v[0:3]
	v_mfma_f32_16x16x32_bf16 v[28:31], v[194:197], v[210:213], v[28:31]
	v_mfma_f32_16x16x32_bf16 v[24:27], v[202:205], v[210:213], v[24:27]
	v_mfma_f32_16x16x32_bf16 v[20:23], v[194:197], v[218:221], v[20:23]
	v_mfma_f32_16x16x32_bf16 v[16:19], v[202:205], v[218:221], v[16:19]
	v_mfma_f32_16x16x32_bf16 v[12:15], v[194:197], v[234:237], v[12:15]
	v_mfma_f32_16x16x32_bf16 v[8:11], v[202:205], v[234:237], v[8:11]
	v_mfma_f32_16x16x32_bf16 v[4:7], v[194:197], v[246:249], v[4:7]
	v_mfma_f32_16x16x32_bf16 v[0:3], v[202:205], v[246:249], v[0:3]
	s_setprio 0
	s_barrier
; #define G_STAGE_A(bufoff, p0, p1, koff) do { \
;         __builtin_amdgcn_global_load_lds((const unsigned*)(gbase + (size_t)(unsigned)((p0) + (koff) + voffA[0])), (LAS unsigned*)(lds + (bufoff) + ldsw), 16, 0, 0); \
;         __builtin_amdgcn_global_load_lds((const unsigned*)(gbase + (size_t)(unsigned)((p1) + (koff) + voffA[1])), (LAS unsigned*)(lds + (bufoff) + ldsw + 8192), 16, 0, 0); } while (0)
; #define G_STAGE_B(bufoff, p, koff) do { \
;         __builtin_amdgcn_global_load_lds((const unsigned*)(gbase + (size_t)(unsigned)((p) + (koff) + voffB[0])), (LAS unsigned*)(lds + (bufoff) + ldsw), 16, 0, 0); \
;         __builtin_amdgcn_global_load_lds((const unsigned*)(gbase + (size_t)(unsigned)((p) + (koff) + voffB[1])), (LAS unsigned*)(lds + (bufoff) + ldsw + 8192), 16, 0, 0); } while (0)
; #define G_LDA(dst, b, h) do { _Pragma("unroll") for (int m = 0; m < 4; ++m) _Pragma("unroll") for (int k = 0; k < 2; ++k) dst[m][k] = *(const LAS bf16x8*)(lds + G_SA(b, h) + aoff + m * 2048 + k * 1024); } while (0)
; #define G_LDB(dst, b, h) do { _Pragma("unroll") for (int n = 0; n < 2; ++n) _Pragma("unroll") for (int k = 0; k < 2; ++k) dst[n][k] = *(const LAS bf16x8*)(lds + G_SB(b, h) + boff + n * 2048 + k * 1024); } while (0)
; #define G_MMA(ai, bj, At, Bt) do { __builtin_amdgcn_s_setprio(1); _Pragma("unroll") for (int m = 0; m < 4; ++m) _Pragma("unroll") for (int n = 0; n < 2; ++n) _Pragma("unroll") for (int k = 0; k < 2; ++k) \
;         acc[ai][bj][m][n] = __builtin_amdgcn_mfma_f32_16x16x32_bf16(Bt[n][k], At[m][k], acc[ai][bj][m][n], 0, 0, 0); __builtin_amdgcn_s_setprio(0); } while (0)
; #define G_WAIT_V(n) asm volatile("s_waitcnt vmcnt(" #n ")" ::: "memory")
; #define G_WAIT_L(n) asm volatile("s_waitcnt lgkmcnt(" #n ")" ::: "memory")
; #define G_BAR __builtin_amdgcn_s_barrier()
; template <class Epi>
; DI void gemm_phase(LAS unsigned char* lds, const Sched& S, const Epi& E, const int K) {
;     ...
;             G_LDB(B0, 1, 0); G_LDB(B1, 1, 1); G_SCHED; G_LDA(At, 1, 0); G_STAGE_A(G_SA(0, 1), x2, x3, k2);
;             G_WAIT_V(8); G_WAIT_L(0); G_BAR; G_MMA(0, 0, At, B0); G_MMA(0, 1, At, B1); G_BAR; G_SCHED;
;             G_LDA(At, 1, 1); G_STAGE_B(G_SB(1, 0), xb, kb3); G_STAGE_B(G_SB(1, 1), xb + hstepB, kb3); G_STAGE_A(G_SA(1, 0), x0, x1, k3);
;             G_WAIT_V(8); G_WAIT_L(0); G_BAR; G_MMA(1, 0, At, B0); G_MMA(1, 1, At, B1); G_BAR; G_SCHED;
	s_add_i32 s12, 0, 0x18000
	s_add_i32 s13, 0, 0x1c000
	v_add_u32_e32 v164, s12, v173
	v_add_u32_e32 v168, s13, v173
	ds_read_b128 v[152:155], v164
	ds_read_b128 v[156:159], v164 offset:1024
	ds_read_b128 v[160:163], v164 offset:2048
	ds_read_b128 v[164:167], v164 offset:3072
	ds_read_b128 v[178:181], v168
	ds_read_b128 v[194:197], v168 offset:1024
	ds_read_b128 v[198:201], v168 offset:2048
	ds_read_b128 v[202:205], v168 offset:3072
	s_mov_b32 m0, s19
	ds_read_b128 v[206:209], v177 offset:32768
	ds_read_b128 v[210:213], v177 offset:33792
	ds_read_b128 v[214:217], v177 offset:34816
	ds_read_b128 v[218:221], v177 offset:35840
	ds_read_b128 v[222:225], v177 offset:36864
	ds_read_b128 v[234:237], v177 offset:37888
	ds_read_b128 v[242:245], v177 offset:38912
	ds_read_b128 v[246:249], v177 offset:39936
	global_load_lds_dwordx4 v[132:133], off
	s_mov_b32 m0, s20
	s_nop 0
	global_load_lds_dwordx4 v[134:135], off
	s_waitcnt vmcnt(8)
	s_waitcnt lgkmcnt(0)
	s_barrier
	s_setprio 1
	v_mfma_f32_16x16x32_bf16 v[124:127], v[152:155], v[206:209], v[124:127]
	v_mfma_f32_16x16x32_bf16 v[120:123], v[160:163], v[206:209], v[120:123]
	v_mfma_f32_16x16x32_bf16 v[116:119], v[152:155], v[214:217], v[116:119]
	v_mfma_f32_16x16x32_bf16 v[112:115], v[160:163], v[214:217], v[112:115]
	v_mfma_f32_16x16x32_bf16 v[108:111], v[152:155], v[222:225], v[108:111]
	v_mfma_f32_16x16x32_bf16 v[104:107], v[160:163], v[222:225], v[104:107]
	v_mfma_f32_16x16x32_bf16 v[100:103], v[152:155], v[242:245], v[100:103]
	v_mfma_f32_16x16x32_bf16 v[96:99], v[160:163], v[242:245], v[96:99]
	v_mfma_f32_16x16x32_bf16 v[124:127], v[156:159], v[210:213], v[124:127]
	v_mfma_f32_16x16x32_bf16 v[120:123], v[164:167], v[210:213], v[120:123]
	v_mfma_f32_16x16x32_bf16 v[116:119], v[156:159], v[218:221], v[116:119]
	v_mfma_f32_16x16x32_bf16 v[112:115], v[164:167], v[218:221], v[112:115]
	v_mfma_f32_16x16x32_bf16 v[108:111], v[156:159], v[234:237], v[108:111]
	v_mfma_f32_16x16x32_bf16 v[104:107], v[164:167], v[234:237], v[104:107]
	v_mfma_f32_16x16x32_bf16 v[100:103], v[156:159], v[246:249], v[100:103]
	v_mfma_f32_16x16x32_bf16 v[96:99], v[164:167], v[246:249], v[96:99]
	v_mfma_f32_16x16x32_bf16 v[92:95], v[178:181], v[206:209], v[92:95]
	v_mfma_f32_16x16x32_bf16 v[88:91], v[198:201], v[206:209], v[88:91]
	v_mfma_f32_16x16x32_bf16 v[84:87], v[178:181], v[214:217], v[84:87]
	v_mfma_f32_16x16x32_bf16 v[80:83], v[198:201], v[214:217], v[80:83]
	v_mfma_f32_16x16x32_bf16 v[76:79], v[178:181], v[222:225], v[76:79]
	v_mfma_f32_16x16x32_bf16 v[72:75], v[198:201], v[222:225], v[72:75]
	v_mfma_f32_16x16x32_bf16 v[68:71], v[178:181], v[242:245], v[68:71]
	v_mfma_f32_16x16x32_bf16 v[64:67], v[198:201], v[242:245], v[64:67]
	v_mfma_f32_16x16x32_bf16 v[92:95], v[194:197], v[210:213], v[92:95]
	v_mfma_f32_16x16x32_bf16 v[88:91], v[202:205], v[210:213], v[88:91]
	v_mfma_f32_16x16x32_bf16 v[84:87], v[194:197], v[218:221], v[84:87]
	v_mfma_f32_16x16x32_bf16 v[80:83], v[202:205], v[218:221], v[80:83]
	v_mfma_f32_16x16x32_bf16 v[76:79], v[194:197], v[234:237], v[76:79]
	v_mfma_f32_16x16x32_bf16 v[72:75], v[202:205], v[234:237], v[72:75]
	v_mfma_f32_16x16x32_bf16 v[68:71], v[194:197], v[246:249], v[68:71]
	v_mfma_f32_16x16x32_bf16 v[64:67], v[202:205], v[246:249], v[64:67]
	s_setprio 0
	s_barrier
	s_add_i32 s12, s12, s16
	s_mov_b32 m0, s12
	ds_read_b128 v[206:209], v177 offset:49152
	ds_read_b128 v[210:213], v177 offset:50176
	ds_read_b128 v[214:217], v177 offset:51200
	ds_read_b128 v[218:221], v177 offset:52224
	ds_read_b128 v[222:225], v177 offset:53248
	ds_read_b128 v[234:237], v177 offset:54272
	ds_read_b128 v[242:245], v177 offset:55296
	ds_read_b128 v[246:249], v177 offset:56320
	global_load_lds_dwordx4 v226, s[82:83]
	s_add_i32 m0, s12, 0x2000
	s_add_i32 s12, s13, s16
	global_load_lds_dwordx4 v229, s[82:83]
	s_mov_b32 m0, s12
	s_nop 0
	global_load_lds_dwordx4 v233, s[82:83]
	s_add_i32 m0, s12, 0x2000
	s_nop 0
	global_load_lds_dwordx4 v250, s[82:83]
	s_mov_b32 m0, s21
	s_nop 0
	global_load_lds_dwordx4 v[136:137], off
	s_mov_b32 m0, s24
	s_nop 0
	global_load_lds_dwordx4 v[138:139], off
	s_waitcnt vmcnt(8)
	s_waitcnt lgkmcnt(0)
	s_barrier
	s_setprio 1
	v_mfma_f32_16x16x32_bf16 v[60:63], v[152:155], v[206:209], v[60:63]
	v_mfma_f32_16x16x32_bf16 v[56:59], v[160:163], v[206:209], v[56:59]
	v_mfma_f32_16x16x32_bf16 v[52:55], v[152:155], v[214:217], v[52:55]
	v_mfma_f32_16x16x32_bf16 v[48:51], v[160:163], v[214:217], v[48:51]
	v_mfma_f32_16x16x32_bf16 v[44:47], v[152:155], v[222:225], v[44:47]
	v_mfma_f32_16x16x32_bf16 v[40:43], v[160:163], v[222:225], v[40:43]
	v_mfma_f32_16x16x32_bf16 v[36:39], v[152:155], v[242:245], v[36:39]
	v_mfma_f32_16x16x32_bf16 v[32:35], v[160:163], v[242:245], v[32:35]
	v_mfma_f32_16x16x32_bf16 v[60:63], v[156:159], v[210:213], v[60:63]
	v_mfma_f32_16x16x32_bf16 v[56:59], v[164:167], v[210:213], v[56:59]
	v_mfma_f32_16x16x32_bf16 v[52:55], v[156:159], v[218:221], v[52:55]
	v_mfma_f32_16x16x32_bf16 v[48:51], v[164:167], v[218:221], v[48:51]
	v_mfma_f32_16x16x32_bf16 v[44:47], v[156:159], v[234:237], v[44:47]
	v_mfma_f32_16x16x32_bf16 v[40:43], v[164:167], v[234:237], v[40:43]
	v_mfma_f32_16x16x32_bf16 v[36:39], v[156:159], v[246:249], v[36:39]
	v_mfma_f32_16x16x32_bf16 v[32:35], v[164:167], v[246:249], v[32:35]
	v_mfma_f32_16x16x32_bf16 v[28:31], v[178:181], v[206:209], v[28:31]
	v_mfma_f32_16x16x32_bf16 v[24:27], v[198:201], v[206:209], v[24:27]
	v_mfma_f32_16x16x32_bf16 v[20:23], v[178:181], v[214:217], v[20:23]
	v_mfma_f32_16x16x32_bf16 v[16:19], v[198:201], v[214:217], v[16:19]
	v_mfma_f32_16x16x32_bf16 v[12:15], v[178:181], v[222:225], v[12:15]
	v_mfma_f32_16x16x32_bf16 v[8:11], v[198:201], v[222:225], v[8:11]
	v_mfma_f32_16x16x32_bf16 v[4:7], v[178:181], v[242:245], v[4:7]
	v_mfma_f32_16x16x32_bf16 v[0:3], v[198:201], v[242:245], v[0:3]
	v_mfma_f32_16x16x32_bf16 v[28:31], v[194:197], v[210:213], v[28:31]
	v_mfma_f32_16x16x32_bf16 v[24:27], v[202:205], v[210:213], v[24:27]
	v_mfma_f32_16x16x32_bf16 v[20:23], v[194:197], v[218:221], v[20:23]
	v_mfma_f32_16x16x32_bf16 v[16:19], v[202:205], v[218:221], v[16:19]
	v_mfma_f32_16x16x32_bf16 v[12:15], v[194:197], v[234:237], v[12:15]
	v_mfma_f32_16x16x32_bf16 v[8:11], v[202:205], v[234:237], v[8:11]
	v_mfma_f32_16x16x32_bf16 v[4:7], v[194:197], v[246:249], v[4:7]
	v_mfma_f32_16x16x32_bf16 v[0:3], v[202:205], v[246:249], v[0:3]
	s_setprio 0
	s_barrier
; #define G_BAR __builtin_amdgcn_s_barrier()
; DI u32x4 pack8(const f32x4& v0, const f32x4& v1) { u32x4 w; w.x = pk2(v0[0], v0[1]); w.y = pk2(v0[2], v0[3]); w.z = pk2(v1[0], v1[1]); w.w = pk2(v1[2], v1[3]); return w; }
; template <class Epi>
; DI void gemm_phase(LAS unsigned char* lds, const Sched& S, const Epi& E, const int K) {
;     ...
;         if (wr == 0) G_BAR;
;     DI void operator()(const f32x4 (&acc)[2][2][4][2], const Unit& u, int wr, int wc, int fr, int fq) const {
;     ...
;             const int k1 = 16 * m + fr;
; #pragma unroll
;             for (int bj = 0; bj < 2; ++bj) {
;                 const int j0 = 128 * bj + 32 * wc + 8 * fq, ge = 4 * u.pn + (j0 >> 6), nl0 = j0 & 63;
;                 const f32x4* tw = (const f32x4*)(TW + (size_t)(k1 * 64 + nl0) * 2);
;                 f32x4 yr[2], yi[2];
; #pragma unroll
;                 for (int n = 0; n < 2; ++n) {
;                     const f32x4 t0 = tw[2 * n], t1 = tw[2 * n + 1];
;                     const f32x4 c = {t0.x, t0.z, t1.x, t1.z}, s = {t0.y, t0.w, t1.y, t1.w};
;                     const f32x4 r = acc[0][bj][m][n], i = acc[1][bj][m][n];
;                     yr[n] = c * r + s * i; yi[n] = c * i - s * r;
;                 }
;                 bf16_t* dst = YP + ((((size_t)(u.z * 64 + k1)) * 1024 + ge) * 2) * 64 + nl0;
;                 *(u32x4*)dst = pack8(yr[0], yr[1]); *(u32x4*)(dst + 64) = pack8(yi[0], yi[1]);
	s_andn2_b64 vcc, exec, s[10:11]
	s_cbranch_vccnz .LBB0_263
	s_lshl_b32 s44, s26, 6
	v_or_b32_e32 v152, s44, v172
	v_ashrrev_i32_e32 v153, 31, v152
	s_barrier
	v_lshlrev_b64 v[182:183], 18, v[152:153]
	global_load_dwordx4 v[178:181], v[140:141], off offset:32
	global_load_dwordx4 v[162:165], v[140:141], off offset:48
	global_load_dwordx4 v[152:155], v[140:141], off
	global_load_dwordx4 v[156:159], v[140:141], off offset:16
	s_lshl_b32 s12, s27, 2
	s_or_b32 s14, s12, s25
	v_readlane_b32 s46, v254, 39
	s_ashr_i32 s15, s14, 31
	v_readlane_b32 s47, v254, 40
	s_lshl_b64 s[12:13], s[14:15], 8
	s_or_b32 s14, s14, 2
	s_ashr_i32 s15, s14, 31
	s_lshl_b64 s[14:15], s[14:15], 8
	s_waitcnt vmcnt(0)
	v_mov_b32_e32 v168, v153
	v_mov_b32_e32 v166, v157
	v_mov_b32_e32 v167, v159
	v_mov_b32_e32 v169, v155
	v_pk_mul_f32 v[160:161], v[62:63], v[166:167]
	v_pk_mul_f32 v[194:195], v[60:61], v[168:169]
	v_mov_b32_e32 v157, v158
	v_mov_b32_e32 v153, v154
	v_pk_mul_f32 v[154:155], v[126:127], v[166:167]
	v_pk_mul_f32 v[166:167], v[124:125], v[168:169]
	v_pk_fma_f32 v[158:159], v[126:127], v[156:157], v[160:161]
	v_pk_fma_f32 v[160:161], v[124:125], v[152:153], v[194:195]
	v_pk_fma_f32 v[154:155], v[62:63], v[156:157], v[154:155] neg_lo:[0,0,1] neg_hi:[0,0,1]
	v_pk_fma_f32 v[156:157], v[60:61], v[152:153], v[166:167] neg_lo:[0,0,1] neg_hi:[0,0,1]
	v_mov_b32_e32 v152, v163
	v_mov_b32_e32 v153, v165
	v_pk_mul_f32 v[166:167], v[58:59], v[152:153]
	v_mov_b32_e32 v194, v179
	v_mov_b32_e32 v195, v181
	v_mov_b32_e32 v163, v164
	v_pk_mul_f32 v[152:153], v[122:123], v[152:153]
	v_pk_mul_f32 v[168:169], v[56:57], v[194:195]
	v_pk_fma_f32 v[166:167], v[122:123], v[162:163], v[166:167]
	v_mov_b32_e32 v179, v180
	v_pk_mul_f32 v[164:165], v[120:121], v[194:195]
	v_pk_fma_f32 v[162:163], v[58:59], v[162:163], v[152:153] neg_lo:[0,0,1] neg_hi:[0,0,1]
	v_lshl_add_u64 v[152:153], s[46:47], 0, v[182:183]
	v_pk_fma_f32 v[168:169], v[120:121], v[178:179], v[168:169]
	v_pk_fma_f32 v[164:165], v[56:57], v[178:179], v[164:165] neg_lo:[0,0,1] neg_hi:[0,0,1]
	v_lshl_add_u64 v[178:179], v[152:153], 0, s[12:13]
	v_lshl_add_u64 v[182:183], v[178:179], 0, v[184:185]
	v_cvt_pk_bf16_f32 v178, v160, v161
	v_cvt_pk_bf16_f32 v179, v158, v159
	v_cvt_pk_bf16_f32 v180, v168, v169
	v_cvt_pk_bf16_f32 v181, v166, v167
	v_cvt_pk_bf16_f32 v156, v156, v157
	v_cvt_pk_bf16_f32 v157, v154, v155
	v_cvt_pk_bf16_f32 v158, v164, v165
	v_cvt_pk_bf16_f32 v159, v162, v163
	global_store_dwordx4 v[182:183], v[178:181], off
	global_store_dwordx4 v[182:183], v[156:159], off offset:128
	global_load_dwordx4 v[178:181], v[140:141], off offset:32
	s_nop 0
	global_load_dwordx4 v[162:165], v[140:141], off offset:48
	global_load_dwordx4 v[166:169], v[140:141], off
	global_load_dwordx4 v[154:157], v[140:141], off offset:16
	v_lshl_add_u64 v[152:153], v[152:153], 0, s[14:15]
	s_waitcnt vmcnt(1)
	v_mov_b32_e32 v194, v167
	s_waitcnt vmcnt(0)
	v_mov_b32_e32 v182, v155
	v_mov_b32_e32 v183, v157
	v_mov_b32_e32 v195, v169
	v_pk_mul_f32 v[158:159], v[30:31], v[182:183]
	v_pk_mul_f32 v[160:161], v[28:29], v[194:195]
	v_mov_b32_e32 v155, v156
	v_mov_b32_e32 v167, v168
	v_pk_mul_f32 v[156:157], v[94:95], v[182:183]
	v_pk_mul_f32 v[168:169], v[92:93], v[194:195]
	v_mov_b32_e32 v182, v163
	v_mov_b32_e32 v183, v165
	v_mov_b32_e32 v194, v179
	v_mov_b32_e32 v195, v181
	v_pk_fma_f32 v[158:159], v[94:95], v[154:155], v[158:159]
	v_pk_fma_f32 v[160:161], v[92:93], v[166:167], v[160:161]
	v_pk_fma_f32 v[154:155], v[30:31], v[154:155], v[156:157] neg_lo:[0,0,1] neg_hi:[0,0,1]
	v_pk_fma_f32 v[156:157], v[28:29], v[166:167], v[168:169] neg_lo:[0,0,1] neg_hi:[0,0,1]
	v_pk_mul_f32 v[166:167], v[26:27], v[182:183]
	v_mov_b32_e32 v163, v164
	v_mov_b32_e32 v179, v180
	v_pk_mul_f32 v[164:165], v[90:91], v[182:183]
	v_pk_mul_f32 v[180:181], v[88:89], v[194:195]
	v_pk_mul_f32 v[168:169], v[24:25], v[194:195]
	v_pk_fma_f32 v[166:167], v[90:91], v[162:163], v[166:167]
	v_pk_fma_f32 v[162:163], v[26:27], v[162:163], v[164:165] neg_lo:[0,0,1] neg_hi:[0,0,1]
	v_pk_fma_f32 v[164:165], v[24:25], v[178:179], v[180:181] neg_lo:[0,0,1] neg_hi:[0,0,1]
	v_pk_fma_f32 v[168:169], v[88:89], v[178:179], v[168:169]
	v_lshl_add_u64 v[182:183], v[152:153], 0, v[184:185]
	v_cvt_pk_bf16_f32 v152, v156, v157
	v_cvt_pk_bf16_f32 v153, v154, v155
	v_cvt_pk_bf16_f32 v154, v164, v165
	v_cvt_pk_bf16_f32 v155, v162, v163
	v_cvt_pk_bf16_f32 v178, v160, v161
	v_cvt_pk_bf16_f32 v179, v158, v159
	v_cvt_pk_bf16_f32 v180, v168, v169
	v_cvt_pk_bf16_f32 v181, v166, v167
	global_store_dwordx4 v[182:183], v[152:155], off offset:128
	global_store_dwordx4 v[182:183], v[178:181], off
	s_nop 0
	v_or_b32_e32 v152, s44, v174
	v_ashrrev_i32_e32 v153, 31, v152
	v_lshlrev_b64 v[182:183], 18, v[152:153]
	global_load_dwordx4 v[178:181], v[142:143], off offset:32
	global_load_dwordx4 v[162:165], v[142:143], off offset:48
	global_load_dwordx4 v[152:155], v[142:143], off
	global_load_dwordx4 v[156:159], v[142:143], off offset:16
	s_waitcnt vmcnt(1)
	v_mov_b32_e32 v168, v153
	s_waitcnt vmcnt(0)
; DI u32x4 pack8(const f32x4& v0, const f32x4& v1) { u32x4 w; w.x = pk2(v0[0], v0[1]); w.y = pk2(v0[2], v0[3]); w.z = pk2(v1[0], v1[1]); w.w = pk2(v1[2], v1[3]); return w; }
;     DI void operator()(const f32x4 (&acc)[2][2][4][2], const Unit& u, int wr, int wc, int fr, int fq) const {
;         if (wr != 0) return;
; #pragma unroll
;         for (int m = 0; m < 4; ++m) {
;             const int k1 = 16 * m + fr;
; #pragma unroll
;             for (int bj = 0; bj < 2; ++bj) {
;                 const int j0 = 128 * bj + 32 * wc + 8 * fq, ge = 4 * u.pn + (j0 >> 6), nl0 = j0 & 63;
;                 const f32x4* tw = (const f32x4*)(TW + (size_t)(k1 * 64 + nl0) * 2);
;                 f32x4 yr[2], yi[2];
; #pragma unroll
;                 for (int n = 0; n < 2; ++n) {
;                     const f32x4 t0 = tw[2 * n], t1 = tw[2 * n + 1];
;                     const f32x4 c = {t0.x, t0.z, t1.x, t1.z}, s = {t0.y, t0.w, t1.y, t1.w};
;                     const f32x4 r = acc[0][bj][m][n], i = acc[1][bj][m][n];
;                     yr[n] = c * r + s * i; yi[n] = c * i - s * r;
;                 }
;                 bf16_t* dst = YP + ((((size_t)(u.z * 64 + k1)) * 1024 + ge) * 2) * 64 + nl0;
;                 *(u32x4*)dst = pack8(yr[0], yr[1]); *(u32x4*)(dst + 64) = pack8(yi[0], yi[1]);
;             }
;         }
;     }
	v_mov_b32_e32 v166, v157
	v_mov_b32_e32 v167, v159
	v_mov_b32_e32 v169, v155
	v_pk_mul_f32 v[160:161], v[54:55], v[166:167]
	v_pk_mul_f32 v[194:195], v[52:53], v[168:169]
	v_mov_b32_e32 v157, v158
	v_mov_b32_e32 v153, v154
	v_pk_mul_f32 v[154:155], v[118:119], v[166:167]
	v_pk_mul_f32 v[166:167], v[116:117], v[168:169]
	v_pk_fma_f32 v[158:159], v[118:119], v[156:157], v[160:161]
	v_pk_fma_f32 v[160:161], v[116:117], v[152:153], v[194:195]
	v_pk_fma_f32 v[154:155], v[54:55], v[156:157], v[154:155] neg_lo:[0,0,1] neg_hi:[0,0,1]
	v_pk_fma_f32 v[156:157], v[52:53], v[152:153], v[166:167] neg_lo:[0,0,1] neg_hi:[0,0,1]
	v_mov_b32_e32 v152, v163
	v_mov_b32_e32 v153, v165
	v_pk_mul_f32 v[166:167], v[50:51], v[152:153]
	v_mov_b32_e32 v194, v179
	v_mov_b32_e32 v195, v181
	v_mov_b32_e32 v163, v164
	v_pk_mul_f32 v[152:153], v[114:115], v[152:153]
	v_pk_mul_f32 v[168:169], v[48:49], v[194:195]
	v_pk_fma_f32 v[166:167], v[114:115], v[162:163], v[166:167]
	v_mov_b32_e32 v179, v180
	v_pk_mul_f32 v[164:165], v[112:113], v[194:195]
	v_pk_fma_f32 v[162:163], v[50:51], v[162:163], v[152:153] neg_lo:[0,0,1] neg_hi:[0,0,1]
	v_lshl_add_u64 v[152:153], s[46:47], 0, v[182:183]
	v_pk_fma_f32 v[168:169], v[112:113], v[178:179], v[168:169]
	v_pk_fma_f32 v[164:165], v[48:49], v[178:179], v[164:165] neg_lo:[0,0,1] neg_hi:[0,0,1]
	v_lshl_add_u64 v[178:179], v[152:153], 0, s[12:13]
	v_lshl_add_u64 v[182:183], v[178:179], 0, v[184:185]
	v_cvt_pk_bf16_f32 v178, v160, v161
	v_cvt_pk_bf16_f32 v179, v158, v159
	v_cvt_pk_bf16_f32 v180, v168, v169
	v_cvt_pk_bf16_f32 v181, v166, v167
	v_cvt_pk_bf16_f32 v156, v156, v157
	v_cvt_pk_bf16_f32 v157, v154, v155
	v_cvt_pk_bf16_f32 v158, v164, v165
	v_cvt_pk_bf16_f32 v159, v162, v163
	global_store_dwordx4 v[182:183], v[178:181], off
	global_store_dwordx4 v[182:183], v[156:159], off offset:128
	global_load_dwordx4 v[178:181], v[142:143], off offset:32
	s_nop 0
	global_load_dwordx4 v[162:165], v[142:143], off offset:48
	global_load_dwordx4 v[166:169], v[142:143], off
	global_load_dwordx4 v[154:157], v[142:143], off offset:16
	v_lshl_add_u64 v[152:153], v[152:153], 0, s[14:15]
	s_waitcnt vmcnt(1)
	v_mov_b32_e32 v194, v167
	s_waitcnt vmcnt(0)
	v_mov_b32_e32 v182, v155
	v_mov_b32_e32 v183, v157
	v_mov_b32_e32 v195, v169
	v_pk_mul_f32 v[158:159], v[22:23], v[182:183]
	v_pk_mul_f32 v[160:161], v[20:21], v[194:195]
	v_mov_b32_e32 v155, v156
	v_mov_b32_e32 v167, v168
	v_pk_mul_f32 v[156:157], v[86:87], v[182:183]
	v_pk_mul_f32 v[168:169], v[84:85], v[194:195]
	v_mov_b32_e32 v182, v163
	v_mov_b32_e32 v183, v165
	v_mov_b32_e32 v194, v179
	v_mov_b32_e32 v195, v181
	v_pk_fma_f32 v[158:159], v[86:87], v[154:155], v[158:159]
	v_pk_fma_f32 v[160:161], v[84:85], v[166:167], v[160:161]
	v_pk_fma_f32 v[154:155], v[22:23], v[154:155], v[156:157] neg_lo:[0,0,1] neg_hi:[0,0,1]
	v_pk_fma_f32 v[156:157], v[20:21], v[166:167], v[168:169] neg_lo:[0,0,1] neg_hi:[0,0,1]
	v_pk_mul_f32 v[166:167], v[18:19], v[182:183]
	v_mov_b32_e32 v163, v164
	v_mov_b32_e32 v179, v180
	v_pk_mul_f32 v[164:165], v[82:83], v[182:183]
	v_pk_mul_f32 v[180:181], v[80:81], v[194:195]
	v_pk_mul_f32 v[168:169], v[16:17], v[194:195]
	v_pk_fma_f32 v[166:167], v[82:83], v[162:163], v[166:167]
	v_pk_fma_f32 v[162:163], v[18:19], v[162:163], v[164:165] neg_lo:[0,0,1] neg_hi:[0,0,1]
	v_pk_fma_f32 v[164:165], v[16:17], v[178:179], v[180:181] neg_lo:[0,0,1] neg_hi:[0,0,1]
	v_pk_fma_f32 v[168:169], v[80:81], v[178:179], v[168:169]
	v_lshl_add_u64 v[182:183], v[152:153], 0, v[184:185]
	v_cvt_pk_bf16_f32 v152, v156, v157
	v_cvt_pk_bf16_f32 v153, v154, v155
	v_cvt_pk_bf16_f32 v154, v164, v165
	v_cvt_pk_bf16_f32 v155, v162, v163
	v_cvt_pk_bf16_f32 v178, v160, v161
	v_cvt_pk_bf16_f32 v179, v158, v159
	v_cvt_pk_bf16_f32 v180, v168, v169
	v_cvt_pk_bf16_f32 v181, v166, v167
	global_store_dwordx4 v[182:183], v[152:155], off offset:128
	global_store_dwordx4 v[182:183], v[178:181], off
	s_nop 0
	v_or_b32_e32 v152, s44, v175
	v_ashrrev_i32_e32 v153, 31, v152
	v_lshlrev_b64 v[182:183], 18, v[152:153]
	global_load_dwordx4 v[178:181], v[144:145], off offset:32
	global_load_dwordx4 v[162:165], v[144:145], off offset:48
	global_load_dwordx4 v[152:155], v[144:145], off
	global_load_dwordx4 v[156:159], v[144:145], off offset:16
	s_waitcnt vmcnt(1)
	v_mov_b32_e32 v168, v153
	s_waitcnt vmcnt(0)
	v_mov_b32_e32 v166, v157
	v_mov_b32_e32 v167, v159
	v_mov_b32_e32 v169, v155
	v_pk_mul_f32 v[160:161], v[46:47], v[166:167]
	v_pk_mul_f32 v[194:195], v[44:45], v[168:169]
	v_mov_b32_e32 v157, v158
	v_mov_b32_e32 v153, v154
	v_pk_mul_f32 v[154:155], v[110:111], v[166:167]
	v_pk_mul_f32 v[166:167], v[108:109], v[168:169]
	v_pk_fma_f32 v[158:159], v[110:111], v[156:157], v[160:161]
	v_pk_fma_f32 v[160:161], v[108:109], v[152:153], v[194:195]
	v_pk_fma_f32 v[154:155], v[46:47], v[156:157], v[154:155] neg_lo:[0,0,1] neg_hi:[0,0,1]
	v_pk_fma_f32 v[156:157], v[44:45], v[152:153], v[166:167] neg_lo:[0,0,1] neg_hi:[0,0,1]
	v_mov_b32_e32 v152, v163
	v_mov_b32_e32 v153, v165
	v_pk_mul_f32 v[166:167], v[42:43], v[152:153]
	v_mov_b32_e32 v194, v179
	v_mov_b32_e32 v195, v181
	v_mov_b32_e32 v163, v164
	v_pk_mul_f32 v[152:153], v[106:107], v[152:153]
	v_pk_mul_f32 v[168:169], v[40:41], v[194:195]
	v_pk_fma_f32 v[166:167], v[106:107], v[162:163], v[166:167]
	v_mov_b32_e32 v179, v180
	v_pk_mul_f32 v[164:165], v[104:105], v[194:195]
	v_pk_fma_f32 v[162:163], v[42:43], v[162:163], v[152:153] neg_lo:[0,0,1] neg_hi:[0,0,1]
	v_lshl_add_u64 v[152:153], s[46:47], 0, v[182:183]
	v_pk_fma_f32 v[168:169], v[104:105], v[178:179], v[168:169]
	v_pk_fma_f32 v[164:165], v[40:41], v[178:179], v[164:165] neg_lo:[0,0,1] neg_hi:[0,0,1]
	v_lshl_add_u64 v[178:179], v[152:153], 0, s[12:13]
	v_lshl_add_u64 v[182:183], v[178:179], 0, v[184:185]
	v_cvt_pk_bf16_f32 v178, v160, v161
	v_cvt_pk_bf16_f32 v179, v158, v159
	v_cvt_pk_bf16_f32 v180, v168, v169
	v_cvt_pk_bf16_f32 v181, v166, v167
	v_cvt_pk_bf16_f32 v156, v156, v157
	v_cvt_pk_bf16_f32 v157, v154, v155
	v_cvt_pk_bf16_f32 v158, v164, v165
	v_cvt_pk_bf16_f32 v159, v162, v163
	global_store_dwordx4 v[182:183], v[178:181], off
	global_store_dwordx4 v[182:183], v[156:159], off offset:128
	global_load_dwordx4 v[178:181], v[144:145], off offset:32
	s_nop 0
	global_load_dwordx4 v[162:165], v[144:145], off offset:48
	global_load_dwordx4 v[166:169], v[144:145], off
	global_load_dwordx4 v[154:157], v[144:145], off offset:16
	v_lshl_add_u64 v[152:153], v[152:153], 0, s[14:15]
	s_waitcnt vmcnt(1)
; DI u32x4 pack8(const f32x4& v0, const f32x4& v1) { u32x4 w; w.x = pk2(v0[0], v0[1]); w.y = pk2(v0[2], v0[3]); w.z = pk2(v1[0], v1[1]); w.w = pk2(v1[2], v1[3]); return w; }
;     DI void operator()(const f32x4 (&acc)[2][2][4][2], const Unit& u, int wr, int wc, int fr, int fq) const {
;         if (wr != 0) return;
; #pragma unroll
;         for (int m = 0; m < 4; ++m) {
;             const int k1 = 16 * m + fr;
; #pragma unroll
;             for (int bj = 0; bj < 2; ++bj) {
;                 const int j0 = 128 * bj + 32 * wc + 8 * fq, ge = 4 * u.pn + (j0 >> 6), nl0 = j0 & 63;
;                 const f32x4* tw = (const f32x4*)(TW + (size_t)(k1 * 64 + nl0) * 2);
;                 f32x4 yr[2], yi[2];
; #pragma unroll
;                 for (int n = 0; n < 2; ++n) {
;                     const f32x4 t0 = tw[2 * n], t1 = tw[2 * n + 1];
;                     const f32x4 c = {t0.x, t0.z, t1.x, t1.z}, s = {t0.y, t0.w, t1.y, t1.w};
;                     const f32x4 r = acc[0][bj][m][n], i = acc[1][bj][m][n];
;                     yr[n] = c * r + s * i; yi[n] = c * i - s * r;
;                 }
;                 bf16_t* dst = YP + ((((size_t)(u.z * 64 + k1)) * 1024 + ge) * 2) * 64 + nl0;
;                 *(u32x4*)dst = pack8(yr[0], yr[1]); *(u32x4*)(dst + 64) = pack8(yi[0], yi[1]);
;             }
;         }
;     }
	v_mov_b32_e32 v194, v167
	s_waitcnt vmcnt(0)
	v_mov_b32_e32 v182, v155
	v_mov_b32_e32 v183, v157
	v_mov_b32_e32 v195, v169
	v_pk_mul_f32 v[158:159], v[14:15], v[182:183]
	v_pk_mul_f32 v[160:161], v[12:13], v[194:195]
	v_mov_b32_e32 v155, v156
	v_mov_b32_e32 v167, v168
	v_pk_mul_f32 v[156:157], v[78:79], v[182:183]
	v_pk_mul_f32 v[168:169], v[76:77], v[194:195]
	v_mov_b32_e32 v182, v163
	v_mov_b32_e32 v183, v165
	v_mov_b32_e32 v194, v179
	v_mov_b32_e32 v195, v181
	v_pk_fma_f32 v[158:159], v[78:79], v[154:155], v[158:159]
	v_pk_fma_f32 v[160:161], v[76:77], v[166:167], v[160:161]
	v_pk_fma_f32 v[154:155], v[14:15], v[154:155], v[156:157] neg_lo:[0,0,1] neg_hi:[0,0,1]
	v_pk_fma_f32 v[156:157], v[12:13], v[166:167], v[168:169] neg_lo:[0,0,1] neg_hi:[0,0,1]
	v_pk_mul_f32 v[166:167], v[10:11], v[182:183]
	v_mov_b32_e32 v163, v164
	v_mov_b32_e32 v179, v180
	v_pk_mul_f32 v[164:165], v[74:75], v[182:183]
	v_pk_mul_f32 v[180:181], v[72:73], v[194:195]
	v_pk_mul_f32 v[168:169], v[8:9], v[194:195]
	v_pk_fma_f32 v[166:167], v[74:75], v[162:163], v[166:167]
	v_pk_fma_f32 v[162:163], v[10:11], v[162:163], v[164:165] neg_lo:[0,0,1] neg_hi:[0,0,1]
	v_pk_fma_f32 v[164:165], v[8:9], v[178:179], v[180:181] neg_lo:[0,0,1] neg_hi:[0,0,1]
	v_pk_fma_f32 v[168:169], v[72:73], v[178:179], v[168:169]
	v_lshl_add_u64 v[182:183], v[152:153], 0, v[184:185]
	v_cvt_pk_bf16_f32 v152, v156, v157
	v_cvt_pk_bf16_f32 v153, v154, v155
	v_cvt_pk_bf16_f32 v154, v164, v165
	v_cvt_pk_bf16_f32 v155, v162, v163
	v_cvt_pk_bf16_f32 v178, v160, v161
	v_cvt_pk_bf16_f32 v179, v158, v159
	v_cvt_pk_bf16_f32 v180, v168, v169
	v_cvt_pk_bf16_f32 v181, v166, v167
	global_store_dwordx4 v[182:183], v[152:155], off offset:128
	global_store_dwordx4 v[182:183], v[178:181], off
	s_nop 0
	v_or_b32_e32 v152, s44, v176
	v_ashrrev_i32_e32 v153, 31, v152
	v_lshlrev_b64 v[182:183], 18, v[152:153]
	global_load_dwordx4 v[178:181], v[146:147], off offset:32
	global_load_dwordx4 v[162:165], v[146:147], off offset:48
	global_load_dwordx4 v[152:155], v[146:147], off
	global_load_dwordx4 v[156:159], v[146:147], off offset:16
	s_waitcnt vmcnt(1)
	v_mov_b32_e32 v168, v153
	s_waitcnt vmcnt(0)
	v_mov_b32_e32 v166, v157
	v_mov_b32_e32 v167, v159
	v_mov_b32_e32 v169, v155
	v_pk_mul_f32 v[160:161], v[38:39], v[166:167]
	v_pk_mul_f32 v[194:195], v[36:37], v[168:169]
	v_mov_b32_e32 v157, v158
	v_mov_b32_e32 v153, v154
	v_pk_mul_f32 v[154:155], v[102:103], v[166:167]
	v_pk_mul_f32 v[166:167], v[100:101], v[168:169]
	v_pk_fma_f32 v[158:159], v[102:103], v[156:157], v[160:161]
	v_pk_fma_f32 v[160:161], v[100:101], v[152:153], v[194:195]
	v_pk_fma_f32 v[154:155], v[38:39], v[156:157], v[154:155] neg_lo:[0,0,1] neg_hi:[0,0,1]
	v_pk_fma_f32 v[156:157], v[36:37], v[152:153], v[166:167] neg_lo:[0,0,1] neg_hi:[0,0,1]
	v_mov_b32_e32 v152, v163
	v_mov_b32_e32 v153, v165
	v_pk_mul_f32 v[166:167], v[34:35], v[152:153]
	v_mov_b32_e32 v194, v179
	v_mov_b32_e32 v195, v181
	v_mov_b32_e32 v163, v164
	v_pk_mul_f32 v[152:153], v[98:99], v[152:153]
	v_pk_mul_f32 v[168:169], v[32:33], v[194:195]
	v_pk_fma_f32 v[166:167], v[98:99], v[162:163], v[166:167]
	v_mov_b32_e32 v179, v180
	v_pk_mul_f32 v[164:165], v[96:97], v[194:195]
	v_pk_fma_f32 v[162:163], v[34:35], v[162:163], v[152:153] neg_lo:[0,0,1] neg_hi:[0,0,1]
	v_lshl_add_u64 v[152:153], s[46:47], 0, v[182:183]
	v_pk_fma_f32 v[168:169], v[96:97], v[178:179], v[168:169]
	v_pk_fma_f32 v[164:165], v[32:33], v[178:179], v[164:165] neg_lo:[0,0,1] neg_hi:[0,0,1]
	v_lshl_add_u64 v[178:179], v[152:153], 0, s[12:13]
	v_lshl_add_u64 v[182:183], v[178:179], 0, v[184:185]
	v_cvt_pk_bf16_f32 v178, v160, v161
	v_cvt_pk_bf16_f32 v179, v158, v159
	v_cvt_pk_bf16_f32 v180, v168, v169
	v_cvt_pk_bf16_f32 v181, v166, v167
	v_cvt_pk_bf16_f32 v156, v156, v157
	v_cvt_pk_bf16_f32 v157, v154, v155
	v_cvt_pk_bf16_f32 v158, v164, v165
	v_cvt_pk_bf16_f32 v159, v162, v163
	global_store_dwordx4 v[182:183], v[178:181], off
	global_store_dwordx4 v[182:183], v[156:159], off offset:128
	global_load_dwordx4 v[178:181], v[146:147], off offset:32
	s_nop 0
	global_load_dwordx4 v[162:165], v[146:147], off offset:48
	global_load_dwordx4 v[166:169], v[146:147], off
	global_load_dwordx4 v[154:157], v[146:147], off offset:16
	v_lshl_add_u64 v[152:153], v[152:153], 0, s[14:15]
	s_waitcnt vmcnt(1)
	v_mov_b32_e32 v194, v167
	s_waitcnt vmcnt(0)
	v_mov_b32_e32 v182, v155
	v_mov_b32_e32 v183, v157
	v_mov_b32_e32 v195, v169
	v_pk_mul_f32 v[158:159], v[6:7], v[182:183]
	v_pk_mul_f32 v[160:161], v[4:5], v[194:195]
	v_mov_b32_e32 v155, v156
	v_mov_b32_e32 v167, v168
	v_pk_mul_f32 v[156:157], v[70:71], v[182:183]
	v_pk_mul_f32 v[168:169], v[68:69], v[194:195]
	v_mov_b32_e32 v182, v163
	v_mov_b32_e32 v183, v165
	v_mov_b32_e32 v194, v179
	v_mov_b32_e32 v195, v181
	v_pk_fma_f32 v[158:159], v[70:71], v[154:155], v[158:159]
	v_pk_fma_f32 v[160:161], v[68:69], v[166:167], v[160:161]
	v_pk_fma_f32 v[154:155], v[6:7], v[154:155], v[156:157] neg_lo:[0,0,1] neg_hi:[0,0,1]
	v_pk_fma_f32 v[156:157], v[4:5], v[166:167], v[168:169] neg_lo:[0,0,1] neg_hi:[0,0,1]
	v_pk_mul_f32 v[166:167], v[2:3], v[182:183]
	v_pk_mul_f32 v[168:169], v[0:1], v[194:195]
	v_mov_b32_e32 v163, v164
	v_mov_b32_e32 v179, v180
	v_pk_mul_f32 v[164:165], v[66:67], v[182:183]
	v_pk_mul_f32 v[180:181], v[64:65], v[194:195]
	v_pk_fma_f32 v[166:167], v[66:67], v[162:163], v[166:167]
	v_pk_fma_f32 v[168:169], v[64:65], v[178:179], v[168:169]
	v_pk_fma_f32 v[162:163], v[2:3], v[162:163], v[164:165] neg_lo:[0,0,1] neg_hi:[0,0,1]
	v_pk_fma_f32 v[164:165], v[0:1], v[178:179], v[180:181] neg_lo:[0,0,1] neg_hi:[0,0,1]
	v_lshl_add_u64 v[182:183], v[152:153], 0, v[184:185]
	v_cvt_pk_bf16_f32 v178, v160, v161
	v_cvt_pk_bf16_f32 v179, v158, v159
	v_cvt_pk_bf16_f32 v180, v168, v169
	v_cvt_pk_bf16_f32 v181, v166, v167
	v_cvt_pk_bf16_f32 v152, v156, v157
	v_cvt_pk_bf16_f32 v153, v154, v155
	v_cvt_pk_bf16_f32 v154, v164, v165
	v_cvt_pk_bf16_f32 v155, v162, v163
	global_store_dwordx4 v[182:183], v[178:181], off
	global_store_dwordx4 v[182:183], v[152:155], off offset:128
	s_andn2_b64 vcc, exec, s[8:9]
	s_cbranch_vccnz .LBB0_254
	s_branch .LBB0_264

; #define G_STAGE_A(bufoff, p0, p1, koff) do { \
;         __builtin_amdgcn_global_load_lds((const unsigned*)(gbase + (size_t)(unsigned)((p0) + (koff) + voffA[0])), (LAS unsigned*)(lds + (bufoff) + ldsw), 16, 0, 0); \
;         __builtin_amdgcn_global_load_lds((const unsigned*)(gbase + (size_t)(unsigned)((p1) + (koff) + voffA[1])), (LAS unsigned*)(lds + (bufoff) + ldsw + 8192), 16, 0, 0); } while (0)
; #define G_STAGE_B(bufoff, p, koff) do { \
;         __builtin_amdgcn_global_load_lds((const unsigned*)(gbase + (size_t)(unsigned)((p) + (koff) + voffB[0])), (LAS unsigned*)(lds + (bufoff) + ldsw), 16, 0, 0); \
;         __builtin_amdgcn_global_load_lds((const unsigned*)(gbase + (size_t)(unsigned)((p) + (koff) + voffB[1])), (LAS unsigned*)(lds + (bufoff) + ldsw + 8192), 16, 0, 0); } while (0)
; template <class Epi>
; DI void gemm_phase(LAS unsigned char* lds, const Sched& S, const Epi& E, const int K) {
;     ...
;         for (int t = 0; t < nt; t += 2) {
;             const bool last = (t == nt - 2);
;             const unsigned k1 = (unsigned)(t + 1) * kstepA;
;             const unsigned k2 = last ? 0u : (unsigned)(t + 2) * kstepA, k3 = k2 + kstepA;
;             const unsigned kb2 = last ? 0u : (unsigned)(t + 2) * kstepB, kb3 = kb2 + kstepB;
;             const unsigned x0 = last ? n0 : cur.a0, x1 = last ? n1 : cur.a1, x2 = last ? n2 : cur.a2, x3 = last ? n3 : cur.a3;
;             const unsigned xb = last ? nB : cur.b;
;     ...
;             G_LDB(B0, 0, 0); G_LDB(B1, 0, 1); G_SCHED; G_LDA(At, 0, 0); G_STAGE_A(G_SA(1, 1), cur.a2, cur.a3, k1);
;             G_WAIT_V(8); G_WAIT_L(0); G_BAR; G_MMA(0, 0, At, B0); G_MMA(0, 1, At, B1); G_BAR; G_SCHED;
;             G_LDA(At, 0, 1); G_STAGE_B(G_SB(0, 0), xb, kb2); G_STAGE_B(G_SB(0, 1), xb + hstepB, kb2); G_STAGE_A(G_SA(0, 0), x0, x1, k2);
;             G_WAIT_V(8); G_WAIT_L(0); G_BAR; G_MMA(1, 0, At, B0); G_MMA(1, 1, At, B1); G_BAR; G_SCHED;
;             G_LDB(B0, 1, 0); G_LDB(B1, 1, 1); G_SCHED; G_LDA(At, 1, 0); G_STAGE_A(G_SA(0, 1), x2, x3, k2);
;             G_WAIT_V(8); G_WAIT_L(0); G_BAR; G_MMA(0, 0, At, B0); G_MMA(0, 1, At, B1); G_BAR; G_SCHED;
;             G_LDA(At, 1, 1); G_STAGE_B(G_SB(1, 0), xb, kb3); G_STAGE_B(G_SB(1, 1), xb + hstepB, kb3); G_STAGE_A(G_SA(1, 0), x0, x1, k3);
;             G_WAIT_V(8); G_WAIT_L(0); G_BAR; G_MMA(1, 0, At, B0); G_MMA(1, 1, At, B1); G_BAR; G_SCHED;
.LBB0_281:
	s_add_u32 s14, s12, 0x100
	s_addc_u32 s15, s13, 0
	s_cmp_eq_u32 s44, 4
	s_cselect_b32 s40, 0, s14
	s_cselect_b32 s46, s41, s35
	s_add_i32 s47, 0, 0x10000
	v_add_u32_e32 v132, s47, v136
	s_add_i32 s48, 0, 0x14000
	ds_read_b128 v[144:147], v132
	ds_read_b128 v[148:151], v132 offset:1024
	ds_read_b128 v[152:155], v132 offset:2048
	ds_read_b128 v[156:159], v132 offset:3072
	v_add_u32_e32 v132, s48, v136
	ds_read_b128 v[160:163], v132
	ds_read_b128 v[164:167], v132 offset:1024
	ds_read_b128 v[168:171], v132 offset:2048
	ds_read_b128 v[172:175], v132 offset:3072
	s_or_b32 s45, s40, 0x80
	v_lshl_add_u64 v[132:133], v[130:131], 0, s[12:13]
	s_add_i32 m0, s17, 0xc000
	ds_read_b128 v[176:179], v143
	ds_read_b128 v[180:183], v143 offset:1024
	ds_read_b128 v[194:197], v143 offset:2048
	ds_read_b128 v[198:201], v143 offset:3072
	ds_read_b128 v[202:205], v143 offset:4096
	ds_read_b128 v[206:209], v143 offset:5120
	ds_read_b128 v[210:213], v143 offset:6144
	ds_read_b128 v[214:217], v143 offset:7168
	global_load_lds_dwordx4 v[132:133], off
	v_lshl_add_u64 v[132:133], v[128:129], 0, s[12:13]
	s_add_i32 m0, s17, 0xe000
	s_nop 0
	global_load_lds_dwordx4 v[132:133], off
	s_waitcnt vmcnt(8)
	s_waitcnt lgkmcnt(0)
	s_barrier
	s_setprio 1
	v_mfma_f32_16x16x32_bf16 v[124:127], v[144:147], v[176:179], v[124:127]
	v_mfma_f32_16x16x32_bf16 v[120:123], v[152:155], v[176:179], v[120:123]
	v_mfma_f32_16x16x32_bf16 v[116:119], v[144:147], v[194:197], v[116:119]
	v_mfma_f32_16x16x32_bf16 v[112:115], v[152:155], v[194:197], v[112:115]
	v_mfma_f32_16x16x32_bf16 v[108:111], v[144:147], v[202:205], v[108:111]
	v_mfma_f32_16x16x32_bf16 v[104:107], v[152:155], v[202:205], v[104:107]
	v_mfma_f32_16x16x32_bf16 v[100:103], v[144:147], v[210:213], v[100:103]
	v_mfma_f32_16x16x32_bf16 v[96:99], v[152:155], v[210:213], v[96:99]
	v_mfma_f32_16x16x32_bf16 v[124:127], v[148:151], v[180:183], v[124:127]
	v_mfma_f32_16x16x32_bf16 v[120:123], v[156:159], v[180:183], v[120:123]
	v_mfma_f32_16x16x32_bf16 v[116:119], v[148:151], v[198:201], v[116:119]
	v_mfma_f32_16x16x32_bf16 v[112:115], v[156:159], v[198:201], v[112:115]
	v_mfma_f32_16x16x32_bf16 v[108:111], v[148:151], v[206:209], v[108:111]
	v_mfma_f32_16x16x32_bf16 v[104:107], v[156:159], v[206:209], v[104:107]
	v_mfma_f32_16x16x32_bf16 v[100:103], v[148:151], v[214:217], v[100:103]
	v_mfma_f32_16x16x32_bf16 v[96:99], v[156:159], v[214:217], v[96:99]
	v_mfma_f32_16x16x32_bf16 v[92:95], v[160:163], v[176:179], v[92:95]
	v_mfma_f32_16x16x32_bf16 v[88:91], v[168:171], v[176:179], v[88:91]
	v_mfma_f32_16x16x32_bf16 v[84:87], v[160:163], v[194:197], v[84:87]
	v_mfma_f32_16x16x32_bf16 v[80:83], v[168:171], v[194:197], v[80:83]
	v_mfma_f32_16x16x32_bf16 v[76:79], v[160:163], v[202:205], v[76:79]
	v_mfma_f32_16x16x32_bf16 v[72:75], v[168:171], v[202:205], v[72:75]
	v_mfma_f32_16x16x32_bf16 v[68:71], v[160:163], v[210:213], v[68:71]
	v_mfma_f32_16x16x32_bf16 v[64:67], v[168:171], v[210:213], v[64:67]
	v_mfma_f32_16x16x32_bf16 v[92:95], v[164:167], v[180:183], v[92:95]
	v_mfma_f32_16x16x32_bf16 v[88:91], v[172:175], v[180:183], v[88:91]
	v_mfma_f32_16x16x32_bf16 v[84:87], v[164:167], v[198:201], v[84:87]
	v_mfma_f32_16x16x32_bf16 v[80:83], v[172:175], v[198:201], v[80:83]
	v_mfma_f32_16x16x32_bf16 v[76:79], v[164:167], v[206:209], v[76:79]
	v_mfma_f32_16x16x32_bf16 v[72:75], v[172:175], v[206:209], v[72:75]
	v_mfma_f32_16x16x32_bf16 v[68:71], v[164:167], v[214:217], v[68:71]
	v_mfma_f32_16x16x32_bf16 v[64:67], v[172:175], v[214:217], v[64:67]
	s_setprio 0
	s_barrier
	s_add_i32 s12, s40, s46
	s_add_i32 s13, s47, s16
	v_add_u32_e32 v132, s12, v134
	s_mov_b32 m0, s13
	ds_read_b128 v[176:179], v143 offset:16384
	ds_read_b128 v[180:183], v143 offset:17408
	ds_read_b128 v[194:197], v143 offset:18432
	ds_read_b128 v[198:201], v143 offset:19456
	ds_read_b128 v[202:205], v143 offset:20480
	ds_read_b128 v[206:209], v143 offset:21504
	ds_read_b128 v[210:213], v143 offset:22528
	ds_read_b128 v[214:217], v143 offset:23552
	global_load_lds_dwordx4 v132, s[82:83]
	v_add_u32_e32 v132, s12, v135
	s_add_i32 s12, s46, 0x20000
	s_add_i32 m0, s13, 0x2000
	s_add_i32 s13, s12, s40
	s_add_i32 s47, s48, s16
	global_load_lds_dwordx4 v132, s[82:83]
	v_add_u32_e32 v132, s13, v134
	s_mov_b32 m0, s47
	s_nop 0
	global_load_lds_dwordx4 v132, s[82:83]
	v_add_u32_e32 v132, s13, v135
	s_add_i32 m0, s47, 0x2000
	s_nop 0
	global_load_lds_dwordx4 v132, s[82:83]
	v_add_u32_e32 v132, s40, v141
	s_mov_b32 m0, s17
	s_nop 0
	global_load_lds_dwordx4 v132, s[82:83]
	v_add_u32_e32 v132, s40, v142
	s_mov_b32 m0, s18
	s_nop 0
	global_load_lds_dwordx4 v132, s[82:83]
	s_waitcnt vmcnt(8)
	s_waitcnt lgkmcnt(0)
	s_barrier
; #define G_STAGE_A(bufoff, p0, p1, koff) do { \
;         __builtin_amdgcn_global_load_lds((const unsigned*)(gbase + (size_t)(unsigned)((p0) + (koff) + voffA[0])), (LAS unsigned*)(lds + (bufoff) + ldsw), 16, 0, 0); \
;         __builtin_amdgcn_global_load_lds((const unsigned*)(gbase + (size_t)(unsigned)((p1) + (koff) + voffA[1])), (LAS unsigned*)(lds + (bufoff) + ldsw + 8192), 16, 0, 0); } while (0)
; #define G_STAGE_B(bufoff, p, koff) do { \
;         __builtin_amdgcn_global_load_lds((const unsigned*)(gbase + (size_t)(unsigned)((p) + (koff) + voffB[0])), (LAS unsigned*)(lds + (bufoff) + ldsw), 16, 0, 0); \
;         __builtin_amdgcn_global_load_lds((const unsigned*)(gbase + (size_t)(unsigned)((p) + (koff) + voffB[1])), (LAS unsigned*)(lds + (bufoff) + ldsw + 8192), 16, 0, 0); } while (0)
; #define G_LDA(dst, b, h) do { _Pragma("unroll") for (int m = 0; m < 4; ++m) _Pragma("unroll") for (int k = 0; k < 2; ++k) dst[m][k] = *(const LAS bf16x8*)(lds + G_SA(b, h) + aoff + m * 2048 + k * 1024); } while (0)
; #define G_LDB(dst, b, h) do { _Pragma("unroll") for (int n = 0; n < 2; ++n) _Pragma("unroll") for (int k = 0; k < 2; ++k) dst[n][k] = *(const LAS bf16x8*)(lds + G_SB(b, h) + boff + n * 2048 + k * 1024); } while (0)
; #define G_WAIT_V(n) asm volatile("s_waitcnt vmcnt(" #n ")" ::: "memory")
; #define G_BAR __builtin_amdgcn_s_barrier()
; template <class Epi>
; DI void gemm_phase(LAS unsigned char* lds, const Sched& S, const Epi& E, const int K) {
;     ...
;             G_LDB(B0, 0, 0); G_LDB(B1, 0, 1); G_SCHED; G_LDA(At, 0, 0); G_STAGE_A(G_SA(1, 1), cur.a2, cur.a3, k1);
;             G_WAIT_V(8); G_WAIT_L(0); G_BAR; G_MMA(0, 0, At, B0); G_MMA(0, 1, At, B1); G_BAR; G_SCHED;
;             G_LDA(At, 0, 1); G_STAGE_B(G_SB(0, 0), xb, kb2); G_STAGE_B(G_SB(0, 1), xb + hstepB, kb2); G_STAGE_A(G_SA(0, 0), x0, x1, k2);
;             G_WAIT_V(8); G_WAIT_L(0); G_BAR; G_MMA(1, 0, At, B0); G_MMA(1, 1, At, B1); G_BAR; G_SCHED;
;             G_LDB(B0, 1, 0); G_LDB(B1, 1, 1); G_SCHED; G_LDA(At, 1, 0); G_STAGE_A(G_SA(0, 1), x2, x3, k2);
;             G_WAIT_V(8); G_WAIT_L(0); G_BAR; G_MMA(0, 0, At, B0); G_MMA(0, 1, At, B1); G_BAR; G_SCHED;
;             G_LDA(At, 1, 1); G_STAGE_B(G_SB(1, 0), xb, kb3); G_STAGE_B(G_SB(1, 1), xb + hstepB, kb3); G_STAGE_A(G_SA(1, 0), x0, x1, k3);
;             G_WAIT_V(8); G_WAIT_L(0); G_BAR; G_MMA(1, 0, At, B0); G_MMA(1, 1, At, B1); G_BAR; G_SCHED;
	s_setprio 1
	v_mfma_f32_16x16x32_bf16 v[60:63], v[144:147], v[176:179], v[60:63]
	v_mfma_f32_16x16x32_bf16 v[56:59], v[152:155], v[176:179], v[56:59]
	v_mfma_f32_16x16x32_bf16 v[52:55], v[144:147], v[194:197], v[52:55]
	v_mfma_f32_16x16x32_bf16 v[48:51], v[152:155], v[194:197], v[48:51]
	v_mfma_f32_16x16x32_bf16 v[44:47], v[144:147], v[202:205], v[44:47]
	v_mfma_f32_16x16x32_bf16 v[40:43], v[152:155], v[202:205], v[40:43]
	v_mfma_f32_16x16x32_bf16 v[36:39], v[144:147], v[210:213], v[36:39]
	v_mfma_f32_16x16x32_bf16 v[32:35], v[152:155], v[210:213], v[32:35]
	v_mfma_f32_16x16x32_bf16 v[60:63], v[148:151], v[180:183], v[60:63]
	v_mfma_f32_16x16x32_bf16 v[56:59], v[156:159], v[180:183], v[56:59]
	v_mfma_f32_16x16x32_bf16 v[52:55], v[148:151], v[198:201], v[52:55]
	v_mfma_f32_16x16x32_bf16 v[48:51], v[156:159], v[198:201], v[48:51]
	v_mfma_f32_16x16x32_bf16 v[44:47], v[148:151], v[206:209], v[44:47]
	v_mfma_f32_16x16x32_bf16 v[40:43], v[156:159], v[206:209], v[40:43]
	v_mfma_f32_16x16x32_bf16 v[36:39], v[148:151], v[214:217], v[36:39]
	v_mfma_f32_16x16x32_bf16 v[32:35], v[156:159], v[214:217], v[32:35]
	v_mfma_f32_16x16x32_bf16 v[28:31], v[160:163], v[176:179], v[28:31]
	v_mfma_f32_16x16x32_bf16 v[24:27], v[168:171], v[176:179], v[24:27]
	v_mfma_f32_16x16x32_bf16 v[20:23], v[160:163], v[194:197], v[20:23]
	v_mfma_f32_16x16x32_bf16 v[16:19], v[168:171], v[194:197], v[16:19]
	v_mfma_f32_16x16x32_bf16 v[12:15], v[160:163], v[202:205], v[12:15]
	v_mfma_f32_16x16x32_bf16 v[8:11], v[168:171], v[202:205], v[8:11]
	v_mfma_f32_16x16x32_bf16 v[4:7], v[160:163], v[210:213], v[4:7]
	v_mfma_f32_16x16x32_bf16 v[0:3], v[168:171], v[210:213], v[0:3]
	v_mfma_f32_16x16x32_bf16 v[28:31], v[164:167], v[180:183], v[28:31]
	v_mfma_f32_16x16x32_bf16 v[24:27], v[172:175], v[180:183], v[24:27]
	v_mfma_f32_16x16x32_bf16 v[20:23], v[164:167], v[198:201], v[20:23]
	v_mfma_f32_16x16x32_bf16 v[16:19], v[172:175], v[198:201], v[16:19]
	v_mfma_f32_16x16x32_bf16 v[12:15], v[164:167], v[206:209], v[12:15]
	v_mfma_f32_16x16x32_bf16 v[8:11], v[172:175], v[206:209], v[8:11]
	v_mfma_f32_16x16x32_bf16 v[4:7], v[164:167], v[214:217], v[4:7]
	v_mfma_f32_16x16x32_bf16 v[0:3], v[172:175], v[214:217], v[0:3]
	s_setprio 0
	s_barrier
	s_add_i32 s13, 0, 0x18000
	v_add_u32_e32 v132, s13, v136
	s_add_i32 s47, 0, 0x1c000
	ds_read_b128 v[144:147], v132
	ds_read_b128 v[148:151], v132 offset:1024
	ds_read_b128 v[152:155], v132 offset:2048
	ds_read_b128 v[156:159], v132 offset:3072
	v_add_u32_e32 v132, s47, v136
	ds_read_b128 v[160:163], v132
	ds_read_b128 v[164:167], v132 offset:1024
	ds_read_b128 v[168:171], v132 offset:2048
	ds_read_b128 v[172:175], v132 offset:3072
	s_mov_b32 m0, s19
	v_add_u32_e32 v132, s40, v139
	ds_read_b128 v[176:179], v143 offset:32768
	ds_read_b128 v[180:183], v143 offset:33792
	ds_read_b128 v[194:197], v143 offset:34816
	ds_read_b128 v[198:201], v143 offset:35840
	ds_read_b128 v[202:205], v143 offset:36864
	ds_read_b128 v[206:209], v143 offset:37888
	ds_read_b128 v[210:213], v143 offset:38912
	ds_read_b128 v[214:217], v143 offset:39936
	global_load_lds_dwordx4 v132, s[82:83]
	v_add_u32_e32 v132, s40, v140
	s_mov_b32 m0, s20
	s_nop 0
	global_load_lds_dwordx4 v132, s[82:83]
	s_waitcnt vmcnt(8)
	s_waitcnt lgkmcnt(0)
	s_barrier
	s_setprio 1
	v_mfma_f32_16x16x32_bf16 v[124:127], v[144:147], v[176:179], v[124:127]
	v_mfma_f32_16x16x32_bf16 v[120:123], v[152:155], v[176:179], v[120:123]
	v_mfma_f32_16x16x32_bf16 v[116:119], v[144:147], v[194:197], v[116:119]
	v_mfma_f32_16x16x32_bf16 v[112:115], v[152:155], v[194:197], v[112:115]
	v_mfma_f32_16x16x32_bf16 v[108:111], v[144:147], v[202:205], v[108:111]
	v_mfma_f32_16x16x32_bf16 v[104:107], v[152:155], v[202:205], v[104:107]
	v_mfma_f32_16x16x32_bf16 v[100:103], v[144:147], v[210:213], v[100:103]
	v_mfma_f32_16x16x32_bf16 v[96:99], v[152:155], v[210:213], v[96:99]
	v_mfma_f32_16x16x32_bf16 v[124:127], v[148:151], v[180:183], v[124:127]
	v_mfma_f32_16x16x32_bf16 v[120:123], v[156:159], v[180:183], v[120:123]
	v_mfma_f32_16x16x32_bf16 v[116:119], v[148:151], v[198:201], v[116:119]
	v_mfma_f32_16x16x32_bf16 v[112:115], v[156:159], v[198:201], v[112:115]
	v_mfma_f32_16x16x32_bf16 v[108:111], v[148:151], v[206:209], v[108:111]
	v_mfma_f32_16x16x32_bf16 v[104:107], v[156:159], v[206:209], v[104:107]
	v_mfma_f32_16x16x32_bf16 v[100:103], v[148:151], v[214:217], v[100:103]
	v_mfma_f32_16x16x32_bf16 v[96:99], v[156:159], v[214:217], v[96:99]
	v_mfma_f32_16x16x32_bf16 v[92:95], v[160:163], v[176:179], v[92:95]
	v_mfma_f32_16x16x32_bf16 v[88:91], v[168:171], v[176:179], v[88:91]
	v_mfma_f32_16x16x32_bf16 v[84:87], v[160:163], v[194:197], v[84:87]
	v_mfma_f32_16x16x32_bf16 v[80:83], v[168:171], v[194:197], v[80:83]
	v_mfma_f32_16x16x32_bf16 v[76:79], v[160:163], v[202:205], v[76:79]
	v_mfma_f32_16x16x32_bf16 v[72:75], v[168:171], v[202:205], v[72:75]
	v_mfma_f32_16x16x32_bf16 v[68:71], v[160:163], v[210:213], v[68:71]
	v_mfma_f32_16x16x32_bf16 v[64:67], v[168:171], v[210:213], v[64:67]
	v_mfma_f32_16x16x32_bf16 v[92:95], v[164:167], v[180:183], v[92:95]
	v_mfma_f32_16x16x32_bf16 v[88:91], v[172:175], v[180:183], v[88:91]
	v_mfma_f32_16x16x32_bf16 v[84:87], v[164:167], v[198:201], v[84:87]
	v_mfma_f32_16x16x32_bf16 v[80:83], v[172:175], v[198:201], v[80:83]
	v_mfma_f32_16x16x32_bf16 v[76:79], v[164:167], v[206:209], v[76:79]
	v_mfma_f32_16x16x32_bf16 v[72:75], v[172:175], v[206:209], v[72:75]
	v_mfma_f32_16x16x32_bf16 v[68:71], v[164:167], v[214:217], v[68:71]
	v_mfma_f32_16x16x32_bf16 v[64:67], v[172:175], v[214:217], v[64:67]
	s_setprio 0
	s_barrier
; #define G_STAGE_A(bufoff, p0, p1, koff) do { \
;         __builtin_amdgcn_global_load_lds((const unsigned*)(gbase + (size_t)(unsigned)((p0) + (koff) + voffA[0])), (LAS unsigned*)(lds + (bufoff) + ldsw), 16, 0, 0); \
;         __builtin_amdgcn_global_load_lds((const unsigned*)(gbase + (size_t)(unsigned)((p1) + (koff) + voffA[1])), (LAS unsigned*)(lds + (bufoff) + ldsw + 8192), 16, 0, 0); } while (0)
; #define G_STAGE_B(bufoff, p, koff) do { \
;         __builtin_amdgcn_global_load_lds((const unsigned*)(gbase + (size_t)(unsigned)((p) + (koff) + voffB[0])), (LAS unsigned*)(lds + (bufoff) + ldsw), 16, 0, 0); \
;         __builtin_amdgcn_global_load_lds((const unsigned*)(gbase + (size_t)(unsigned)((p) + (koff) + voffB[1])), (LAS unsigned*)(lds + (bufoff) + ldsw + 8192), 16, 0, 0); } while (0)
; #define G_LDA(dst, b, h) do { _Pragma("unroll") for (int m = 0; m < 4; ++m) _Pragma("unroll") for (int k = 0; k < 2; ++k) dst[m][k] = *(const LAS bf16x8*)(lds + G_SA(b, h) + aoff + m * 2048 + k * 1024); } while (0)
; #define G_LDB(dst, b, h) do { _Pragma("unroll") for (int n = 0; n < 2; ++n) _Pragma("unroll") for (int k = 0; k < 2; ++k) dst[n][k] = *(const LAS bf16x8*)(lds + G_SB(b, h) + boff + n * 2048 + k * 1024); } while (0)
; #define G_MMA(ai, bj, At, Bt) do { __builtin_amdgcn_s_setprio(1); _Pragma("unroll") for (int m = 0; m < 4; ++m) _Pragma("unroll") for (int n = 0; n < 2; ++n) _Pragma("unroll") for (int k = 0; k < 2; ++k) \
;         acc[ai][bj][m][n] = __builtin_amdgcn_mfma_f32_16x16x32_bf16(Bt[n][k], At[m][k], acc[ai][bj][m][n], 0, 0, 0); __builtin_amdgcn_s_setprio(0); } while (0)
; #define G_WAIT_V(n) asm volatile("s_waitcnt vmcnt(" #n ")" ::: "memory")
; #define G_WAIT_L(n) asm volatile("s_waitcnt lgkmcnt(" #n ")" ::: "memory")
; #define G_BAR __builtin_amdgcn_s_barrier()
; template <class Epi>
; DI void gemm_phase(LAS unsigned char* lds, const Sched& S, const Epi& E, const int K) {
;     ...
;             G_LDB(B0, 1, 0); G_LDB(B1, 1, 1); G_SCHED; G_LDA(At, 1, 0); G_STAGE_A(G_SA(0, 1), x2, x3, k2);
;             G_WAIT_V(8); G_WAIT_L(0); G_BAR; G_MMA(0, 0, At, B0); G_MMA(0, 1, At, B1); G_BAR; G_SCHED;
;             G_LDA(At, 1, 1); G_STAGE_B(G_SB(1, 0), xb, kb3); G_STAGE_B(G_SB(1, 1), xb + hstepB, kb3); G_STAGE_A(G_SA(1, 0), x0, x1, k3);
;             G_WAIT_V(8); G_WAIT_L(0); G_BAR; G_MMA(1, 0, At, B0); G_MMA(1, 1, At, B1); G_BAR; G_SCHED;
	s_add_i32 s40, s45, s46
	s_add_i32 s13, s13, s16
	v_add_u32_e32 v132, s40, v134
	s_mov_b32 m0, s13
	ds_read_b128 v[176:179], v143 offset:49152
	ds_read_b128 v[180:183], v143 offset:50176
	ds_read_b128 v[194:197], v143 offset:51200
	ds_read_b128 v[198:201], v143 offset:52224
	ds_read_b128 v[202:205], v143 offset:53248
	ds_read_b128 v[206:209], v143 offset:54272
	ds_read_b128 v[210:213], v143 offset:55296
	ds_read_b128 v[214:217], v143 offset:56320
	global_load_lds_dwordx4 v132, s[82:83]
	v_add_u32_e32 v132, s40, v135
	s_add_i32 m0, s13, 0x2000
	s_add_i32 s12, s45, s12
	s_add_i32 s13, s47, s16
	global_load_lds_dwordx4 v132, s[82:83]
	v_add_u32_e32 v132, s12, v134
	s_mov_b32 m0, s13
	s_nop 0
	global_load_lds_dwordx4 v132, s[82:83]
	v_add_u32_e32 v132, s12, v135
	s_add_i32 m0, s13, 0x2000
	s_nop 0
	global_load_lds_dwordx4 v132, s[82:83]
	v_add_u32_e32 v132, s45, v141
	s_mov_b32 m0, s21
	s_nop 0
	global_load_lds_dwordx4 v132, s[82:83]
	v_add_u32_e32 v132, s45, v142
	s_mov_b32 m0, s24
	s_nop 0
	global_load_lds_dwordx4 v132, s[82:83]
	s_waitcnt vmcnt(8)
	s_waitcnt lgkmcnt(0)
	s_barrier
	s_setprio 1
	v_mfma_f32_16x16x32_bf16 v[60:63], v[144:147], v[176:179], v[60:63]
	v_mfma_f32_16x16x32_bf16 v[56:59], v[152:155], v[176:179], v[56:59]
	v_mfma_f32_16x16x32_bf16 v[52:55], v[144:147], v[194:197], v[52:55]
	v_mfma_f32_16x16x32_bf16 v[48:51], v[152:155], v[194:197], v[48:51]
	v_mfma_f32_16x16x32_bf16 v[44:47], v[144:147], v[202:205], v[44:47]
	v_mfma_f32_16x16x32_bf16 v[40:43], v[152:155], v[202:205], v[40:43]
	v_mfma_f32_16x16x32_bf16 v[36:39], v[144:147], v[210:213], v[36:39]
	v_mfma_f32_16x16x32_bf16 v[32:35], v[152:155], v[210:213], v[32:35]
	v_mfma_f32_16x16x32_bf16 v[60:63], v[148:151], v[180:183], v[60:63]
	v_mfma_f32_16x16x32_bf16 v[56:59], v[156:159], v[180:183], v[56:59]
	v_mfma_f32_16x16x32_bf16 v[52:55], v[148:151], v[198:201], v[52:55]
	v_mfma_f32_16x16x32_bf16 v[48:51], v[156:159], v[198:201], v[48:51]
	v_mfma_f32_16x16x32_bf16 v[44:47], v[148:151], v[206:209], v[44:47]
	v_mfma_f32_16x16x32_bf16 v[40:43], v[156:159], v[206:209], v[40:43]
	v_mfma_f32_16x16x32_bf16 v[36:39], v[148:151], v[214:217], v[36:39]
	v_mfma_f32_16x16x32_bf16 v[32:35], v[156:159], v[214:217], v[32:35]
	v_mfma_f32_16x16x32_bf16 v[28:31], v[160:163], v[176:179], v[28:31]
	v_mfma_f32_16x16x32_bf16 v[24:27], v[168:171], v[176:179], v[24:27]
	v_mfma_f32_16x16x32_bf16 v[20:23], v[160:163], v[194:197], v[20:23]
	v_mfma_f32_16x16x32_bf16 v[16:19], v[168:171], v[194:197], v[16:19]
	v_mfma_f32_16x16x32_bf16 v[12:15], v[160:163], v[202:205], v[12:15]
	v_mfma_f32_16x16x32_bf16 v[8:11], v[168:171], v[202:205], v[8:11]
	v_mfma_f32_16x16x32_bf16 v[4:7], v[160:163], v[210:213], v[4:7]
	v_mfma_f32_16x16x32_bf16 v[0:3], v[168:171], v[210:213], v[0:3]
	v_mfma_f32_16x16x32_bf16 v[28:31], v[164:167], v[180:183], v[28:31]
	v_mfma_f32_16x16x32_bf16 v[24:27], v[172:175], v[180:183], v[24:27]
	v_mfma_f32_16x16x32_bf16 v[20:23], v[164:167], v[198:201], v[20:23]
	v_mfma_f32_16x16x32_bf16 v[16:19], v[172:175], v[198:201], v[16:19]
	v_mfma_f32_16x16x32_bf16 v[12:15], v[164:167], v[206:209], v[12:15]
	v_mfma_f32_16x16x32_bf16 v[8:11], v[172:175], v[206:209], v[8:11]
	v_mfma_f32_16x16x32_bf16 v[4:7], v[164:167], v[214:217], v[4:7]
	v_mfma_f32_16x16x32_bf16 v[0:3], v[172:175], v[214:217], v[0:3]
	s_setprio 0
	s_barrier
	s_add_i32 s44, s44, 2
	s_cmp_gt_u32 s44, 5
	s_mov_b64 s[12:13], s[14:15]
	s_cbranch_scc0 .LBB0_281
	s_and_b64 vcc, exec, s[6:7]
	s_cbranch_vccz .LBB0_284
	s_barrier

; #define G_STAGE_A(bufoff, p0, p1, koff) do { \
;         __builtin_amdgcn_global_load_lds((const unsigned*)(gbase + (size_t)(unsigned)((p0) + (koff) + voffA[0])), (LAS unsigned*)(lds + (bufoff) + ldsw), 16, 0, 0); \
;         __builtin_amdgcn_global_load_lds((const unsigned*)(gbase + (size_t)(unsigned)((p1) + (koff) + voffA[1])), (LAS unsigned*)(lds + (bufoff) + ldsw + 8192), 16, 0, 0); } while (0)
; #define G_STAGE_B(bufoff, p, koff) do { \
;         __builtin_amdgcn_global_load_lds((const unsigned*)(gbase + (size_t)(unsigned)((p) + (koff) + voffB[0])), (LAS unsigned*)(lds + (bufoff) + ldsw), 16, 0, 0); \
;         __builtin_amdgcn_global_load_lds((const unsigned*)(gbase + (size_t)(unsigned)((p) + (koff) + voffB[1])), (LAS unsigned*)(lds + (bufoff) + ldsw + 8192), 16, 0, 0); } while (0)
; template <class Epi>
; DI void gemm_phase(LAS unsigned char* lds, const Sched& S, const Epi& E, const int K) {
;     ...
;         for (int t = 0; t < nt; t += 2) {
;             const bool last = (t == nt - 2);
;             const unsigned k1 = (unsigned)(t + 1) * kstepA;
;             const unsigned k2 = last ? 0u : (unsigned)(t + 2) * kstepA, k3 = k2 + kstepA;
;             const unsigned kb2 = last ? 0u : (unsigned)(t + 2) * kstepB, kb3 = kb2 + kstepB;
;             const unsigned x0 = last ? n0 : cur.a0, x1 = last ? n1 : cur.a1, x2 = last ? n2 : cur.a2, x3 = last ? n3 : cur.a3;
;             const unsigned xb = last ? nB : cur.b;
;     ...
;             G_LDB(B0, 0, 0); G_LDB(B1, 0, 1); G_SCHED; G_LDA(At, 0, 0); G_STAGE_A(G_SA(1, 1), cur.a2, cur.a3, k1);
;             G_WAIT_V(8); G_WAIT_L(0); G_BAR; G_MMA(0, 0, At, B0); G_MMA(0, 1, At, B1); G_BAR; G_SCHED;
;             G_LDA(At, 0, 1); G_STAGE_B(G_SB(0, 0), xb, kb2); G_STAGE_B(G_SB(0, 1), xb + hstepB, kb2); G_STAGE_A(G_SA(0, 0), x0, x1, k2);
;             G_WAIT_V(8); G_WAIT_L(0); G_BAR; G_MMA(1, 0, At, B0); G_MMA(1, 1, At, B1); G_BAR; G_SCHED;
;             G_LDB(B0, 1, 0); G_LDB(B1, 1, 1); G_SCHED; G_LDA(At, 1, 0); G_STAGE_A(G_SA(0, 1), x2, x3, k2);
;             G_WAIT_V(8); G_WAIT_L(0); G_BAR; G_MMA(0, 0, At, B0); G_MMA(0, 1, At, B1); G_BAR; G_SCHED;
;             G_LDA(At, 1, 1); G_STAGE_B(G_SB(1, 0), xb, kb3); G_STAGE_B(G_SB(1, 1), xb + hstepB, kb3); G_STAGE_A(G_SA(1, 0), x0, x1, k3);
;             G_WAIT_V(8); G_WAIT_L(0); G_BAR; G_MMA(1, 0, At, B0); G_MMA(1, 1, At, B1); G_BAR; G_SCHED;
.LBB0_318:
	s_add_i32 s40, s86, 0x80
	v_add_u32_e32 v222, s80, v128
	v_add_u32_e32 v224, s40, v129
	v_add_u32_e32 v225, s40, v131
	s_add_i32 s40, 0, 0x10000
	s_add_i32 s80, 0, 0x14000
	v_add_u32_e32 v154, s40, v133
	v_add_u32_e32 v170, s80, v133
	ds_read_b128 v[142:145], v154
	ds_read_b128 v[146:149], v154 offset:1024
	ds_read_b128 v[150:153], v154 offset:2048
	ds_read_b128 v[154:157], v154 offset:3072
	ds_read_b128 v[158:161], v170
	ds_read_b128 v[162:165], v170 offset:1024
	ds_read_b128 v[166:169], v170 offset:2048
	ds_read_b128 v[170:173], v170 offset:3072
	s_add_i32 s36, s86, s44
	v_add_u32_e32 v218, s36, v129
	v_add_u32_e32 v219, s36, v131
	s_addk_i32 s36, 0x80
	v_add_u32_e32 v141, s50, v134
	v_add_u32_e32 v182, s47, v139
	v_add_u32_e32 v183, s86, v129
	v_add_u32_e32 v184, s86, v131
	v_add_u32_e32 v220, s37, v128
	v_add_u32_e32 v221, s79, v130
	v_add_u32_e32 v223, s81, v130
	v_add_u32_e32 v226, s36, v129
	v_add_u32_e32 v229, s36, v131
	v_add_u32_e32 v233, s37, v134
	v_add_u32_e32 v234, s79, v139
	s_add_i32 m0, s46, 0xc000
	ds_read_b128 v[174:177], v140
	ds_read_b128 v[178:181], v140 offset:1024
	ds_read_b128 v[194:197], v140 offset:2048
	ds_read_b128 v[198:201], v140 offset:3072
	ds_read_b128 v[202:205], v140 offset:4096
	ds_read_b128 v[206:209], v140 offset:5120
	ds_read_b128 v[210:213], v140 offset:6144
	ds_read_b128 v[214:217], v140 offset:7168
	global_load_lds_dwordx4 v141, s[82:83]
	s_add_i32 m0, s46, 0xe000
	s_nop 0
	global_load_lds_dwordx4 v182, s[82:83]
	s_waitcnt vmcnt(8)
	s_waitcnt lgkmcnt(0)
	s_barrier
	s_setprio 1
	v_mfma_f32_16x16x32_bf16 v[124:127], v[142:145], v[174:177], v[124:127]
	v_mfma_f32_16x16x32_bf16 v[120:123], v[150:153], v[174:177], v[120:123]
	v_mfma_f32_16x16x32_bf16 v[116:119], v[142:145], v[194:197], v[116:119]
	v_mfma_f32_16x16x32_bf16 v[112:115], v[150:153], v[194:197], v[112:115]
	v_mfma_f32_16x16x32_bf16 v[108:111], v[142:145], v[202:205], v[108:111]
	v_mfma_f32_16x16x32_bf16 v[104:107], v[150:153], v[202:205], v[104:107]
	v_mfma_f32_16x16x32_bf16 v[100:103], v[142:145], v[210:213], v[100:103]
	v_mfma_f32_16x16x32_bf16 v[96:99], v[150:153], v[210:213], v[96:99]
	v_mfma_f32_16x16x32_bf16 v[124:127], v[146:149], v[178:181], v[124:127]
	v_mfma_f32_16x16x32_bf16 v[120:123], v[154:157], v[178:181], v[120:123]
	v_mfma_f32_16x16x32_bf16 v[116:119], v[146:149], v[198:201], v[116:119]
	v_mfma_f32_16x16x32_bf16 v[112:115], v[154:157], v[198:201], v[112:115]
	v_mfma_f32_16x16x32_bf16 v[108:111], v[146:149], v[206:209], v[108:111]
	v_mfma_f32_16x16x32_bf16 v[104:107], v[154:157], v[206:209], v[104:107]
	v_mfma_f32_16x16x32_bf16 v[100:103], v[146:149], v[214:217], v[100:103]
	v_mfma_f32_16x16x32_bf16 v[96:99], v[154:157], v[214:217], v[96:99]
	v_mfma_f32_16x16x32_bf16 v[92:95], v[158:161], v[174:177], v[92:95]
	v_mfma_f32_16x16x32_bf16 v[88:91], v[166:169], v[174:177], v[88:91]
	v_mfma_f32_16x16x32_bf16 v[84:87], v[158:161], v[194:197], v[84:87]
	v_mfma_f32_16x16x32_bf16 v[80:83], v[166:169], v[194:197], v[80:83]
	v_mfma_f32_16x16x32_bf16 v[76:79], v[158:161], v[202:205], v[76:79]
	v_mfma_f32_16x16x32_bf16 v[72:75], v[166:169], v[202:205], v[72:75]
	v_mfma_f32_16x16x32_bf16 v[68:71], v[158:161], v[210:213], v[68:71]
	v_mfma_f32_16x16x32_bf16 v[64:67], v[166:169], v[210:213], v[64:67]
	v_mfma_f32_16x16x32_bf16 v[92:95], v[162:165], v[178:181], v[92:95]
	v_mfma_f32_16x16x32_bf16 v[88:91], v[170:173], v[178:181], v[88:91]
	v_mfma_f32_16x16x32_bf16 v[84:87], v[162:165], v[198:201], v[84:87]
	v_mfma_f32_16x16x32_bf16 v[80:83], v[170:173], v[198:201], v[80:83]
	v_mfma_f32_16x16x32_bf16 v[76:79], v[162:165], v[206:209], v[76:79]
	v_mfma_f32_16x16x32_bf16 v[72:75], v[170:173], v[206:209], v[72:75]
	v_mfma_f32_16x16x32_bf16 v[68:71], v[162:165], v[214:217], v[68:71]
	v_mfma_f32_16x16x32_bf16 v[64:67], v[170:173], v[214:217], v[64:67]
	s_setprio 0
	s_barrier
	s_add_i32 s36, s40, s45
	s_mov_b32 m0, s36
	ds_read_b128 v[174:177], v140 offset:16384
	ds_read_b128 v[178:181], v140 offset:17408
	ds_read_b128 v[194:197], v140 offset:18432
	ds_read_b128 v[198:201], v140 offset:19456
	ds_read_b128 v[202:205], v140 offset:20480
	ds_read_b128 v[206:209], v140 offset:21504
	ds_read_b128 v[210:213], v140 offset:22528
	ds_read_b128 v[214:217], v140 offset:23552
	global_load_lds_dwordx4 v183, s[82:83]
	s_add_i32 m0, s36, 0x2000
	s_add_i32 s36, s80, s45
	global_load_lds_dwordx4 v184, s[82:83]
	s_mov_b32 m0, s36
	s_nop 0
	global_load_lds_dwordx4 v218, s[82:83]
	s_add_i32 m0, s36, 0x2000
	s_nop 0
	global_load_lds_dwordx4 v219, s[82:83]
	s_mov_b32 m0, s46
	s_nop 0
	global_load_lds_dwordx4 v220, s[82:83]
	s_mov_b32 m0, s56
	s_nop 0
	global_load_lds_dwordx4 v221, s[82:83]
	s_waitcnt vmcnt(8)
	s_waitcnt lgkmcnt(0)
	s_barrier
; #define G_STAGE_A(bufoff, p0, p1, koff) do { \
;         __builtin_amdgcn_global_load_lds((const unsigned*)(gbase + (size_t)(unsigned)((p0) + (koff) + voffA[0])), (LAS unsigned*)(lds + (bufoff) + ldsw), 16, 0, 0); \
;         __builtin_amdgcn_global_load_lds((const unsigned*)(gbase + (size_t)(unsigned)((p1) + (koff) + voffA[1])), (LAS unsigned*)(lds + (bufoff) + ldsw + 8192), 16, 0, 0); } while (0)
; #define G_STAGE_B(bufoff, p, koff) do { \
;         __builtin_amdgcn_global_load_lds((const unsigned*)(gbase + (size_t)(unsigned)((p) + (koff) + voffB[0])), (LAS unsigned*)(lds + (bufoff) + ldsw), 16, 0, 0); \
;         __builtin_amdgcn_global_load_lds((const unsigned*)(gbase + (size_t)(unsigned)((p) + (koff) + voffB[1])), (LAS unsigned*)(lds + (bufoff) + ldsw + 8192), 16, 0, 0); } while (0)
; #define G_LDA(dst, b, h) do { _Pragma("unroll") for (int m = 0; m < 4; ++m) _Pragma("unroll") for (int k = 0; k < 2; ++k) dst[m][k] = *(const LAS bf16x8*)(lds + G_SA(b, h) + aoff + m * 2048 + k * 1024); } while (0)
; #define G_LDB(dst, b, h) do { _Pragma("unroll") for (int n = 0; n < 2; ++n) _Pragma("unroll") for (int k = 0; k < 2; ++k) dst[n][k] = *(const LAS bf16x8*)(lds + G_SB(b, h) + boff + n * 2048 + k * 1024); } while (0)
; #define G_MMA(ai, bj, At, Bt) do { __builtin_amdgcn_s_setprio(1); _Pragma("unroll") for (int m = 0; m < 4; ++m) _Pragma("unroll") for (int n = 0; n < 2; ++n) _Pragma("unroll") for (int k = 0; k < 2; ++k) \
;         acc[ai][bj][m][n] = __builtin_amdgcn_mfma_f32_16x16x32_bf16(Bt[n][k], At[m][k], acc[ai][bj][m][n], 0, 0, 0); __builtin_amdgcn_s_setprio(0); } while (0)
; template <class Epi>
; DI void gemm_phase(LAS unsigned char* lds, const Sched& S, const Epi& E, const int K) {
;     ...
;             G_LDB(B0, 0, 0); G_LDB(B1, 0, 1); G_SCHED; G_LDA(At, 0, 0); G_STAGE_A(G_SA(1, 1), cur.a2, cur.a3, k1);
;             G_WAIT_V(8); G_WAIT_L(0); G_BAR; G_MMA(0, 0, At, B0); G_MMA(0, 1, At, B1); G_BAR; G_SCHED;
;             G_LDA(At, 0, 1); G_STAGE_B(G_SB(0, 0), xb, kb2); G_STAGE_B(G_SB(0, 1), xb + hstepB, kb2); G_STAGE_A(G_SA(0, 0), x0, x1, k2);
;             G_WAIT_V(8); G_WAIT_L(0); G_BAR; G_MMA(1, 0, At, B0); G_MMA(1, 1, At, B1); G_BAR; G_SCHED;
;             G_LDB(B0, 1, 0); G_LDB(B1, 1, 1); G_SCHED; G_LDA(At, 1, 0); G_STAGE_A(G_SA(0, 1), x2, x3, k2);
;             G_WAIT_V(8); G_WAIT_L(0); G_BAR; G_MMA(0, 0, At, B0); G_MMA(0, 1, At, B1); G_BAR; G_SCHED;
	s_setprio 1
	v_mfma_f32_16x16x32_bf16 v[60:63], v[142:145], v[174:177], v[60:63]
	v_mfma_f32_16x16x32_bf16 v[56:59], v[150:153], v[174:177], v[56:59]
	v_mfma_f32_16x16x32_bf16 v[52:55], v[142:145], v[194:197], v[52:55]
	v_mfma_f32_16x16x32_bf16 v[48:51], v[150:153], v[194:197], v[48:51]
	v_mfma_f32_16x16x32_bf16 v[44:47], v[142:145], v[202:205], v[44:47]
	v_mfma_f32_16x16x32_bf16 v[40:43], v[150:153], v[202:205], v[40:43]
	v_mfma_f32_16x16x32_bf16 v[36:39], v[142:145], v[210:213], v[36:39]
	v_mfma_f32_16x16x32_bf16 v[32:35], v[150:153], v[210:213], v[32:35]
	v_mfma_f32_16x16x32_bf16 v[60:63], v[146:149], v[178:181], v[60:63]
	v_mfma_f32_16x16x32_bf16 v[56:59], v[154:157], v[178:181], v[56:59]
	v_mfma_f32_16x16x32_bf16 v[52:55], v[146:149], v[198:201], v[52:55]
	v_mfma_f32_16x16x32_bf16 v[48:51], v[154:157], v[198:201], v[48:51]
	v_mfma_f32_16x16x32_bf16 v[44:47], v[146:149], v[206:209], v[44:47]
	v_mfma_f32_16x16x32_bf16 v[40:43], v[154:157], v[206:209], v[40:43]
	v_mfma_f32_16x16x32_bf16 v[36:39], v[146:149], v[214:217], v[36:39]
	v_mfma_f32_16x16x32_bf16 v[32:35], v[154:157], v[214:217], v[32:35]
	v_mfma_f32_16x16x32_bf16 v[28:31], v[158:161], v[174:177], v[28:31]
	v_mfma_f32_16x16x32_bf16 v[24:27], v[166:169], v[174:177], v[24:27]
	v_mfma_f32_16x16x32_bf16 v[20:23], v[158:161], v[194:197], v[20:23]
	v_mfma_f32_16x16x32_bf16 v[16:19], v[166:169], v[194:197], v[16:19]
	v_mfma_f32_16x16x32_bf16 v[12:15], v[158:161], v[202:205], v[12:15]
	v_mfma_f32_16x16x32_bf16 v[8:11], v[166:169], v[202:205], v[8:11]
	v_mfma_f32_16x16x32_bf16 v[4:7], v[158:161], v[210:213], v[4:7]
	v_mfma_f32_16x16x32_bf16 v[0:3], v[166:169], v[210:213], v[0:3]
	v_mfma_f32_16x16x32_bf16 v[28:31], v[162:165], v[178:181], v[28:31]
	v_mfma_f32_16x16x32_bf16 v[24:27], v[170:173], v[178:181], v[24:27]
	v_mfma_f32_16x16x32_bf16 v[20:23], v[162:165], v[198:201], v[20:23]
	v_mfma_f32_16x16x32_bf16 v[16:19], v[170:173], v[198:201], v[16:19]
	v_mfma_f32_16x16x32_bf16 v[12:15], v[162:165], v[206:209], v[12:15]
	v_mfma_f32_16x16x32_bf16 v[8:11], v[170:173], v[206:209], v[8:11]
	v_mfma_f32_16x16x32_bf16 v[4:7], v[162:165], v[214:217], v[4:7]
	v_mfma_f32_16x16x32_bf16 v[0:3], v[170:173], v[214:217], v[0:3]
	s_setprio 0
	s_barrier
	s_add_i32 s36, 0, 0x18000
	v_add_u32_e32 v141, s36, v133
	s_add_i32 s37, 0, 0x1c000
	ds_read_b128 v[142:145], v141
	ds_read_b128 v[146:149], v141 offset:1024
	ds_read_b128 v[150:153], v141 offset:2048
	ds_read_b128 v[154:157], v141 offset:3072
	v_add_u32_e32 v141, s37, v133
	ds_read_b128 v[158:161], v141
	ds_read_b128 v[162:165], v141 offset:1024
	ds_read_b128 v[166:169], v141 offset:2048
	ds_read_b128 v[170:173], v141 offset:3072
	s_mov_b32 m0, s57
	ds_read_b128 v[174:177], v140 offset:32768
	ds_read_b128 v[178:181], v140 offset:33792
	ds_read_b128 v[194:197], v140 offset:34816
	ds_read_b128 v[198:201], v140 offset:35840
	ds_read_b128 v[202:205], v140 offset:36864
	ds_read_b128 v[206:209], v140 offset:37888
	ds_read_b128 v[210:213], v140 offset:38912
	ds_read_b128 v[214:217], v140 offset:39936
	global_load_lds_dwordx4 v222, s[82:83]
	s_mov_b32 m0, s58
	s_nop 0
	global_load_lds_dwordx4 v223, s[82:83]
	s_waitcnt vmcnt(8)
	s_waitcnt lgkmcnt(0)
	s_barrier
; #define G_STAGE_A(bufoff, p0, p1, koff) do { \
;         __builtin_amdgcn_global_load_lds((const unsigned*)(gbase + (size_t)(unsigned)((p0) + (koff) + voffA[0])), (LAS unsigned*)(lds + (bufoff) + ldsw), 16, 0, 0); \
;         __builtin_amdgcn_global_load_lds((const unsigned*)(gbase + (size_t)(unsigned)((p1) + (koff) + voffA[1])), (LAS unsigned*)(lds + (bufoff) + ldsw + 8192), 16, 0, 0); } while (0)
; #define G_STAGE_B(bufoff, p, koff) do { \
;         __builtin_amdgcn_global_load_lds((const unsigned*)(gbase + (size_t)(unsigned)((p) + (koff) + voffB[0])), (LAS unsigned*)(lds + (bufoff) + ldsw), 16, 0, 0); \
;         __builtin_amdgcn_global_load_lds((const unsigned*)(gbase + (size_t)(unsigned)((p) + (koff) + voffB[1])), (LAS unsigned*)(lds + (bufoff) + ldsw + 8192), 16, 0, 0); } while (0)
; #define G_LDA(dst, b, h) do { _Pragma("unroll") for (int m = 0; m < 4; ++m) _Pragma("unroll") for (int k = 0; k < 2; ++k) dst[m][k] = *(const LAS bf16x8*)(lds + G_SA(b, h) + aoff + m * 2048 + k * 1024); } while (0)
; #define G_LDB(dst, b, h) do { _Pragma("unroll") for (int n = 0; n < 2; ++n) _Pragma("unroll") for (int k = 0; k < 2; ++k) dst[n][k] = *(const LAS bf16x8*)(lds + G_SB(b, h) + boff + n * 2048 + k * 1024); } while (0)
; #define G_MMA(ai, bj, At, Bt) do { __builtin_amdgcn_s_setprio(1); _Pragma("unroll") for (int m = 0; m < 4; ++m) _Pragma("unroll") for (int n = 0; n < 2; ++n) _Pragma("unroll") for (int k = 0; k < 2; ++k) \
;         acc[ai][bj][m][n] = __builtin_amdgcn_mfma_f32_16x16x32_bf16(Bt[n][k], At[m][k], acc[ai][bj][m][n], 0, 0, 0); __builtin_amdgcn_s_setprio(0); } while (0)
; #define G_WAIT_V(n) asm volatile("s_waitcnt vmcnt(" #n ")" ::: "memory")
; #define G_WAIT_L(n) asm volatile("s_waitcnt lgkmcnt(" #n ")" ::: "memory")
; template <class Epi>
; DI void gemm_phase(LAS unsigned char* lds, const Sched& S, const Epi& E, const int K) {
;     ...
;             G_LDB(B0, 1, 0); G_LDB(B1, 1, 1); G_SCHED; G_LDA(At, 1, 0); G_STAGE_A(G_SA(0, 1), x2, x3, k2);
;             G_WAIT_V(8); G_WAIT_L(0); G_BAR; G_MMA(0, 0, At, B0); G_MMA(0, 1, At, B1); G_BAR; G_SCHED;
;             G_LDA(At, 1, 1); G_STAGE_B(G_SB(1, 0), xb, kb3); G_STAGE_B(G_SB(1, 1), xb + hstepB, kb3); G_STAGE_A(G_SA(1, 0), x0, x1, k3);
;             G_WAIT_V(8); G_WAIT_L(0); G_BAR; G_MMA(1, 0, At, B0); G_MMA(1, 1, At, B1); G_BAR; G_SCHED;
;     ...
;         if (wr == 0) G_BAR;
	s_setprio 1
	v_mfma_f32_16x16x32_bf16 v[124:127], v[142:145], v[174:177], v[124:127]
	v_mfma_f32_16x16x32_bf16 v[120:123], v[150:153], v[174:177], v[120:123]
	v_mfma_f32_16x16x32_bf16 v[116:119], v[142:145], v[194:197], v[116:119]
	v_mfma_f32_16x16x32_bf16 v[112:115], v[150:153], v[194:197], v[112:115]
	v_mfma_f32_16x16x32_bf16 v[108:111], v[142:145], v[202:205], v[108:111]
	v_mfma_f32_16x16x32_bf16 v[104:107], v[150:153], v[202:205], v[104:107]
	v_mfma_f32_16x16x32_bf16 v[100:103], v[142:145], v[210:213], v[100:103]
	v_mfma_f32_16x16x32_bf16 v[96:99], v[150:153], v[210:213], v[96:99]
	v_mfma_f32_16x16x32_bf16 v[124:127], v[146:149], v[178:181], v[124:127]
	v_mfma_f32_16x16x32_bf16 v[120:123], v[154:157], v[178:181], v[120:123]
	v_mfma_f32_16x16x32_bf16 v[116:119], v[146:149], v[198:201], v[116:119]
	v_mfma_f32_16x16x32_bf16 v[112:115], v[154:157], v[198:201], v[112:115]
	v_mfma_f32_16x16x32_bf16 v[108:111], v[146:149], v[206:209], v[108:111]
	v_mfma_f32_16x16x32_bf16 v[104:107], v[154:157], v[206:209], v[104:107]
	v_mfma_f32_16x16x32_bf16 v[100:103], v[146:149], v[214:217], v[100:103]
	v_mfma_f32_16x16x32_bf16 v[96:99], v[154:157], v[214:217], v[96:99]
	v_mfma_f32_16x16x32_bf16 v[92:95], v[158:161], v[174:177], v[92:95]
	v_mfma_f32_16x16x32_bf16 v[88:91], v[166:169], v[174:177], v[88:91]
	v_mfma_f32_16x16x32_bf16 v[84:87], v[158:161], v[194:197], v[84:87]
	v_mfma_f32_16x16x32_bf16 v[80:83], v[166:169], v[194:197], v[80:83]
	v_mfma_f32_16x16x32_bf16 v[76:79], v[158:161], v[202:205], v[76:79]
	v_mfma_f32_16x16x32_bf16 v[72:75], v[166:169], v[202:205], v[72:75]
	v_mfma_f32_16x16x32_bf16 v[68:71], v[158:161], v[210:213], v[68:71]
	v_mfma_f32_16x16x32_bf16 v[64:67], v[166:169], v[210:213], v[64:67]
	v_mfma_f32_16x16x32_bf16 v[92:95], v[162:165], v[178:181], v[92:95]
	v_mfma_f32_16x16x32_bf16 v[88:91], v[170:173], v[178:181], v[88:91]
	v_mfma_f32_16x16x32_bf16 v[84:87], v[162:165], v[198:201], v[84:87]
	v_mfma_f32_16x16x32_bf16 v[80:83], v[170:173], v[198:201], v[80:83]
	v_mfma_f32_16x16x32_bf16 v[76:79], v[162:165], v[206:209], v[76:79]
	v_mfma_f32_16x16x32_bf16 v[72:75], v[170:173], v[206:209], v[72:75]
	v_mfma_f32_16x16x32_bf16 v[68:71], v[162:165], v[214:217], v[68:71]
	v_mfma_f32_16x16x32_bf16 v[64:67], v[170:173], v[214:217], v[64:67]
	s_setprio 0
	s_barrier
	s_add_i32 s36, s36, s45
	s_mov_b32 m0, s36
	ds_read_b128 v[174:177], v140 offset:49152
	ds_read_b128 v[178:181], v140 offset:50176
	ds_read_b128 v[194:197], v140 offset:51200
	ds_read_b128 v[198:201], v140 offset:52224
	ds_read_b128 v[202:205], v140 offset:53248
	ds_read_b128 v[206:209], v140 offset:54272
	ds_read_b128 v[210:213], v140 offset:55296
	ds_read_b128 v[214:217], v140 offset:56320
	global_load_lds_dwordx4 v224, s[82:83]
	s_add_i32 m0, s36, 0x2000
	s_add_i32 s36, s37, s45
	global_load_lds_dwordx4 v225, s[82:83]
	s_mov_b32 m0, s36
	s_nop 0
	global_load_lds_dwordx4 v226, s[82:83]
	s_add_i32 m0, s36, 0x2000
	s_nop 0
	global_load_lds_dwordx4 v229, s[82:83]
	s_mov_b32 m0, s59
	s_nop 0
	global_load_lds_dwordx4 v233, s[82:83]
	s_mov_b32 m0, s60
	s_nop 0
	global_load_lds_dwordx4 v234, s[82:83]
	s_waitcnt vmcnt(8)
	s_waitcnt lgkmcnt(0)
	s_barrier
	s_setprio 1
	v_mfma_f32_16x16x32_bf16 v[60:63], v[142:145], v[174:177], v[60:63]
	v_mfma_f32_16x16x32_bf16 v[56:59], v[150:153], v[174:177], v[56:59]
	v_mfma_f32_16x16x32_bf16 v[52:55], v[142:145], v[194:197], v[52:55]
	v_mfma_f32_16x16x32_bf16 v[48:51], v[150:153], v[194:197], v[48:51]
	v_mfma_f32_16x16x32_bf16 v[44:47], v[142:145], v[202:205], v[44:47]
	v_mfma_f32_16x16x32_bf16 v[40:43], v[150:153], v[202:205], v[40:43]
	v_mfma_f32_16x16x32_bf16 v[36:39], v[142:145], v[210:213], v[36:39]
	v_mfma_f32_16x16x32_bf16 v[32:35], v[150:153], v[210:213], v[32:35]
	v_mfma_f32_16x16x32_bf16 v[60:63], v[146:149], v[178:181], v[60:63]
	v_mfma_f32_16x16x32_bf16 v[56:59], v[154:157], v[178:181], v[56:59]
	v_mfma_f32_16x16x32_bf16 v[52:55], v[146:149], v[198:201], v[52:55]
	v_mfma_f32_16x16x32_bf16 v[48:51], v[154:157], v[198:201], v[48:51]
	v_mfma_f32_16x16x32_bf16 v[44:47], v[146:149], v[206:209], v[44:47]
	v_mfma_f32_16x16x32_bf16 v[40:43], v[154:157], v[206:209], v[40:43]
	v_mfma_f32_16x16x32_bf16 v[36:39], v[146:149], v[214:217], v[36:39]
	v_mfma_f32_16x16x32_bf16 v[32:35], v[154:157], v[214:217], v[32:35]
	v_mfma_f32_16x16x32_bf16 v[28:31], v[158:161], v[174:177], v[28:31]
	v_mfma_f32_16x16x32_bf16 v[24:27], v[166:169], v[174:177], v[24:27]
	v_mfma_f32_16x16x32_bf16 v[20:23], v[158:161], v[194:197], v[20:23]
	v_mfma_f32_16x16x32_bf16 v[16:19], v[166:169], v[194:197], v[16:19]
	v_mfma_f32_16x16x32_bf16 v[12:15], v[158:161], v[202:205], v[12:15]
	v_mfma_f32_16x16x32_bf16 v[8:11], v[166:169], v[202:205], v[8:11]
	v_mfma_f32_16x16x32_bf16 v[4:7], v[158:161], v[210:213], v[4:7]
	v_mfma_f32_16x16x32_bf16 v[0:3], v[166:169], v[210:213], v[0:3]
	v_mfma_f32_16x16x32_bf16 v[28:31], v[162:165], v[178:181], v[28:31]
	v_mfma_f32_16x16x32_bf16 v[24:27], v[170:173], v[178:181], v[24:27]
	v_mfma_f32_16x16x32_bf16 v[20:23], v[162:165], v[198:201], v[20:23]
	v_mfma_f32_16x16x32_bf16 v[16:19], v[170:173], v[198:201], v[16:19]
	v_mfma_f32_16x16x32_bf16 v[12:15], v[162:165], v[206:209], v[12:15]
	v_mfma_f32_16x16x32_bf16 v[8:11], v[170:173], v[206:209], v[8:11]
	v_mfma_f32_16x16x32_bf16 v[4:7], v[162:165], v[214:217], v[4:7]
	v_mfma_f32_16x16x32_bf16 v[0:3], v[170:173], v[214:217], v[0:3]
	s_setprio 0
	s_barrier
	s_andn2_b64 vcc, exec, s[24:25]
	s_cbranch_vccnz .LBB0_320
	s_barrier

; #define G_STAGE_A(bufoff, p0, p1, koff) do { \
;         __builtin_amdgcn_global_load_lds((const unsigned*)(gbase + (size_t)(unsigned)((p0) + (koff) + voffA[0])), (LAS unsigned*)(lds + (bufoff) + ldsw), 16, 0, 0); \
;         __builtin_amdgcn_global_load_lds((const unsigned*)(gbase + (size_t)(unsigned)((p1) + (koff) + voffA[1])), (LAS unsigned*)(lds + (bufoff) + ldsw + 8192), 16, 0, 0); } while (0)
; #define G_STAGE_B(bufoff, p, koff) do { \
;         __builtin_amdgcn_global_load_lds((const unsigned*)(gbase + (size_t)(unsigned)((p) + (koff) + voffB[0])), (LAS unsigned*)(lds + (bufoff) + ldsw), 16, 0, 0); \
;         __builtin_amdgcn_global_load_lds((const unsigned*)(gbase + (size_t)(unsigned)((p) + (koff) + voffB[1])), (LAS unsigned*)(lds + (bufoff) + ldsw + 8192), 16, 0, 0); } while (0)
; template <class Epi>
; DI void gemm_phase(LAS unsigned char* lds, const Sched& S, const Epi& E, const int K) {
;     ...
;         for (int t = 0; t < nt; t += 2) {
;             const bool last = (t == nt - 2);
;             const unsigned k1 = (unsigned)(t + 1) * kstepA;
;             const unsigned k2 = last ? 0u : (unsigned)(t + 2) * kstepA, k3 = k2 + kstepA;
;             const unsigned kb2 = last ? 0u : (unsigned)(t + 2) * kstepB, kb3 = kb2 + kstepB;
;             const unsigned x0 = last ? n0 : cur.a0, x1 = last ? n1 : cur.a1, x2 = last ? n2 : cur.a2, x3 = last ? n3 : cur.a3;
;             const unsigned xb = last ? nB : cur.b;
;     ...
;             G_LDB(B0, 0, 0); G_LDB(B1, 0, 1); G_SCHED; G_LDA(At, 0, 0); G_STAGE_A(G_SA(1, 1), cur.a2, cur.a3, k1);
;             G_WAIT_V(8); G_WAIT_L(0); G_BAR; G_MMA(0, 0, At, B0); G_MMA(0, 1, At, B1); G_BAR; G_SCHED;
;             G_LDA(At, 0, 1); G_STAGE_B(G_SB(0, 0), xb, kb2); G_STAGE_B(G_SB(0, 1), xb + hstepB, kb2); G_STAGE_A(G_SA(0, 0), x0, x1, k2);
;             G_WAIT_V(8); G_WAIT_L(0); G_BAR; G_MMA(1, 0, At, B0); G_MMA(1, 1, At, B1); G_BAR; G_SCHED;
;             G_LDB(B0, 1, 0); G_LDB(B1, 1, 1); G_SCHED; G_LDA(At, 1, 0); G_STAGE_A(G_SA(0, 1), x2, x3, k2);
;             G_WAIT_V(8); G_WAIT_L(0); G_BAR; G_MMA(0, 0, At, B0); G_MMA(0, 1, At, B1); G_BAR; G_SCHED;
;             G_LDA(At, 1, 1); G_STAGE_B(G_SB(1, 0), xb, kb3); G_STAGE_B(G_SB(1, 1), xb + hstepB, kb3); G_STAGE_A(G_SA(1, 0), x0, x1, k3);
;             G_WAIT_V(8); G_WAIT_L(0); G_BAR; G_MMA(1, 0, At, B0); G_MMA(1, 1, At, B1); G_BAR; G_SCHED;
.LBB0_511:
	s_add_i32 s27, s26, 0x100
	s_cmp_eq_u32 s10, 28
	s_cselect_b32 s48, 0, s27
	s_cselect_b32 s72, s20, s45
	s_cselect_b32 s73, s24, s41
	s_cselect_b32 s75, s21, s44
	s_cselect_b32 s78, s11, s46
	s_cselect_b32 s37, s25, s40
	s_add_i32 s79, 0, 0x10000
	v_add_u32_e32 v130, s79, v148
	s_add_i32 s80, 0, 0x14000
	ds_read_b128 v[138:141], v130
	ds_read_b128 v[154:157], v130 offset:1024
	ds_read_b128 v[158:161], v130 offset:2048
	ds_read_b128 v[162:165], v130 offset:3072
	v_add_u32_e32 v130, s80, v148
	ds_read_b128 v[166:169], v130
	ds_read_b128 v[170:173], v130 offset:1024
	ds_read_b128 v[174:177], v130 offset:2048
	ds_read_b128 v[178:181], v130 offset:3072
	s_or_b32 s36, s48, 0x80
	v_add_u32_e32 v130, s26, v129
	s_add_i32 m0, s50, 0xc000
	ds_read_b128 v[194:197], v152
	ds_read_b128 v[198:201], v152 offset:1024
	ds_read_b128 v[202:205], v152 offset:2048
	ds_read_b128 v[206:209], v152 offset:3072
	ds_read_b128 v[210:213], v152 offset:4096
	ds_read_b128 v[214:217], v152 offset:5120
	ds_read_b128 v[218:221], v152 offset:6144
	ds_read_b128 v[222:225], v152 offset:7168
	global_load_lds_dwordx4 v130, s[82:83]
	v_add_u32_e32 v130, s26, v128
	s_add_i32 m0, s50, 0xe000
	s_nop 0
	global_load_lds_dwordx4 v130, s[82:83]
	s_waitcnt vmcnt(8)
	s_waitcnt lgkmcnt(0)
	s_barrier
	s_setprio 1
	v_mfma_f32_16x16x32_bf16 v[124:127], v[138:141], v[194:197], v[124:127]
	v_mfma_f32_16x16x32_bf16 v[120:123], v[158:161], v[194:197], v[120:123]
	v_mfma_f32_16x16x32_bf16 v[116:119], v[138:141], v[202:205], v[116:119]
	v_mfma_f32_16x16x32_bf16 v[112:115], v[158:161], v[202:205], v[112:115]
	v_mfma_f32_16x16x32_bf16 v[108:111], v[138:141], v[210:213], v[108:111]
	v_mfma_f32_16x16x32_bf16 v[104:107], v[158:161], v[210:213], v[104:107]
	v_mfma_f32_16x16x32_bf16 v[100:103], v[138:141], v[218:221], v[100:103]
	v_mfma_f32_16x16x32_bf16 v[96:99], v[158:161], v[218:221], v[96:99]
	v_mfma_f32_16x16x32_bf16 v[124:127], v[154:157], v[198:201], v[124:127]
	v_mfma_f32_16x16x32_bf16 v[120:123], v[162:165], v[198:201], v[120:123]
	v_mfma_f32_16x16x32_bf16 v[116:119], v[154:157], v[206:209], v[116:119]
	v_mfma_f32_16x16x32_bf16 v[112:115], v[162:165], v[206:209], v[112:115]
	v_mfma_f32_16x16x32_bf16 v[108:111], v[154:157], v[214:217], v[108:111]
	v_mfma_f32_16x16x32_bf16 v[104:107], v[162:165], v[214:217], v[104:107]
	v_mfma_f32_16x16x32_bf16 v[100:103], v[154:157], v[222:225], v[100:103]
	v_mfma_f32_16x16x32_bf16 v[96:99], v[162:165], v[222:225], v[96:99]
	v_mfma_f32_16x16x32_bf16 v[92:95], v[166:169], v[194:197], v[92:95]
	v_mfma_f32_16x16x32_bf16 v[88:91], v[174:177], v[194:197], v[88:91]
	v_mfma_f32_16x16x32_bf16 v[84:87], v[166:169], v[202:205], v[84:87]
	v_mfma_f32_16x16x32_bf16 v[80:83], v[174:177], v[202:205], v[80:83]
	v_mfma_f32_16x16x32_bf16 v[76:79], v[166:169], v[210:213], v[76:79]
	v_mfma_f32_16x16x32_bf16 v[72:75], v[174:177], v[210:213], v[72:75]
	v_mfma_f32_16x16x32_bf16 v[68:71], v[166:169], v[218:221], v[68:71]
	v_mfma_f32_16x16x32_bf16 v[64:67], v[174:177], v[218:221], v[64:67]
	v_mfma_f32_16x16x32_bf16 v[92:95], v[170:173], v[198:201], v[92:95]
	v_mfma_f32_16x16x32_bf16 v[88:91], v[178:181], v[198:201], v[88:91]
	v_mfma_f32_16x16x32_bf16 v[84:87], v[170:173], v[206:209], v[84:87]
	v_mfma_f32_16x16x32_bf16 v[80:83], v[178:181], v[206:209], v[80:83]
	v_mfma_f32_16x16x32_bf16 v[76:79], v[170:173], v[214:217], v[76:79]
	v_mfma_f32_16x16x32_bf16 v[72:75], v[178:181], v[214:217], v[72:75]
	v_mfma_f32_16x16x32_bf16 v[68:71], v[170:173], v[222:225], v[68:71]
	v_mfma_f32_16x16x32_bf16 v[64:67], v[178:181], v[222:225], v[64:67]
	s_setprio 0
	s_barrier
	s_add_i32 s26, s48, s37
	s_add_i32 s79, s79, s47
	v_add_u32_e32 v130, s26, v144
	s_mov_b32 m0, s79
	ds_read_b128 v[194:197], v152 offset:16384
	ds_read_b128 v[198:201], v152 offset:17408
	ds_read_b128 v[202:205], v152 offset:18432
	ds_read_b128 v[206:209], v152 offset:19456
	ds_read_b128 v[210:213], v152 offset:20480
	ds_read_b128 v[214:217], v152 offset:21504
	ds_read_b128 v[218:221], v152 offset:22528
	ds_read_b128 v[222:225], v152 offset:23552
	global_load_lds_dwordx4 v130, s[82:83]
	v_add_u32_e32 v130, s26, v146
	s_add_i32 s26, s37, 0x80000
	s_add_i32 m0, s79, 0x2000
	s_add_i32 s79, s26, s48
	s_add_i32 s80, s80, s47
	global_load_lds_dwordx4 v130, s[82:83]
	v_add_u32_e32 v130, s79, v144
	s_mov_b32 m0, s80
	s_nop 0
	global_load_lds_dwordx4 v130, s[82:83]
	v_add_u32_e32 v130, s79, v146
	s_add_i32 m0, s80, 0x2000
	s_nop 0
	global_load_lds_dwordx4 v130, s[82:83]
	v_add_u32_e32 v130, s78, v133
	v_add_u32_e32 v131, s48, v130
	s_mov_b32 m0, s50
	s_nop 0
	global_load_lds_dwordx4 v131, s[82:83]
	v_add_u32_e32 v131, s72, v145
	v_add_u32_e32 v142, s48, v131
	s_mov_b32 m0, s54
	s_nop 0
	global_load_lds_dwordx4 v142, s[82:83]
	s_waitcnt vmcnt(8)
	s_waitcnt lgkmcnt(0)
	s_barrier
; #define G_STAGE_A(bufoff, p0, p1, koff) do { \
;         __builtin_amdgcn_global_load_lds((const unsigned*)(gbase + (size_t)(unsigned)((p0) + (koff) + voffA[0])), (LAS unsigned*)(lds + (bufoff) + ldsw), 16, 0, 0); \
;         __builtin_amdgcn_global_load_lds((const unsigned*)(gbase + (size_t)(unsigned)((p1) + (koff) + voffA[1])), (LAS unsigned*)(lds + (bufoff) + ldsw + 8192), 16, 0, 0); } while (0)
; #define G_STAGE_B(bufoff, p, koff) do { \
;         __builtin_amdgcn_global_load_lds((const unsigned*)(gbase + (size_t)(unsigned)((p) + (koff) + voffB[0])), (LAS unsigned*)(lds + (bufoff) + ldsw), 16, 0, 0); \
;         __builtin_amdgcn_global_load_lds((const unsigned*)(gbase + (size_t)(unsigned)((p) + (koff) + voffB[1])), (LAS unsigned*)(lds + (bufoff) + ldsw + 8192), 16, 0, 0); } while (0)
; #define G_LDA(dst, b, h) do { _Pragma("unroll") for (int m = 0; m < 4; ++m) _Pragma("unroll") for (int k = 0; k < 2; ++k) dst[m][k] = *(const LAS bf16x8*)(lds + G_SA(b, h) + aoff + m * 2048 + k * 1024); } while (0)
; #define G_LDB(dst, b, h) do { _Pragma("unroll") for (int n = 0; n < 2; ++n) _Pragma("unroll") for (int k = 0; k < 2; ++k) dst[n][k] = *(const LAS bf16x8*)(lds + G_SB(b, h) + boff + n * 2048 + k * 1024); } while (0)
; #define G_MMA(ai, bj, At, Bt) do { __builtin_amdgcn_s_setprio(1); _Pragma("unroll") for (int m = 0; m < 4; ++m) _Pragma("unroll") for (int n = 0; n < 2; ++n) _Pragma("unroll") for (int k = 0; k < 2; ++k) \
;         acc[ai][bj][m][n] = __builtin_amdgcn_mfma_f32_16x16x32_bf16(Bt[n][k], At[m][k], acc[ai][bj][m][n], 0, 0, 0); __builtin_amdgcn_s_setprio(0); } while (0)
; template <class Epi>
; DI void gemm_phase(LAS unsigned char* lds, const Sched& S, const Epi& E, const int K) {
;     ...
;             G_LDB(B0, 0, 0); G_LDB(B1, 0, 1); G_SCHED; G_LDA(At, 0, 0); G_STAGE_A(G_SA(1, 1), cur.a2, cur.a3, k1);
;             G_WAIT_V(8); G_WAIT_L(0); G_BAR; G_MMA(0, 0, At, B0); G_MMA(0, 1, At, B1); G_BAR; G_SCHED;
;             G_LDA(At, 0, 1); G_STAGE_B(G_SB(0, 0), xb, kb2); G_STAGE_B(G_SB(0, 1), xb + hstepB, kb2); G_STAGE_A(G_SA(0, 0), x0, x1, k2);
;             G_WAIT_V(8); G_WAIT_L(0); G_BAR; G_MMA(1, 0, At, B0); G_MMA(1, 1, At, B1); G_BAR; G_SCHED;
;             G_LDB(B0, 1, 0); G_LDB(B1, 1, 1); G_SCHED; G_LDA(At, 1, 0); G_STAGE_A(G_SA(0, 1), x2, x3, k2);
;             G_WAIT_V(8); G_WAIT_L(0); G_BAR; G_MMA(0, 0, At, B0); G_MMA(0, 1, At, B1); G_BAR; G_SCHED;
	s_setprio 1
	v_mfma_f32_16x16x32_bf16 v[60:63], v[138:141], v[194:197], v[60:63]
	v_mfma_f32_16x16x32_bf16 v[56:59], v[158:161], v[194:197], v[56:59]
	v_mfma_f32_16x16x32_bf16 v[52:55], v[138:141], v[202:205], v[52:55]
	v_mfma_f32_16x16x32_bf16 v[48:51], v[158:161], v[202:205], v[48:51]
	v_mfma_f32_16x16x32_bf16 v[44:47], v[138:141], v[210:213], v[44:47]
	v_mfma_f32_16x16x32_bf16 v[40:43], v[158:161], v[210:213], v[40:43]
	v_mfma_f32_16x16x32_bf16 v[36:39], v[138:141], v[218:221], v[36:39]
	v_mfma_f32_16x16x32_bf16 v[32:35], v[158:161], v[218:221], v[32:35]
	v_mfma_f32_16x16x32_bf16 v[60:63], v[154:157], v[198:201], v[60:63]
	v_mfma_f32_16x16x32_bf16 v[56:59], v[162:165], v[198:201], v[56:59]
	v_mfma_f32_16x16x32_bf16 v[52:55], v[154:157], v[206:209], v[52:55]
	v_mfma_f32_16x16x32_bf16 v[48:51], v[162:165], v[206:209], v[48:51]
	v_mfma_f32_16x16x32_bf16 v[44:47], v[154:157], v[214:217], v[44:47]
	v_mfma_f32_16x16x32_bf16 v[40:43], v[162:165], v[214:217], v[40:43]
	v_mfma_f32_16x16x32_bf16 v[36:39], v[154:157], v[222:225], v[36:39]
	v_mfma_f32_16x16x32_bf16 v[32:35], v[162:165], v[222:225], v[32:35]
	v_mfma_f32_16x16x32_bf16 v[28:31], v[166:169], v[194:197], v[28:31]
	v_mfma_f32_16x16x32_bf16 v[24:27], v[174:177], v[194:197], v[24:27]
	v_mfma_f32_16x16x32_bf16 v[20:23], v[166:169], v[202:205], v[20:23]
	v_mfma_f32_16x16x32_bf16 v[16:19], v[174:177], v[202:205], v[16:19]
	v_mfma_f32_16x16x32_bf16 v[12:15], v[166:169], v[210:213], v[12:15]
	v_mfma_f32_16x16x32_bf16 v[8:11], v[174:177], v[210:213], v[8:11]
	v_mfma_f32_16x16x32_bf16 v[4:7], v[166:169], v[218:221], v[4:7]
	v_mfma_f32_16x16x32_bf16 v[0:3], v[174:177], v[218:221], v[0:3]
	v_mfma_f32_16x16x32_bf16 v[28:31], v[170:173], v[198:201], v[28:31]
	v_mfma_f32_16x16x32_bf16 v[24:27], v[178:181], v[198:201], v[24:27]
	v_mfma_f32_16x16x32_bf16 v[20:23], v[170:173], v[206:209], v[20:23]
	v_mfma_f32_16x16x32_bf16 v[16:19], v[178:181], v[206:209], v[16:19]
	v_mfma_f32_16x16x32_bf16 v[12:15], v[170:173], v[214:217], v[12:15]
	v_mfma_f32_16x16x32_bf16 v[8:11], v[178:181], v[214:217], v[8:11]
	v_mfma_f32_16x16x32_bf16 v[4:7], v[170:173], v[222:225], v[4:7]
	v_mfma_f32_16x16x32_bf16 v[0:3], v[178:181], v[222:225], v[0:3]
	s_setprio 0
	s_barrier
	s_add_i32 s72, 0, 0x18000
	v_add_u32_e32 v142, s72, v148
	s_add_i32 s78, 0, 0x1c000
	ds_read_b128 v[138:141], v142
	ds_read_b128 v[154:157], v142 offset:1024
	ds_read_b128 v[158:161], v142 offset:2048
	ds_read_b128 v[162:165], v142 offset:3072
	v_add_u32_e32 v142, s78, v148
	ds_read_b128 v[166:169], v142
	ds_read_b128 v[170:173], v142 offset:1024
	ds_read_b128 v[174:177], v142 offset:2048
	ds_read_b128 v[178:181], v142 offset:3072
	s_add_i32 s75, s75, s48
	s_mov_b32 m0, s55
	v_add_u32_e32 v142, s75, v133
	s_add_i32 s73, s73, s48
	ds_read_b128 v[194:197], v152 offset:32768
	ds_read_b128 v[198:201], v152 offset:33792
	ds_read_b128 v[202:205], v152 offset:34816
	ds_read_b128 v[206:209], v152 offset:35840
	ds_read_b128 v[210:213], v152 offset:36864
	ds_read_b128 v[214:217], v152 offset:37888
	ds_read_b128 v[218:221], v152 offset:38912
	ds_read_b128 v[222:225], v152 offset:39936
	global_load_lds_dwordx4 v142, s[82:83]
	v_add_u32_e32 v142, s73, v145
	s_mov_b32 m0, s56
	s_nop 0
	global_load_lds_dwordx4 v142, s[82:83]
	s_waitcnt vmcnt(8)
	s_waitcnt lgkmcnt(0)
	s_barrier
	s_setprio 1
	v_mfma_f32_16x16x32_bf16 v[124:127], v[138:141], v[194:197], v[124:127]
	v_mfma_f32_16x16x32_bf16 v[120:123], v[158:161], v[194:197], v[120:123]
	v_mfma_f32_16x16x32_bf16 v[116:119], v[138:141], v[202:205], v[116:119]
	v_mfma_f32_16x16x32_bf16 v[112:115], v[158:161], v[202:205], v[112:115]
	v_mfma_f32_16x16x32_bf16 v[108:111], v[138:141], v[210:213], v[108:111]
	v_mfma_f32_16x16x32_bf16 v[104:107], v[158:161], v[210:213], v[104:107]
	v_mfma_f32_16x16x32_bf16 v[100:103], v[138:141], v[218:221], v[100:103]
	v_mfma_f32_16x16x32_bf16 v[96:99], v[158:161], v[218:221], v[96:99]
	v_mfma_f32_16x16x32_bf16 v[124:127], v[154:157], v[198:201], v[124:127]
	v_mfma_f32_16x16x32_bf16 v[120:123], v[162:165], v[198:201], v[120:123]
	v_mfma_f32_16x16x32_bf16 v[116:119], v[154:157], v[206:209], v[116:119]
	v_mfma_f32_16x16x32_bf16 v[112:115], v[162:165], v[206:209], v[112:115]
	v_mfma_f32_16x16x32_bf16 v[108:111], v[154:157], v[214:217], v[108:111]
	v_mfma_f32_16x16x32_bf16 v[104:107], v[162:165], v[214:217], v[104:107]
	v_mfma_f32_16x16x32_bf16 v[100:103], v[154:157], v[222:225], v[100:103]
	v_mfma_f32_16x16x32_bf16 v[96:99], v[162:165], v[222:225], v[96:99]
	v_mfma_f32_16x16x32_bf16 v[92:95], v[166:169], v[194:197], v[92:95]
	v_mfma_f32_16x16x32_bf16 v[88:91], v[174:177], v[194:197], v[88:91]
	v_mfma_f32_16x16x32_bf16 v[84:87], v[166:169], v[202:205], v[84:87]
	v_mfma_f32_16x16x32_bf16 v[80:83], v[174:177], v[202:205], v[80:83]
	v_mfma_f32_16x16x32_bf16 v[76:79], v[166:169], v[210:213], v[76:79]
	v_mfma_f32_16x16x32_bf16 v[72:75], v[174:177], v[210:213], v[72:75]
	v_mfma_f32_16x16x32_bf16 v[68:71], v[166:169], v[218:221], v[68:71]
	v_mfma_f32_16x16x32_bf16 v[64:67], v[174:177], v[218:221], v[64:67]
	v_mfma_f32_16x16x32_bf16 v[92:95], v[170:173], v[198:201], v[92:95]
	v_mfma_f32_16x16x32_bf16 v[88:91], v[178:181], v[198:201], v[88:91]
	v_mfma_f32_16x16x32_bf16 v[84:87], v[170:173], v[206:209], v[84:87]
	v_mfma_f32_16x16x32_bf16 v[80:83], v[178:181], v[206:209], v[80:83]
	v_mfma_f32_16x16x32_bf16 v[76:79], v[170:173], v[214:217], v[76:79]
	v_mfma_f32_16x16x32_bf16 v[72:75], v[178:181], v[214:217], v[72:75]
	v_mfma_f32_16x16x32_bf16 v[68:71], v[170:173], v[222:225], v[68:71]
	v_mfma_f32_16x16x32_bf16 v[64:67], v[178:181], v[222:225], v[64:67]
	s_setprio 0
	s_barrier
; #define G_STAGE_A(bufoff, p0, p1, koff) do { \
;         __builtin_amdgcn_global_load_lds((const unsigned*)(gbase + (size_t)(unsigned)((p0) + (koff) + voffA[0])), (LAS unsigned*)(lds + (bufoff) + ldsw), 16, 0, 0); \
;         __builtin_amdgcn_global_load_lds((const unsigned*)(gbase + (size_t)(unsigned)((p1) + (koff) + voffA[1])), (LAS unsigned*)(lds + (bufoff) + ldsw + 8192), 16, 0, 0); } while (0)
; #define G_STAGE_B(bufoff, p, koff) do { \
;         __builtin_amdgcn_global_load_lds((const unsigned*)(gbase + (size_t)(unsigned)((p) + (koff) + voffB[0])), (LAS unsigned*)(lds + (bufoff) + ldsw), 16, 0, 0); \
;         __builtin_amdgcn_global_load_lds((const unsigned*)(gbase + (size_t)(unsigned)((p) + (koff) + voffB[1])), (LAS unsigned*)(lds + (bufoff) + ldsw + 8192), 16, 0, 0); } while (0)
; #define G_LDA(dst, b, h) do { _Pragma("unroll") for (int m = 0; m < 4; ++m) _Pragma("unroll") for (int k = 0; k < 2; ++k) dst[m][k] = *(const LAS bf16x8*)(lds + G_SA(b, h) + aoff + m * 2048 + k * 1024); } while (0)
; #define G_LDB(dst, b, h) do { _Pragma("unroll") for (int n = 0; n < 2; ++n) _Pragma("unroll") for (int k = 0; k < 2; ++k) dst[n][k] = *(const LAS bf16x8*)(lds + G_SB(b, h) + boff + n * 2048 + k * 1024); } while (0)
; #define G_MMA(ai, bj, At, Bt) do { __builtin_amdgcn_s_setprio(1); _Pragma("unroll") for (int m = 0; m < 4; ++m) _Pragma("unroll") for (int n = 0; n < 2; ++n) _Pragma("unroll") for (int k = 0; k < 2; ++k) \
;         acc[ai][bj][m][n] = __builtin_amdgcn_mfma_f32_16x16x32_bf16(Bt[n][k], At[m][k], acc[ai][bj][m][n], 0, 0, 0); __builtin_amdgcn_s_setprio(0); } while (0)
; #define G_WAIT_V(n) asm volatile("s_waitcnt vmcnt(" #n ")" ::: "memory")
; #define G_WAIT_L(n) asm volatile("s_waitcnt lgkmcnt(" #n ")" ::: "memory")
; #define G_BAR __builtin_amdgcn_s_barrier()
; template <class Epi>
; DI void gemm_phase(LAS unsigned char* lds, const Sched& S, const Epi& E, const int K) {
;     ...
;             G_LDB(B0, 1, 0); G_LDB(B1, 1, 1); G_SCHED; G_LDA(At, 1, 0); G_STAGE_A(G_SA(0, 1), x2, x3, k2);
;             G_WAIT_V(8); G_WAIT_L(0); G_BAR; G_MMA(0, 0, At, B0); G_MMA(0, 1, At, B1); G_BAR; G_SCHED;
;             G_LDA(At, 1, 1); G_STAGE_B(G_SB(1, 0), xb, kb3); G_STAGE_B(G_SB(1, 1), xb + hstepB, kb3); G_STAGE_A(G_SA(1, 0), x0, x1, k3);
;             G_WAIT_V(8); G_WAIT_L(0); G_BAR; G_MMA(1, 0, At, B0); G_MMA(1, 1, At, B1); G_BAR; G_SCHED;
	s_add_i32 s37, s36, s37
	s_add_i32 s48, s72, s47
	v_add_u32_e32 v142, s37, v144
	s_mov_b32 m0, s48
	ds_read_b128 v[194:197], v152 offset:49152
	ds_read_b128 v[198:201], v152 offset:50176
	ds_read_b128 v[202:205], v152 offset:51200
	ds_read_b128 v[206:209], v152 offset:52224
	ds_read_b128 v[210:213], v152 offset:53248
	ds_read_b128 v[214:217], v152 offset:54272
	ds_read_b128 v[218:221], v152 offset:55296
	ds_read_b128 v[222:225], v152 offset:56320
	global_load_lds_dwordx4 v142, s[82:83]
	v_add_u32_e32 v142, s37, v146
	s_add_i32 m0, s48, 0x2000
	s_add_i32 s26, s36, s26
	s_add_i32 s37, s78, s47
	global_load_lds_dwordx4 v142, s[82:83]
	v_add_u32_e32 v142, s26, v144
	s_mov_b32 m0, s37
	v_add_u32_e32 v130, s36, v130
	global_load_lds_dwordx4 v142, s[82:83]
	v_add_u32_e32 v142, s26, v146
	s_add_i32 m0, s37, 0x2000
	s_nop 0
	global_load_lds_dwordx4 v142, s[82:83]
	s_mov_b32 m0, s57
	s_nop 0
	global_load_lds_dwordx4 v130, s[82:83]
	v_add_u32_e32 v130, s36, v131
	s_mov_b32 m0, s58
	s_nop 0
	global_load_lds_dwordx4 v130, s[82:83]
	s_waitcnt vmcnt(8)
	s_waitcnt lgkmcnt(0)
	s_barrier
	s_setprio 1
	v_mfma_f32_16x16x32_bf16 v[60:63], v[138:141], v[194:197], v[60:63]
	v_mfma_f32_16x16x32_bf16 v[56:59], v[158:161], v[194:197], v[56:59]
	v_mfma_f32_16x16x32_bf16 v[52:55], v[138:141], v[202:205], v[52:55]
	v_mfma_f32_16x16x32_bf16 v[48:51], v[158:161], v[202:205], v[48:51]
	v_mfma_f32_16x16x32_bf16 v[44:47], v[138:141], v[210:213], v[44:47]
	v_mfma_f32_16x16x32_bf16 v[40:43], v[158:161], v[210:213], v[40:43]
	v_mfma_f32_16x16x32_bf16 v[36:39], v[138:141], v[218:221], v[36:39]
	v_mfma_f32_16x16x32_bf16 v[32:35], v[158:161], v[218:221], v[32:35]
	v_mfma_f32_16x16x32_bf16 v[60:63], v[154:157], v[198:201], v[60:63]
	v_mfma_f32_16x16x32_bf16 v[56:59], v[162:165], v[198:201], v[56:59]
	v_mfma_f32_16x16x32_bf16 v[52:55], v[154:157], v[206:209], v[52:55]
	v_mfma_f32_16x16x32_bf16 v[48:51], v[162:165], v[206:209], v[48:51]
	v_mfma_f32_16x16x32_bf16 v[44:47], v[154:157], v[214:217], v[44:47]
	v_mfma_f32_16x16x32_bf16 v[40:43], v[162:165], v[214:217], v[40:43]
	v_mfma_f32_16x16x32_bf16 v[36:39], v[154:157], v[222:225], v[36:39]
	v_mfma_f32_16x16x32_bf16 v[32:35], v[162:165], v[222:225], v[32:35]
	v_mfma_f32_16x16x32_bf16 v[28:31], v[166:169], v[194:197], v[28:31]
	v_mfma_f32_16x16x32_bf16 v[24:27], v[174:177], v[194:197], v[24:27]
	v_mfma_f32_16x16x32_bf16 v[20:23], v[166:169], v[202:205], v[20:23]
	v_mfma_f32_16x16x32_bf16 v[16:19], v[174:177], v[202:205], v[16:19]
	v_mfma_f32_16x16x32_bf16 v[12:15], v[166:169], v[210:213], v[12:15]
	v_mfma_f32_16x16x32_bf16 v[8:11], v[174:177], v[210:213], v[8:11]
	v_mfma_f32_16x16x32_bf16 v[4:7], v[166:169], v[218:221], v[4:7]
	v_mfma_f32_16x16x32_bf16 v[0:3], v[174:177], v[218:221], v[0:3]
	v_mfma_f32_16x16x32_bf16 v[28:31], v[170:173], v[198:201], v[28:31]
	v_mfma_f32_16x16x32_bf16 v[24:27], v[178:181], v[198:201], v[24:27]
	v_mfma_f32_16x16x32_bf16 v[20:23], v[170:173], v[206:209], v[20:23]
	v_mfma_f32_16x16x32_bf16 v[16:19], v[178:181], v[206:209], v[16:19]
	v_mfma_f32_16x16x32_bf16 v[12:15], v[170:173], v[214:217], v[12:15]
	v_mfma_f32_16x16x32_bf16 v[8:11], v[178:181], v[214:217], v[8:11]
	v_mfma_f32_16x16x32_bf16 v[4:7], v[170:173], v[222:225], v[4:7]
	v_mfma_f32_16x16x32_bf16 v[0:3], v[178:181], v[222:225], v[0:3]
	s_setprio 0
	s_barrier
	s_add_i32 s10, s10, 2
	s_cmp_gt_u32 s10, 29
	s_mov_b32 s26, s27
	s_cbranch_scc0 .LBB0_511
	s_and_b64 vcc, exec, s[14:15]
	s_cbranch_vccz .LBB0_514
	s_barrier
